# v82 minus all remaining K-loop s_setprio flips (no user priority at all; A/B of the per-segment flips)
# speedup vs baseline: 1.0082x; 1.0017x over previous
.LBB0_193:
	v_add_u32_e32 v126, s73, v177
	ds_read_b128 v[122:125], v126
	ds_read_b128 v[136:139], v126 offset:1024
	ds_read_b128 v[140:143], v126 offset:2048
	ds_read_b128 v[192:195], v126 offset:3072
	v_add_u32_e32 v126, s54, v177
	ds_read_b128 v[196:199], v126
	ds_read_b128 v[204:207], v126 offset:1024
	ds_read_b128 v[208:211], v126 offset:2048
	ds_read_b128 v[212:215], v126 offset:3072
	s_add_u32 s8, s0, 0xfff80080
	s_addc_u32 s9, s1, -1
	s_and_b64 s[4:5], s[4:5], exec
	s_cselect_b32 s9, s11, s9
	s_cselect_b32 s8, s12, s8
	s_cselect_b32 s5, s3, s17
	s_cselect_b32 s4, s13, s16
	v_lshl_add_u64 v[126:127], s[0:1], 0, v[168:169]
	s_add_i32 m0, s27, 0xc000
	ds_read_b128 v[216:219], v181
	ds_read_b128 v[220:223], v181 offset:1024
	ds_read_b128 v[224:227], v181 offset:2048
	ds_read_b128 v[228:231], v181 offset:3072
	ds_read_b128 v[232:235], v181 offset:4096
	ds_read_b128 v[236:239], v181 offset:5120
	ds_read_b128 v[240:243], v181 offset:6144
	ds_read_b128 v[244:247], v181 offset:7168
	global_load_lds_dwordx4 v[126:127], off
	v_lshl_add_u64 v[126:127], s[0:1], 0, v[166:167]
	s_add_i32 m0, s27, 0xe000
	s_nop 0
	global_load_lds_dwordx4 v[126:127], off
	s_waitcnt vmcnt(8)
	s_waitcnt lgkmcnt(0)
	s_barrier
	s_waitcnt lgkmcnt(0)
	v_mfma_f32_16x16x32_bf16 v[112:115], v[122:125], v[216:219], v[112:115]
	v_mfma_f32_16x16x32_bf16 v[116:119], v[140:143], v[216:219], v[116:119]
	v_mfma_f32_16x16x32_bf16 v[108:111], v[122:125], v[224:227], v[108:111]
	v_mfma_f32_16x16x32_bf16 v[100:103], v[140:143], v[224:227], v[100:103]
	v_mfma_f32_16x16x32_bf16 v[92:95], v[122:125], v[232:235], v[92:95]
	v_mfma_f32_16x16x32_bf16 v[84:87], v[140:143], v[232:235], v[84:87]
	v_mfma_f32_16x16x32_bf16 v[76:79], v[122:125], v[240:243], v[76:79]
	v_mfma_f32_16x16x32_bf16 v[68:71], v[140:143], v[240:243], v[68:71]
	v_mfma_f32_16x16x32_bf16 v[112:115], v[136:139], v[220:223], v[112:115]
	v_mfma_f32_16x16x32_bf16 v[116:119], v[192:195], v[220:223], v[116:119]
	v_mfma_f32_16x16x32_bf16 v[108:111], v[136:139], v[228:231], v[108:111]
	v_mfma_f32_16x16x32_bf16 v[100:103], v[192:195], v[228:231], v[100:103]
	v_mfma_f32_16x16x32_bf16 v[92:95], v[136:139], v[236:239], v[92:95]
	v_mfma_f32_16x16x32_bf16 v[84:87], v[192:195], v[236:239], v[84:87]
	v_mfma_f32_16x16x32_bf16 v[76:79], v[136:139], v[244:247], v[76:79]
	v_mfma_f32_16x16x32_bf16 v[68:71], v[192:195], v[244:247], v[68:71]
	v_mfma_f32_16x16x32_bf16 v[104:107], v[196:199], v[216:219], v[104:107]
	v_mfma_f32_16x16x32_bf16 v[96:99], v[208:211], v[216:219], v[96:99]
	v_mfma_f32_16x16x32_bf16 v[88:91], v[196:199], v[224:227], v[88:91]
	v_mfma_f32_16x16x32_bf16 v[80:83], v[208:211], v[224:227], v[80:83]
	v_mfma_f32_16x16x32_bf16 v[72:75], v[196:199], v[232:235], v[72:75]
	v_mfma_f32_16x16x32_bf16 v[64:67], v[208:211], v[232:235], v[64:67]
	v_mfma_f32_16x16x32_bf16 v[60:63], v[196:199], v[240:243], v[60:63]
	v_mfma_f32_16x16x32_bf16 v[56:59], v[208:211], v[240:243], v[56:59]
	v_mfma_f32_16x16x32_bf16 v[104:107], v[204:207], v[220:223], v[104:107]
	v_mfma_f32_16x16x32_bf16 v[96:99], v[212:215], v[220:223], v[96:99]
	v_mfma_f32_16x16x32_bf16 v[88:91], v[204:207], v[228:231], v[88:91]
	v_mfma_f32_16x16x32_bf16 v[80:83], v[212:215], v[228:231], v[80:83]
	v_mfma_f32_16x16x32_bf16 v[72:75], v[204:207], v[236:239], v[72:75]
	v_mfma_f32_16x16x32_bf16 v[64:67], v[212:215], v[236:239], v[64:67]
	v_mfma_f32_16x16x32_bf16 v[60:63], v[204:207], v[244:247], v[60:63]
	v_mfma_f32_16x16x32_bf16 v[56:59], v[212:215], v[244:247], v[56:59]
	s_barrier
	s_add_i32 s56, s73, s24
	v_lshl_add_u64 v[200:201], s[4:5], 0, v[146:147]
	s_mov_b32 m0, s56
	ds_read_b128 v[216:219], v181 offset:16384
	ds_read_b128 v[220:223], v181 offset:17408
	ds_read_b128 v[224:227], v181 offset:18432
	ds_read_b128 v[228:231], v181 offset:19456
	ds_read_b128 v[232:235], v181 offset:20480
	ds_read_b128 v[236:239], v181 offset:21504
	ds_read_b128 v[240:243], v181 offset:22528
	ds_read_b128 v[244:247], v181 offset:23552
	global_load_lds_dwordx4 v[200:201], off
	s_add_i32 m0, s56, 0x2000
	s_add_u32 s56, s4, 0x80000
	v_lshl_add_u64 v[248:249], s[4:5], 0, v[150:151]
	s_addc_u32 s57, s5, 0
	s_add_i32 s58, s54, s24
	global_load_lds_dwordx4 v[248:249], off
	v_lshl_add_u64 v[126:127], s[56:57], 0, v[146:147]
	s_mov_b32 m0, s58
	v_lshl_add_u64 v[250:251], s[8:9], 0, v[144:145]
	global_load_lds_dwordx4 v[126:127], off
	v_lshl_add_u64 v[126:127], s[56:57], 0, v[150:151]
	s_add_i32 m0, s58, 0x2000
	v_lshl_add_u64 v[252:253], s[8:9], 0, v[148:149]
	global_load_lds_dwordx4 v[126:127], off
	s_mov_b32 m0, s27
	s_nop 0
	global_load_lds_dwordx4 v[250:251], off
	s_mov_b32 m0, s28
	s_nop 0
	global_load_lds_dwordx4 v[252:253], off
	s_waitcnt vmcnt(8)
	s_waitcnt lgkmcnt(0)
	s_barrier
	s_waitcnt lgkmcnt(0)
	v_mfma_f32_16x16x32_bf16 v[52:55], v[122:125], v[216:219], v[52:55]
	v_mfma_f32_16x16x32_bf16 v[48:51], v[140:143], v[216:219], v[48:51]
	v_mfma_f32_16x16x32_bf16 v[44:47], v[122:125], v[224:227], v[44:47]
	v_mfma_f32_16x16x32_bf16 v[36:39], v[140:143], v[224:227], v[36:39]
	v_mfma_f32_16x16x32_bf16 v[28:31], v[122:125], v[232:235], v[28:31]
	v_mfma_f32_16x16x32_bf16 v[20:23], v[140:143], v[232:235], v[20:23]
	v_mfma_f32_16x16x32_bf16 v[126:129], v[140:143], v[240:243], v[128:131]
	v_mfma_f32_16x16x32_bf16 v[52:55], v[136:139], v[220:223], v[52:55]
	v_mfma_f32_16x16x32_bf16 v[48:51], v[192:195], v[220:223], v[48:51]
	v_mfma_f32_16x16x32_bf16 v[44:47], v[136:139], v[228:231], v[44:47]
	v_mfma_f32_16x16x32_bf16 v[36:39], v[192:195], v[228:231], v[36:39]
	v_mfma_f32_16x16x32_bf16 v[28:31], v[136:139], v[236:239], v[28:31]
	v_mfma_f32_16x16x32_bf16 v[20:23], v[192:195], v[236:239], v[20:23]
	v_mfma_f32_16x16x32_bf16 v[122:125], v[122:125], v[240:243], v[132:135]
	v_mfma_f32_16x16x32_bf16 v[126:129], v[192:195], v[244:247], v[126:129]
	v_mfma_f32_16x16x32_bf16 v[122:125], v[136:139], v[244:247], v[122:125]
	v_mfma_f32_16x16x32_bf16 v[40:43], v[196:199], v[216:219], v[40:43]
	v_mfma_f32_16x16x32_bf16 v[32:35], v[208:211], v[216:219], v[32:35]
	v_mfma_f32_16x16x32_bf16 v[24:27], v[196:199], v[224:227], v[24:27]
	v_mfma_f32_16x16x32_bf16 v[16:19], v[208:211], v[224:227], v[16:19]
	v_mfma_f32_16x16x32_bf16 v[12:15], v[196:199], v[232:235], v[12:15]
	v_mfma_f32_16x16x32_bf16 v[8:11], v[208:211], v[232:235], v[8:11]
	v_mfma_f32_16x16x32_bf16 v[4:7], v[196:199], v[240:243], v[4:7]
	v_mfma_f32_16x16x32_bf16 v[0:3], v[208:211], v[240:243], v[0:3]
	v_mfma_f32_16x16x32_bf16 v[40:43], v[204:207], v[220:223], v[40:43]
	v_mfma_f32_16x16x32_bf16 v[32:35], v[212:215], v[220:223], v[32:35]
	v_mfma_f32_16x16x32_bf16 v[24:27], v[204:207], v[228:231], v[24:27]
	v_mfma_f32_16x16x32_bf16 v[16:19], v[212:215], v[228:231], v[16:19]
	v_mfma_f32_16x16x32_bf16 v[12:15], v[204:207], v[236:239], v[12:15]
	v_mfma_f32_16x16x32_bf16 v[8:11], v[212:215], v[236:239], v[8:11]
	v_mfma_f32_16x16x32_bf16 v[4:7], v[204:207], v[244:247], v[4:7]
	v_mfma_f32_16x16x32_bf16 v[0:3], v[212:215], v[244:247], v[0:3]
	s_barrier
	s_add_i32 s56, 16, 0x18000
	v_add_u32_e32 v142, s56, v177
	s_add_i32 s57, 16, 0x1c000
	ds_read_b128 v[130:133], v142
	ds_read_b128 v[134:137], v142 offset:1024
	ds_read_b128 v[138:141], v142 offset:2048
	ds_read_b128 v[192:195], v142 offset:3072
	v_add_u32_e32 v142, s57, v177
	ds_read_b128 v[196:199], v142
	ds_read_b128 v[204:207], v142 offset:1024
	ds_read_b128 v[208:211], v142 offset:2048
	ds_read_b128 v[212:215], v142 offset:3072
	s_add_u32 s8, s8, 0x80000
	s_addc_u32 s9, s9, 0
	s_mov_b32 m0, s29
	v_lshl_add_u64 v[142:143], s[8:9], 0, v[144:145]
	ds_read_b128 v[216:219], v181 offset:32768
	ds_read_b128 v[220:223], v181 offset:33792
	ds_read_b128 v[224:227], v181 offset:34816
	ds_read_b128 v[228:231], v181 offset:35840
	ds_read_b128 v[232:235], v181 offset:36864
	ds_read_b128 v[236:239], v181 offset:37888
	ds_read_b128 v[240:243], v181 offset:38912
	ds_read_b128 v[244:247], v181 offset:39936
	global_load_lds_dwordx4 v[142:143], off
	v_lshl_add_u64 v[142:143], s[8:9], 0, v[148:149]
	s_mov_b32 m0, s97
	s_nop 0
	global_load_lds_dwordx4 v[142:143], off
	s_waitcnt vmcnt(8)
	s_waitcnt lgkmcnt(0)
	s_barrier
	s_waitcnt lgkmcnt(0)
	v_mfma_f32_16x16x32_bf16 v[112:115], v[130:133], v[216:219], v[112:115]
	v_mfma_f32_16x16x32_bf16 v[116:119], v[138:141], v[216:219], v[116:119]
	v_mfma_f32_16x16x32_bf16 v[108:111], v[130:133], v[224:227], v[108:111]
	v_mfma_f32_16x16x32_bf16 v[100:103], v[138:141], v[224:227], v[100:103]
	v_mfma_f32_16x16x32_bf16 v[92:95], v[130:133], v[232:235], v[92:95]
	v_mfma_f32_16x16x32_bf16 v[84:87], v[138:141], v[232:235], v[84:87]
	v_mfma_f32_16x16x32_bf16 v[76:79], v[130:133], v[240:243], v[76:79]
	v_mfma_f32_16x16x32_bf16 v[68:71], v[138:141], v[240:243], v[68:71]
	v_mfma_f32_16x16x32_bf16 v[112:115], v[134:137], v[220:223], v[112:115]
	v_mfma_f32_16x16x32_bf16 v[116:119], v[192:195], v[220:223], v[116:119]
	v_mfma_f32_16x16x32_bf16 v[108:111], v[134:137], v[228:231], v[108:111]
	v_mfma_f32_16x16x32_bf16 v[100:103], v[192:195], v[228:231], v[100:103]
	v_mfma_f32_16x16x32_bf16 v[92:95], v[134:137], v[236:239], v[92:95]
	v_mfma_f32_16x16x32_bf16 v[84:87], v[192:195], v[236:239], v[84:87]
	v_mfma_f32_16x16x32_bf16 v[76:79], v[134:137], v[244:247], v[76:79]
	v_mfma_f32_16x16x32_bf16 v[68:71], v[192:195], v[244:247], v[68:71]
	v_mfma_f32_16x16x32_bf16 v[104:107], v[196:199], v[216:219], v[104:107]
	v_mfma_f32_16x16x32_bf16 v[96:99], v[208:211], v[216:219], v[96:99]
	v_mfma_f32_16x16x32_bf16 v[88:91], v[196:199], v[224:227], v[88:91]
	v_mfma_f32_16x16x32_bf16 v[80:83], v[208:211], v[224:227], v[80:83]
	v_mfma_f32_16x16x32_bf16 v[72:75], v[196:199], v[232:235], v[72:75]
	v_mfma_f32_16x16x32_bf16 v[64:67], v[208:211], v[232:235], v[64:67]
	v_mfma_f32_16x16x32_bf16 v[60:63], v[196:199], v[240:243], v[60:63]
	v_mfma_f32_16x16x32_bf16 v[56:59], v[208:211], v[240:243], v[56:59]
	v_mfma_f32_16x16x32_bf16 v[104:107], v[204:207], v[220:223], v[104:107]
	v_mfma_f32_16x16x32_bf16 v[96:99], v[212:215], v[220:223], v[96:99]
	v_mfma_f32_16x16x32_bf16 v[88:91], v[204:207], v[228:231], v[88:91]
	v_mfma_f32_16x16x32_bf16 v[80:83], v[212:215], v[228:231], v[80:83]
	v_mfma_f32_16x16x32_bf16 v[72:75], v[204:207], v[236:239], v[72:75]
	v_mfma_f32_16x16x32_bf16 v[64:67], v[212:215], v[236:239], v[64:67]
	v_mfma_f32_16x16x32_bf16 v[60:63], v[204:207], v[244:247], v[60:63]
	v_mfma_f32_16x16x32_bf16 v[56:59], v[212:215], v[244:247], v[56:59]
	s_barrier
	s_add_i32 s8, s56, s24
	v_lshl_add_u64 v[142:143], v[200:201], 0, s[88:89]
	s_mov_b32 m0, s8
	ds_read_b128 v[216:219], v181 offset:49152
	ds_read_b128 v[220:223], v181 offset:50176
	ds_read_b128 v[224:227], v181 offset:51200
	ds_read_b128 v[228:231], v181 offset:52224
	ds_read_b128 v[232:235], v181 offset:53248
	ds_read_b128 v[236:239], v181 offset:54272
	ds_read_b128 v[240:243], v181 offset:55296
	ds_read_b128 v[244:247], v181 offset:56320
	global_load_lds_dwordx4 v[142:143], off
	s_add_i32 m0, s8, 0x2000
	s_add_u32 s4, s4, 0x80080
	v_lshl_add_u64 v[142:143], v[248:249], 0, s[88:89]
	s_addc_u32 s5, s5, 0
	s_add_i32 s8, s57, s24
	global_load_lds_dwordx4 v[142:143], off
	v_lshl_add_u64 v[142:143], s[4:5], 0, v[146:147]
	s_mov_b32 m0, s8
	s_nop 0
	global_load_lds_dwordx4 v[142:143], off
	v_lshl_add_u64 v[142:143], s[4:5], 0, v[150:151]
	s_add_i32 m0, s8, 0x2000
	s_nop 0
	global_load_lds_dwordx4 v[142:143], off
	v_lshl_add_u64 v[142:143], v[250:251], 0, s[88:89]
	s_mov_b32 m0, s80
	s_nop 0
	global_load_lds_dwordx4 v[142:143], off
	v_lshl_add_u64 v[142:143], v[252:253], 0, s[88:89]
	s_mov_b32 m0, s81
	s_nop 0
	global_load_lds_dwordx4 v[142:143], off
	s_waitcnt vmcnt(8)
	s_waitcnt lgkmcnt(0)
	s_barrier
	s_waitcnt lgkmcnt(0)
	v_mfma_f32_16x16x32_bf16 v[52:55], v[130:133], v[216:219], v[52:55]
	v_mfma_f32_16x16x32_bf16 v[44:47], v[130:133], v[224:227], v[44:47]
	v_mfma_f32_16x16x32_bf16 v[28:31], v[130:133], v[232:235], v[28:31]
	v_mfma_f32_16x16x32_bf16 v[122:125], v[130:133], v[240:243], v[122:125]
	v_mfma_f32_16x16x32_bf16 v[52:55], v[134:137], v[220:223], v[52:55]
	v_mfma_f32_16x16x32_bf16 v[48:51], v[138:141], v[216:219], v[48:51]
	v_mfma_f32_16x16x32_bf16 v[44:47], v[134:137], v[228:231], v[44:47]
	v_mfma_f32_16x16x32_bf16 v[36:39], v[138:141], v[224:227], v[36:39]
	v_mfma_f32_16x16x32_bf16 v[28:31], v[134:137], v[236:239], v[28:31]
	v_mfma_f32_16x16x32_bf16 v[20:23], v[138:141], v[232:235], v[20:23]
	v_mfma_f32_16x16x32_bf16 v[132:135], v[134:137], v[244:247], v[122:125]
	v_mfma_f32_16x16x32_bf16 v[122:125], v[138:141], v[240:243], v[126:129]
	v_mfma_f32_16x16x32_bf16 v[48:51], v[192:195], v[220:223], v[48:51]
	v_mfma_f32_16x16x32_bf16 v[36:39], v[192:195], v[228:231], v[36:39]
	v_mfma_f32_16x16x32_bf16 v[20:23], v[192:195], v[236:239], v[20:23]
	v_mfma_f32_16x16x32_bf16 v[128:131], v[192:195], v[244:247], v[122:125]
	v_mfma_f32_16x16x32_bf16 v[40:43], v[196:199], v[216:219], v[40:43]
	v_mfma_f32_16x16x32_bf16 v[32:35], v[208:211], v[216:219], v[32:35]
	v_mfma_f32_16x16x32_bf16 v[24:27], v[196:199], v[224:227], v[24:27]
	v_mfma_f32_16x16x32_bf16 v[16:19], v[208:211], v[224:227], v[16:19]
	v_mfma_f32_16x16x32_bf16 v[12:15], v[196:199], v[232:235], v[12:15]
	v_mfma_f32_16x16x32_bf16 v[8:11], v[208:211], v[232:235], v[8:11]
	v_mfma_f32_16x16x32_bf16 v[4:7], v[196:199], v[240:243], v[4:7]
	v_mfma_f32_16x16x32_bf16 v[0:3], v[208:211], v[240:243], v[0:3]
	v_mfma_f32_16x16x32_bf16 v[40:43], v[204:207], v[220:223], v[40:43]
	v_mfma_f32_16x16x32_bf16 v[32:35], v[212:215], v[220:223], v[32:35]
	v_mfma_f32_16x16x32_bf16 v[24:27], v[204:207], v[228:231], v[24:27]
	v_mfma_f32_16x16x32_bf16 v[16:19], v[212:215], v[228:231], v[16:19]
	v_mfma_f32_16x16x32_bf16 v[12:15], v[204:207], v[236:239], v[12:15]
	v_mfma_f32_16x16x32_bf16 v[8:11], v[212:215], v[236:239], v[8:11]
	v_mfma_f32_16x16x32_bf16 v[4:7], v[204:207], v[244:247], v[4:7]
	v_mfma_f32_16x16x32_bf16 v[0:3], v[212:215], v[244:247], v[0:3]
	s_barrier
	s_add_i32 s35, s35, 2
	s_add_u32 s16, s16, 0x100
	s_addc_u32 s17, s17, 0
	s_add_u32 s0, s0, 0x100
	s_addc_u32 s1, s1, 0
	s_cmp_gt_u32 s35, 29
	s_cbranch_scc1 .LBB0_196

.LBB0_532:
	s_add_i32 s92, s26, 2
	s_add_u32 s27, vcc_lo, 0xfffc0080
	s_addc_u32 s28, vcc_hi, -1
	s_add_i32 s52, 16, 0x10000
	s_cmp_eq_u32 s35, s26
	s_cselect_b32 s29, s89, s28
	s_cselect_b32 s28, s91, s27
	s_cselect_b32 s27, s33, s95
	s_cselect_b32 s26, s34, s94
	s_add_i32 s93, 16, 0x14000
	v_add_u32_e32 v140, s52, v184
	v_add_u32_e32 v187, s93, v184
	ds_read_b128 v[128:131], v140
	ds_read_b128 v[132:135], v140 offset:1024
	ds_read_b128 v[136:139], v140 offset:2048
	ds_read_b128 v[140:143], v140 offset:3072
	ds_read_b128 v[174:177], v187
	ds_read_b128 v[178:181], v187 offset:1024
	ds_read_b128 v[188:191], v187 offset:2048
	ds_read_b128 v[192:195], v187 offset:3072
	v_lshl_add_u64 v[228:229], vcc, 0, v[172:173]
	s_add_i32 m0, s63, 0xc000
	ds_read_b128 v[196:199], v153
	ds_read_b128 v[200:203], v153 offset:1024
	ds_read_b128 v[204:207], v153 offset:2048
	ds_read_b128 v[208:211], v153 offset:3072
	ds_read_b128 v[212:215], v153 offset:4096
	ds_read_b128 v[216:219], v153 offset:5120
	ds_read_b128 v[220:223], v153 offset:6144
	ds_read_b128 v[224:227], v153 offset:7168
	global_load_lds_dwordx4 v[228:229], off
	v_lshl_add_u64 v[228:229], vcc, 0, v[170:171]
	s_add_i32 m0, s63, 0xe000
	s_nop 0
	global_load_lds_dwordx4 v[228:229], off
	s_waitcnt vmcnt(8)
	s_waitcnt lgkmcnt(0)
	s_barrier
	s_waitcnt lgkmcnt(0)
	v_mfma_f32_16x16x32_bf16 v[60:63], v[128:131], v[196:199], v[60:63]
	v_mfma_f32_16x16x32_bf16 v[56:59], v[136:139], v[196:199], v[56:59]
	v_mfma_f32_16x16x32_bf16 v[44:47], v[128:131], v[204:207], v[44:47]
	v_mfma_f32_16x16x32_bf16 v[40:43], v[136:139], v[204:207], v[40:43]
	v_mfma_f32_16x16x32_bf16 v[28:31], v[128:131], v[212:215], v[28:31]
	v_mfma_f32_16x16x32_bf16 v[24:27], v[136:139], v[212:215], v[24:27]
	v_mfma_f32_16x16x32_bf16 v[12:15], v[128:131], v[220:223], v[12:15]
	v_mfma_f32_16x16x32_bf16 v[8:11], v[136:139], v[220:223], v[8:11]
	v_mfma_f32_16x16x32_bf16 v[60:63], v[132:135], v[200:203], v[60:63]
	v_mfma_f32_16x16x32_bf16 v[56:59], v[140:143], v[200:203], v[56:59]
	v_mfma_f32_16x16x32_bf16 v[44:47], v[132:135], v[208:211], v[44:47]
	v_mfma_f32_16x16x32_bf16 v[40:43], v[140:143], v[208:211], v[40:43]
	v_mfma_f32_16x16x32_bf16 v[28:31], v[132:135], v[216:219], v[28:31]
	v_mfma_f32_16x16x32_bf16 v[24:27], v[140:143], v[216:219], v[24:27]
	v_mfma_f32_16x16x32_bf16 v[12:15], v[132:135], v[224:227], v[12:15]
	v_mfma_f32_16x16x32_bf16 v[8:11], v[140:143], v[224:227], v[8:11]
	v_mfma_f32_16x16x32_bf16 v[52:55], v[174:177], v[196:199], v[52:55]
	v_mfma_f32_16x16x32_bf16 v[48:51], v[188:191], v[196:199], v[48:51]
	v_mfma_f32_16x16x32_bf16 v[36:39], v[174:177], v[204:207], v[36:39]
	v_mfma_f32_16x16x32_bf16 v[32:35], v[188:191], v[204:207], v[32:35]
	v_mfma_f32_16x16x32_bf16 v[20:23], v[174:177], v[212:215], v[20:23]
	v_mfma_f32_16x16x32_bf16 v[16:19], v[188:191], v[212:215], v[16:19]
	v_mfma_f32_16x16x32_bf16 v[4:7], v[174:177], v[220:223], v[4:7]
	v_mfma_f32_16x16x32_bf16 v[0:3], v[188:191], v[220:223], v[0:3]
	v_mfma_f32_16x16x32_bf16 v[52:55], v[178:181], v[200:203], v[52:55]
	v_mfma_f32_16x16x32_bf16 v[48:51], v[192:195], v[200:203], v[48:51]
	v_mfma_f32_16x16x32_bf16 v[36:39], v[178:181], v[208:211], v[36:39]
	v_mfma_f32_16x16x32_bf16 v[32:35], v[192:195], v[208:211], v[32:35]
	v_mfma_f32_16x16x32_bf16 v[20:23], v[178:181], v[216:219], v[20:23]
	v_mfma_f32_16x16x32_bf16 v[16:19], v[192:195], v[216:219], v[16:19]
	v_mfma_f32_16x16x32_bf16 v[4:7], v[178:181], v[224:227], v[4:7]
	v_mfma_f32_16x16x32_bf16 v[0:3], v[192:195], v[224:227], v[0:3]
	s_barrier
	s_add_i32 s52, s52, s62
	v_lshl_add_u64 v[228:229], s[26:27], 0, v[144:145]
	s_mov_b32 m0, s52
	ds_read_b128 v[196:199], v153 offset:16384
	ds_read_b128 v[200:203], v153 offset:17408
	ds_read_b128 v[204:207], v153 offset:18432
	ds_read_b128 v[208:211], v153 offset:19456
	ds_read_b128 v[212:215], v153 offset:20480
	ds_read_b128 v[216:219], v153 offset:21504
	ds_read_b128 v[220:223], v153 offset:22528
	ds_read_b128 v[224:227], v153 offset:23552
	global_load_lds_dwordx4 v[228:229], off
	s_add_i32 m0, s52, 0x2000
	s_add_u32 s52, s26, 0x40000
	v_lshl_add_u64 v[230:231], s[26:27], 0, v[146:147]
	s_addc_u32 s53, s27, 0
	s_add_i32 s93, s93, s62
	global_load_lds_dwordx4 v[230:231], off
	v_lshl_add_u64 v[232:233], s[52:53], 0, v[144:145]
	s_mov_b32 m0, s93
	v_lshl_add_u64 v[234:235], s[28:29], 0, v[148:149]
	global_load_lds_dwordx4 v[232:233], off
	v_lshl_add_u64 v[232:233], s[52:53], 0, v[146:147]
	s_add_i32 m0, s93, 0x2000
	s_nop 0
	global_load_lds_dwordx4 v[232:233], off
	v_lshl_add_u64 v[232:233], s[28:29], 0, v[150:151]
	s_mov_b32 m0, s63
	s_nop 0
	global_load_lds_dwordx4 v[232:233], off
	s_mov_b32 m0, s64
	s_nop 0
	global_load_lds_dwordx4 v[234:235], off
	s_waitcnt vmcnt(8)
	s_waitcnt lgkmcnt(0)
	s_barrier
	s_waitcnt lgkmcnt(0)
	v_mfma_f32_16x16x32_bf16 v[124:127], v[128:131], v[196:199], v[124:127]
	v_mfma_f32_16x16x32_bf16 v[120:123], v[136:139], v[196:199], v[120:123]
	v_mfma_f32_16x16x32_bf16 v[108:111], v[128:131], v[204:207], v[108:111]
	v_mfma_f32_16x16x32_bf16 v[104:107], v[136:139], v[204:207], v[104:107]
	v_mfma_f32_16x16x32_bf16 v[92:95], v[128:131], v[212:215], v[92:95]
	v_mfma_f32_16x16x32_bf16 v[88:91], v[136:139], v[212:215], v[88:91]
	v_mfma_f32_16x16x32_bf16 v[76:79], v[128:131], v[220:223], v[76:79]
	v_mfma_f32_16x16x32_bf16 v[72:75], v[136:139], v[220:223], v[72:75]
	v_mfma_f32_16x16x32_bf16 v[124:127], v[132:135], v[200:203], v[124:127]
	v_mfma_f32_16x16x32_bf16 v[120:123], v[140:143], v[200:203], v[120:123]
	v_mfma_f32_16x16x32_bf16 v[108:111], v[132:135], v[208:211], v[108:111]
	v_mfma_f32_16x16x32_bf16 v[104:107], v[140:143], v[208:211], v[104:107]
	v_mfma_f32_16x16x32_bf16 v[92:95], v[132:135], v[216:219], v[92:95]
	v_mfma_f32_16x16x32_bf16 v[88:91], v[140:143], v[216:219], v[88:91]
	v_mfma_f32_16x16x32_bf16 v[76:79], v[132:135], v[224:227], v[76:79]
	v_mfma_f32_16x16x32_bf16 v[72:75], v[140:143], v[224:227], v[72:75]
	v_mfma_f32_16x16x32_bf16 v[116:119], v[174:177], v[196:199], v[116:119]
	v_mfma_f32_16x16x32_bf16 v[112:115], v[188:191], v[196:199], v[112:115]
	v_mfma_f32_16x16x32_bf16 v[100:103], v[174:177], v[204:207], v[100:103]
	v_mfma_f32_16x16x32_bf16 v[96:99], v[188:191], v[204:207], v[96:99]
	v_mfma_f32_16x16x32_bf16 v[84:87], v[174:177], v[212:215], v[84:87]
	v_mfma_f32_16x16x32_bf16 v[80:83], v[188:191], v[212:215], v[80:83]
	v_mfma_f32_16x16x32_bf16 v[68:71], v[174:177], v[220:223], v[68:71]
	v_mfma_f32_16x16x32_bf16 v[64:67], v[188:191], v[220:223], v[64:67]
	v_mfma_f32_16x16x32_bf16 v[116:119], v[178:181], v[200:203], v[116:119]
	v_mfma_f32_16x16x32_bf16 v[112:115], v[192:195], v[200:203], v[112:115]
	v_mfma_f32_16x16x32_bf16 v[100:103], v[178:181], v[208:211], v[100:103]
	v_mfma_f32_16x16x32_bf16 v[96:99], v[192:195], v[208:211], v[96:99]
	v_mfma_f32_16x16x32_bf16 v[84:87], v[178:181], v[216:219], v[84:87]
	v_mfma_f32_16x16x32_bf16 v[80:83], v[192:195], v[216:219], v[80:83]
	v_mfma_f32_16x16x32_bf16 v[68:71], v[178:181], v[224:227], v[68:71]
	v_mfma_f32_16x16x32_bf16 v[64:67], v[192:195], v[224:227], v[64:67]
	s_barrier
	s_add_i32 s52, 16, 0x18000
	s_add_i32 s53, 16, 0x1c000
	v_add_u32_e32 v140, s52, v184
	v_add_u32_e32 v187, s53, v184
	ds_read_b128 v[128:131], v140
	ds_read_b128 v[132:135], v140 offset:1024
	ds_read_b128 v[136:139], v140 offset:2048
	ds_read_b128 v[140:143], v140 offset:3072
	ds_read_b128 v[174:177], v187
	ds_read_b128 v[178:181], v187 offset:1024
	ds_read_b128 v[188:191], v187 offset:2048
	ds_read_b128 v[192:195], v187 offset:3072
	s_add_u32 s28, s28, 0x40000
	s_addc_u32 s29, s29, 0
	s_mov_b32 m0, s65
	v_lshl_add_u64 v[236:237], s[28:29], 0, v[150:151]
	ds_read_b128 v[196:199], v153 offset:32768
	ds_read_b128 v[200:203], v153 offset:33792
	ds_read_b128 v[204:207], v153 offset:34816
	ds_read_b128 v[208:211], v153 offset:35840
	ds_read_b128 v[212:215], v153 offset:36864
	ds_read_b128 v[216:219], v153 offset:37888
	ds_read_b128 v[220:223], v153 offset:38912
	ds_read_b128 v[224:227], v153 offset:39936
	global_load_lds_dwordx4 v[236:237], off
	v_lshl_add_u64 v[236:237], s[28:29], 0, v[148:149]
	s_mov_b32 m0, s66
	s_nop 0
	global_load_lds_dwordx4 v[236:237], off
	s_waitcnt vmcnt(8)
	s_waitcnt lgkmcnt(0)
	s_barrier
	s_waitcnt lgkmcnt(0)
	v_mfma_f32_16x16x32_bf16 v[60:63], v[128:131], v[196:199], v[60:63]
	v_mfma_f32_16x16x32_bf16 v[56:59], v[136:139], v[196:199], v[56:59]
	v_mfma_f32_16x16x32_bf16 v[44:47], v[128:131], v[204:207], v[44:47]
	v_mfma_f32_16x16x32_bf16 v[40:43], v[136:139], v[204:207], v[40:43]
	v_mfma_f32_16x16x32_bf16 v[28:31], v[128:131], v[212:215], v[28:31]
	v_mfma_f32_16x16x32_bf16 v[24:27], v[136:139], v[212:215], v[24:27]
	v_mfma_f32_16x16x32_bf16 v[12:15], v[128:131], v[220:223], v[12:15]
	v_mfma_f32_16x16x32_bf16 v[8:11], v[136:139], v[220:223], v[8:11]
	v_mfma_f32_16x16x32_bf16 v[60:63], v[132:135], v[200:203], v[60:63]
	v_mfma_f32_16x16x32_bf16 v[56:59], v[140:143], v[200:203], v[56:59]
	v_mfma_f32_16x16x32_bf16 v[44:47], v[132:135], v[208:211], v[44:47]
	v_mfma_f32_16x16x32_bf16 v[40:43], v[140:143], v[208:211], v[40:43]
	v_mfma_f32_16x16x32_bf16 v[28:31], v[132:135], v[216:219], v[28:31]
	v_mfma_f32_16x16x32_bf16 v[24:27], v[140:143], v[216:219], v[24:27]
	v_mfma_f32_16x16x32_bf16 v[12:15], v[132:135], v[224:227], v[12:15]
	v_mfma_f32_16x16x32_bf16 v[8:11], v[140:143], v[224:227], v[8:11]
	v_mfma_f32_16x16x32_bf16 v[52:55], v[174:177], v[196:199], v[52:55]
	v_mfma_f32_16x16x32_bf16 v[48:51], v[188:191], v[196:199], v[48:51]
	v_mfma_f32_16x16x32_bf16 v[36:39], v[174:177], v[204:207], v[36:39]
	v_mfma_f32_16x16x32_bf16 v[32:35], v[188:191], v[204:207], v[32:35]
	v_mfma_f32_16x16x32_bf16 v[20:23], v[174:177], v[212:215], v[20:23]
	v_mfma_f32_16x16x32_bf16 v[16:19], v[188:191], v[212:215], v[16:19]
	v_mfma_f32_16x16x32_bf16 v[4:7], v[174:177], v[220:223], v[4:7]
	v_mfma_f32_16x16x32_bf16 v[0:3], v[188:191], v[220:223], v[0:3]
	v_mfma_f32_16x16x32_bf16 v[52:55], v[178:181], v[200:203], v[52:55]
	v_mfma_f32_16x16x32_bf16 v[48:51], v[192:195], v[200:203], v[48:51]
	v_mfma_f32_16x16x32_bf16 v[36:39], v[178:181], v[208:211], v[36:39]
	v_mfma_f32_16x16x32_bf16 v[32:35], v[192:195], v[208:211], v[32:35]
	v_mfma_f32_16x16x32_bf16 v[20:23], v[178:181], v[216:219], v[20:23]
	v_mfma_f32_16x16x32_bf16 v[16:19], v[192:195], v[216:219], v[16:19]
	v_mfma_f32_16x16x32_bf16 v[4:7], v[178:181], v[224:227], v[4:7]
	v_mfma_f32_16x16x32_bf16 v[0:3], v[192:195], v[224:227], v[0:3]
	s_barrier
	s_add_i32 s28, s52, s62
	v_lshl_add_u64 v[228:229], v[228:229], 0, s[54:55]
	s_mov_b32 m0, s28
	ds_read_b128 v[196:199], v153 offset:49152
	ds_read_b128 v[200:203], v153 offset:50176
	ds_read_b128 v[204:207], v153 offset:51200
	ds_read_b128 v[208:211], v153 offset:52224
	ds_read_b128 v[212:215], v153 offset:53248
	ds_read_b128 v[216:219], v153 offset:54272
	ds_read_b128 v[220:223], v153 offset:55296
	ds_read_b128 v[224:227], v153 offset:56320
	global_load_lds_dwordx4 v[228:229], off
	s_add_i32 m0, s28, 0x2000
	s_add_u32 s26, s26, 0x40080
	v_lshl_add_u64 v[228:229], v[230:231], 0, s[54:55]
	s_addc_u32 s27, s27, 0
	s_add_i32 s28, s53, s62
	global_load_lds_dwordx4 v[228:229], off
	v_lshl_add_u64 v[228:229], s[26:27], 0, v[144:145]
	s_mov_b32 m0, s28
	s_nop 0
	global_load_lds_dwordx4 v[228:229], off
	v_lshl_add_u64 v[228:229], s[26:27], 0, v[146:147]
	s_add_i32 m0, s28, 0x2000
	s_nop 0
	global_load_lds_dwordx4 v[228:229], off
	v_lshl_add_u64 v[228:229], v[232:233], 0, s[54:55]
	s_mov_b32 m0, s67
	s_nop 0
	global_load_lds_dwordx4 v[228:229], off
	v_lshl_add_u64 v[228:229], v[234:235], 0, s[54:55]
	s_mov_b32 m0, s77
	s_nop 0
	global_load_lds_dwordx4 v[228:229], off
	s_waitcnt vmcnt(8)
	s_waitcnt lgkmcnt(0)
	s_barrier
	s_waitcnt lgkmcnt(0)
	v_mfma_f32_16x16x32_bf16 v[124:127], v[128:131], v[196:199], v[124:127]
	v_mfma_f32_16x16x32_bf16 v[120:123], v[136:139], v[196:199], v[120:123]
	v_mfma_f32_16x16x32_bf16 v[108:111], v[128:131], v[204:207], v[108:111]
	v_mfma_f32_16x16x32_bf16 v[104:107], v[136:139], v[204:207], v[104:107]
	v_mfma_f32_16x16x32_bf16 v[92:95], v[128:131], v[212:215], v[92:95]
	v_mfma_f32_16x16x32_bf16 v[88:91], v[136:139], v[212:215], v[88:91]
	v_mfma_f32_16x16x32_bf16 v[76:79], v[128:131], v[220:223], v[76:79]
	v_mfma_f32_16x16x32_bf16 v[72:75], v[136:139], v[220:223], v[72:75]
	v_mfma_f32_16x16x32_bf16 v[124:127], v[132:135], v[200:203], v[124:127]
	v_mfma_f32_16x16x32_bf16 v[120:123], v[140:143], v[200:203], v[120:123]
	v_mfma_f32_16x16x32_bf16 v[108:111], v[132:135], v[208:211], v[108:111]
	v_mfma_f32_16x16x32_bf16 v[104:107], v[140:143], v[208:211], v[104:107]
	v_mfma_f32_16x16x32_bf16 v[92:95], v[132:135], v[216:219], v[92:95]
	v_mfma_f32_16x16x32_bf16 v[88:91], v[140:143], v[216:219], v[88:91]
	v_mfma_f32_16x16x32_bf16 v[76:79], v[132:135], v[224:227], v[76:79]
	v_mfma_f32_16x16x32_bf16 v[72:75], v[140:143], v[224:227], v[72:75]
	v_mfma_f32_16x16x32_bf16 v[116:119], v[174:177], v[196:199], v[116:119]
	v_mfma_f32_16x16x32_bf16 v[112:115], v[188:191], v[196:199], v[112:115]
	v_mfma_f32_16x16x32_bf16 v[100:103], v[174:177], v[204:207], v[100:103]
	v_mfma_f32_16x16x32_bf16 v[96:99], v[188:191], v[204:207], v[96:99]
	v_mfma_f32_16x16x32_bf16 v[84:87], v[174:177], v[212:215], v[84:87]
	v_mfma_f32_16x16x32_bf16 v[80:83], v[188:191], v[212:215], v[80:83]
	v_mfma_f32_16x16x32_bf16 v[68:71], v[174:177], v[220:223], v[68:71]
	v_mfma_f32_16x16x32_bf16 v[64:67], v[188:191], v[220:223], v[64:67]
	v_mfma_f32_16x16x32_bf16 v[116:119], v[178:181], v[200:203], v[116:119]
	v_mfma_f32_16x16x32_bf16 v[112:115], v[192:195], v[200:203], v[112:115]
	v_mfma_f32_16x16x32_bf16 v[100:103], v[178:181], v[208:211], v[100:103]
	v_mfma_f32_16x16x32_bf16 v[96:99], v[192:195], v[208:211], v[96:99]
	v_mfma_f32_16x16x32_bf16 v[84:87], v[178:181], v[216:219], v[84:87]
	v_mfma_f32_16x16x32_bf16 v[80:83], v[192:195], v[216:219], v[80:83]
	v_mfma_f32_16x16x32_bf16 v[68:71], v[178:181], v[224:227], v[68:71]
	v_mfma_f32_16x16x32_bf16 v[64:67], v[192:195], v[224:227], v[64:67]
	s_barrier
	s_add_u32 s94, s94, 0x100
	s_addc_u32 s95, s95, 0
	s_add_u32 vcc_lo, vcc_lo, 0x100
	s_addc_u32 vcc_hi, vcc_hi, 0
	s_cmp_ge_u32 s92, s57
	s_mov_b32 s26, s92
	s_cbranch_scc0 .LBB0_532
	s_and_b64 vcc, exec, s[80:81]
	s_cbranch_vccz .LBB0_535
	s_barrier

.LBB0_623:
	ds_read_b128 v[158:161], v137
	ds_read_b128 v[162:165], v137 offset:1024
	ds_read_b128 v[166:169], v137 offset:2048
	ds_read_b128 v[170:173], v137 offset:3072
	ds_read_b128 v[186:189], v177
	ds_read_b128 v[190:193], v177 offset:1024
	ds_read_b128 v[194:197], v177 offset:2048
	ds_read_b128 v[198:201], v177 offset:3072
	s_add_i32 s81, s14, 2
	s_add_u32 s15, s8, 0xfffc0080
	s_addc_u32 s24, s9, -1
	s_cmp_eq_u32 s33, s14
	s_cselect_b32 s14, s27, s77
	s_cselect_b32 s25, s83, s24
	s_cselect_b32 s24, s82, s15
	s_cselect_b32 s15, s26, s79
	v_lshl_add_u64 v[180:181], s[8:9], 0, v[156:157]
	s_add_i32 m0, s11, 0xc000
	ds_read_b128 v[202:205], v178
	ds_read_b128 v[206:209], v178 offset:1024
	ds_read_b128 v[210:213], v178 offset:2048
	ds_read_b128 v[214:217], v178 offset:3072
	ds_read_b128 v[218:221], v178 offset:4096
	ds_read_b128 v[222:225], v178 offset:5120
	ds_read_b128 v[226:229], v178 offset:6144
	ds_read_b128 v[230:233], v178 offset:7168
	global_load_lds_dwordx4 v[180:181], off
	v_lshl_add_u64 v[180:181], s[8:9], 0, v[154:155]
	s_add_i32 m0, s11, 0xe000
	s_nop 0
	global_load_lds_dwordx4 v[180:181], off
	s_waitcnt vmcnt(8)
	s_waitcnt lgkmcnt(0)
	s_barrier
	s_waitcnt lgkmcnt(0)
	v_mfma_f32_16x16x32_bf16 v[60:63], v[158:161], v[202:205], v[60:63]
	v_mfma_f32_16x16x32_bf16 v[56:59], v[166:169], v[202:205], v[56:59]
	v_mfma_f32_16x16x32_bf16 v[44:47], v[158:161], v[210:213], v[44:47]
	v_mfma_f32_16x16x32_bf16 v[40:43], v[166:169], v[210:213], v[40:43]
	v_mfma_f32_16x16x32_bf16 v[28:31], v[158:161], v[218:221], v[28:31]
	v_mfma_f32_16x16x32_bf16 v[24:27], v[166:169], v[218:221], v[24:27]
	v_mfma_f32_16x16x32_bf16 v[12:15], v[158:161], v[226:229], v[12:15]
	v_mfma_f32_16x16x32_bf16 v[8:11], v[166:169], v[226:229], v[8:11]
	v_mfma_f32_16x16x32_bf16 v[60:63], v[162:165], v[206:209], v[60:63]
	v_mfma_f32_16x16x32_bf16 v[56:59], v[170:173], v[206:209], v[56:59]
	v_mfma_f32_16x16x32_bf16 v[44:47], v[162:165], v[214:217], v[44:47]
	v_mfma_f32_16x16x32_bf16 v[40:43], v[170:173], v[214:217], v[40:43]
	v_mfma_f32_16x16x32_bf16 v[28:31], v[162:165], v[222:225], v[28:31]
	v_mfma_f32_16x16x32_bf16 v[24:27], v[170:173], v[222:225], v[24:27]
	v_mfma_f32_16x16x32_bf16 v[12:15], v[162:165], v[230:233], v[12:15]
	v_mfma_f32_16x16x32_bf16 v[8:11], v[170:173], v[230:233], v[8:11]
	v_mfma_f32_16x16x32_bf16 v[52:55], v[186:189], v[202:205], v[52:55]
	v_mfma_f32_16x16x32_bf16 v[48:51], v[194:197], v[202:205], v[48:51]
	v_mfma_f32_16x16x32_bf16 v[36:39], v[186:189], v[210:213], v[36:39]
	v_mfma_f32_16x16x32_bf16 v[32:35], v[194:197], v[210:213], v[32:35]
	v_mfma_f32_16x16x32_bf16 v[20:23], v[186:189], v[218:221], v[20:23]
	v_mfma_f32_16x16x32_bf16 v[16:19], v[194:197], v[218:221], v[16:19]
	v_mfma_f32_16x16x32_bf16 v[4:7], v[186:189], v[226:229], v[4:7]
	v_mfma_f32_16x16x32_bf16 v[0:3], v[194:197], v[226:229], v[0:3]
	v_mfma_f32_16x16x32_bf16 v[52:55], v[190:193], v[206:209], v[52:55]
	v_mfma_f32_16x16x32_bf16 v[48:51], v[198:201], v[206:209], v[48:51]
	v_mfma_f32_16x16x32_bf16 v[36:39], v[190:193], v[214:217], v[36:39]
	v_mfma_f32_16x16x32_bf16 v[32:35], v[198:201], v[214:217], v[32:35]
	v_mfma_f32_16x16x32_bf16 v[20:23], v[190:193], v[222:225], v[20:23]
	v_mfma_f32_16x16x32_bf16 v[16:19], v[198:201], v[222:225], v[16:19]
	v_mfma_f32_16x16x32_bf16 v[4:7], v[190:193], v[230:233], v[4:7]
	v_mfma_f32_16x16x32_bf16 v[0:3], v[198:201], v[230:233], v[0:3]
	s_barrier
	s_add_i32 s87, s64, s28
	v_lshl_add_u64 v[180:181], s[14:15], 0, v[130:131]
	s_mov_b32 m0, s87
	ds_read_b128 v[202:205], v178 offset:16384
	ds_read_b128 v[206:209], v178 offset:17408
	ds_read_b128 v[210:213], v178 offset:18432
	ds_read_b128 v[214:217], v178 offset:19456
	ds_read_b128 v[218:221], v178 offset:20480
	ds_read_b128 v[222:225], v178 offset:21504
	ds_read_b128 v[226:229], v178 offset:22528
	ds_read_b128 v[230:233], v178 offset:23552
	global_load_lds_dwordx4 v[180:181], off
	s_add_i32 m0, s87, 0x2000
	s_add_u32 s92, s14, 0x40000
	v_lshl_add_u64 v[234:235], s[14:15], 0, v[134:135]
	s_addc_u32 s93, s15, 0
	s_add_i32 s87, s65, s28
	global_load_lds_dwordx4 v[234:235], off
	v_lshl_add_u64 v[236:237], s[92:93], 0, v[130:131]
	s_mov_b32 m0, s87
	v_lshl_add_u64 v[238:239], s[24:25], 0, v[132:133]
	global_load_lds_dwordx4 v[236:237], off
	v_lshl_add_u64 v[236:237], s[92:93], 0, v[134:135]
	s_add_i32 m0, s87, 0x2000
	s_nop 0
	global_load_lds_dwordx4 v[236:237], off
	v_lshl_add_u64 v[236:237], s[24:25], 0, v[128:129]
	s_mov_b32 m0, s11
	s_nop 0
	global_load_lds_dwordx4 v[236:237], off
	s_mov_b32 m0, s29
	s_nop 0
	global_load_lds_dwordx4 v[238:239], off
	s_waitcnt vmcnt(8)
	s_waitcnt lgkmcnt(0)
	s_barrier
	s_waitcnt lgkmcnt(0)
	v_mfma_f32_16x16x32_bf16 v[124:127], v[158:161], v[202:205], v[124:127]
	v_mfma_f32_16x16x32_bf16 v[120:123], v[166:169], v[202:205], v[120:123]
	v_mfma_f32_16x16x32_bf16 v[108:111], v[158:161], v[210:213], v[108:111]
	v_mfma_f32_16x16x32_bf16 v[104:107], v[166:169], v[210:213], v[104:107]
	v_mfma_f32_16x16x32_bf16 v[92:95], v[158:161], v[218:221], v[92:95]
	v_mfma_f32_16x16x32_bf16 v[88:91], v[166:169], v[218:221], v[88:91]
	v_mfma_f32_16x16x32_bf16 v[76:79], v[158:161], v[226:229], v[76:79]
	v_mfma_f32_16x16x32_bf16 v[72:75], v[166:169], v[226:229], v[72:75]
	v_mfma_f32_16x16x32_bf16 v[124:127], v[162:165], v[206:209], v[124:127]
	v_mfma_f32_16x16x32_bf16 v[120:123], v[170:173], v[206:209], v[120:123]
	v_mfma_f32_16x16x32_bf16 v[108:111], v[162:165], v[214:217], v[108:111]
	v_mfma_f32_16x16x32_bf16 v[104:107], v[170:173], v[214:217], v[104:107]
	v_mfma_f32_16x16x32_bf16 v[92:95], v[162:165], v[222:225], v[92:95]
	v_mfma_f32_16x16x32_bf16 v[88:91], v[170:173], v[222:225], v[88:91]
	v_mfma_f32_16x16x32_bf16 v[76:79], v[162:165], v[230:233], v[76:79]
	v_mfma_f32_16x16x32_bf16 v[72:75], v[170:173], v[230:233], v[72:75]
	v_mfma_f32_16x16x32_bf16 v[116:119], v[186:189], v[202:205], v[116:119]
	v_mfma_f32_16x16x32_bf16 v[112:115], v[194:197], v[202:205], v[112:115]
	v_mfma_f32_16x16x32_bf16 v[100:103], v[186:189], v[210:213], v[100:103]
	v_mfma_f32_16x16x32_bf16 v[96:99], v[194:197], v[210:213], v[96:99]
	v_mfma_f32_16x16x32_bf16 v[84:87], v[186:189], v[218:221], v[84:87]
	v_mfma_f32_16x16x32_bf16 v[80:83], v[194:197], v[218:221], v[80:83]
	v_mfma_f32_16x16x32_bf16 v[68:71], v[186:189], v[226:229], v[68:71]
	v_mfma_f32_16x16x32_bf16 v[64:67], v[194:197], v[226:229], v[64:67]
	v_mfma_f32_16x16x32_bf16 v[116:119], v[190:193], v[206:209], v[116:119]
	v_mfma_f32_16x16x32_bf16 v[112:115], v[198:201], v[206:209], v[112:115]
	v_mfma_f32_16x16x32_bf16 v[100:103], v[190:193], v[214:217], v[100:103]
	v_mfma_f32_16x16x32_bf16 v[96:99], v[198:201], v[214:217], v[96:99]
	v_mfma_f32_16x16x32_bf16 v[84:87], v[190:193], v[222:225], v[84:87]
	v_mfma_f32_16x16x32_bf16 v[80:83], v[198:201], v[222:225], v[80:83]
	v_mfma_f32_16x16x32_bf16 v[68:71], v[190:193], v[230:233], v[68:71]
	v_mfma_f32_16x16x32_bf16 v[64:67], v[198:201], v[230:233], v[64:67]
	s_barrier
	s_add_i32 s87, 16, 0x18000
	s_add_i32 s92, 16, 0x1c000
	v_add_u32_e32 v170, s87, v175
	v_add_u32_e32 v179, s92, v175
	ds_read_b128 v[158:161], v170
	ds_read_b128 v[162:165], v170 offset:1024
	ds_read_b128 v[166:169], v170 offset:2048
	ds_read_b128 v[170:173], v170 offset:3072
	ds_read_b128 v[186:189], v179
	ds_read_b128 v[190:193], v179 offset:1024
	ds_read_b128 v[194:197], v179 offset:2048
	ds_read_b128 v[198:201], v179 offset:3072
	s_add_u32 s24, s24, 0x40000
	s_addc_u32 s25, s25, 0
	s_mov_b32 m0, s30
	v_lshl_add_u64 v[240:241], s[24:25], 0, v[128:129]
	ds_read_b128 v[202:205], v178 offset:32768
	ds_read_b128 v[206:209], v178 offset:33792
	ds_read_b128 v[210:213], v178 offset:34816
	ds_read_b128 v[214:217], v178 offset:35840
	ds_read_b128 v[218:221], v178 offset:36864
	ds_read_b128 v[222:225], v178 offset:37888
	ds_read_b128 v[226:229], v178 offset:38912
	ds_read_b128 v[230:233], v178 offset:39936
	global_load_lds_dwordx4 v[240:241], off
	v_lshl_add_u64 v[240:241], s[24:25], 0, v[132:133]
	s_mov_b32 m0, s56
	s_nop 0
	global_load_lds_dwordx4 v[240:241], off
	s_waitcnt vmcnt(8)
	s_waitcnt lgkmcnt(0)
	s_barrier
	s_waitcnt lgkmcnt(0)
	v_mfma_f32_16x16x32_bf16 v[60:63], v[158:161], v[202:205], v[60:63]
	v_mfma_f32_16x16x32_bf16 v[56:59], v[166:169], v[202:205], v[56:59]
	v_mfma_f32_16x16x32_bf16 v[44:47], v[158:161], v[210:213], v[44:47]
	v_mfma_f32_16x16x32_bf16 v[40:43], v[166:169], v[210:213], v[40:43]
	v_mfma_f32_16x16x32_bf16 v[28:31], v[158:161], v[218:221], v[28:31]
	v_mfma_f32_16x16x32_bf16 v[24:27], v[166:169], v[218:221], v[24:27]
	v_mfma_f32_16x16x32_bf16 v[12:15], v[158:161], v[226:229], v[12:15]
	v_mfma_f32_16x16x32_bf16 v[8:11], v[166:169], v[226:229], v[8:11]
	v_mfma_f32_16x16x32_bf16 v[60:63], v[162:165], v[206:209], v[60:63]
	v_mfma_f32_16x16x32_bf16 v[56:59], v[170:173], v[206:209], v[56:59]
	v_mfma_f32_16x16x32_bf16 v[44:47], v[162:165], v[214:217], v[44:47]
	v_mfma_f32_16x16x32_bf16 v[40:43], v[170:173], v[214:217], v[40:43]
	v_mfma_f32_16x16x32_bf16 v[28:31], v[162:165], v[222:225], v[28:31]
	v_mfma_f32_16x16x32_bf16 v[24:27], v[170:173], v[222:225], v[24:27]
	v_mfma_f32_16x16x32_bf16 v[12:15], v[162:165], v[230:233], v[12:15]
	v_mfma_f32_16x16x32_bf16 v[8:11], v[170:173], v[230:233], v[8:11]
	v_mfma_f32_16x16x32_bf16 v[52:55], v[186:189], v[202:205], v[52:55]
	v_mfma_f32_16x16x32_bf16 v[48:51], v[194:197], v[202:205], v[48:51]
	v_mfma_f32_16x16x32_bf16 v[36:39], v[186:189], v[210:213], v[36:39]
	v_mfma_f32_16x16x32_bf16 v[32:35], v[194:197], v[210:213], v[32:35]
	v_mfma_f32_16x16x32_bf16 v[20:23], v[186:189], v[218:221], v[20:23]
	v_mfma_f32_16x16x32_bf16 v[16:19], v[194:197], v[218:221], v[16:19]
	v_mfma_f32_16x16x32_bf16 v[4:7], v[186:189], v[226:229], v[4:7]
	v_mfma_f32_16x16x32_bf16 v[0:3], v[194:197], v[226:229], v[0:3]
	v_mfma_f32_16x16x32_bf16 v[52:55], v[190:193], v[206:209], v[52:55]
	v_mfma_f32_16x16x32_bf16 v[48:51], v[198:201], v[206:209], v[48:51]
	v_mfma_f32_16x16x32_bf16 v[36:39], v[190:193], v[214:217], v[36:39]
	v_mfma_f32_16x16x32_bf16 v[32:35], v[198:201], v[214:217], v[32:35]
	v_mfma_f32_16x16x32_bf16 v[20:23], v[190:193], v[222:225], v[20:23]
	v_mfma_f32_16x16x32_bf16 v[16:19], v[198:201], v[222:225], v[16:19]
	v_mfma_f32_16x16x32_bf16 v[4:7], v[190:193], v[230:233], v[4:7]
	v_mfma_f32_16x16x32_bf16 v[0:3], v[198:201], v[230:233], v[0:3]
	s_barrier
	s_add_i32 s24, s87, s28
	v_lshl_add_u64 v[180:181], v[180:181], 0, s[16:17]
	s_mov_b32 m0, s24
	ds_read_b128 v[202:205], v178 offset:49152
	ds_read_b128 v[206:209], v178 offset:50176
	ds_read_b128 v[210:213], v178 offset:51200
	ds_read_b128 v[214:217], v178 offset:52224
	ds_read_b128 v[218:221], v178 offset:53248
	ds_read_b128 v[222:225], v178 offset:54272
	ds_read_b128 v[226:229], v178 offset:55296
	ds_read_b128 v[230:233], v178 offset:56320
	global_load_lds_dwordx4 v[180:181], off
	s_add_i32 m0, s24, 0x2000
	s_add_u32 s14, s14, 0x40080
	v_lshl_add_u64 v[180:181], v[234:235], 0, s[16:17]
	s_addc_u32 s15, s15, 0
	s_add_i32 s24, s92, s28
	global_load_lds_dwordx4 v[180:181], off
	v_lshl_add_u64 v[180:181], s[14:15], 0, v[130:131]
	s_mov_b32 m0, s24
	s_nop 0
	global_load_lds_dwordx4 v[180:181], off
	v_lshl_add_u64 v[180:181], s[14:15], 0, v[134:135]
	s_add_i32 m0, s24, 0x2000
	s_nop 0
	global_load_lds_dwordx4 v[180:181], off
	v_lshl_add_u64 v[180:181], v[236:237], 0, s[16:17]
	s_mov_b32 m0, s57
	s_nop 0
	global_load_lds_dwordx4 v[180:181], off
	v_lshl_add_u64 v[180:181], v[238:239], 0, s[16:17]
	s_mov_b32 m0, s58
	s_nop 0
	global_load_lds_dwordx4 v[180:181], off
	s_waitcnt vmcnt(8)
	s_waitcnt lgkmcnt(0)
	s_barrier
	s_waitcnt lgkmcnt(0)
	v_mfma_f32_16x16x32_bf16 v[124:127], v[158:161], v[202:205], v[124:127]
	v_mfma_f32_16x16x32_bf16 v[120:123], v[166:169], v[202:205], v[120:123]
	v_mfma_f32_16x16x32_bf16 v[108:111], v[158:161], v[210:213], v[108:111]
	v_mfma_f32_16x16x32_bf16 v[104:107], v[166:169], v[210:213], v[104:107]
	v_mfma_f32_16x16x32_bf16 v[92:95], v[158:161], v[218:221], v[92:95]
	v_mfma_f32_16x16x32_bf16 v[88:91], v[166:169], v[218:221], v[88:91]
	v_mfma_f32_16x16x32_bf16 v[76:79], v[158:161], v[226:229], v[76:79]
	v_mfma_f32_16x16x32_bf16 v[72:75], v[166:169], v[226:229], v[72:75]
	v_mfma_f32_16x16x32_bf16 v[124:127], v[162:165], v[206:209], v[124:127]
	v_mfma_f32_16x16x32_bf16 v[120:123], v[170:173], v[206:209], v[120:123]
	v_mfma_f32_16x16x32_bf16 v[108:111], v[162:165], v[214:217], v[108:111]
	v_mfma_f32_16x16x32_bf16 v[104:107], v[170:173], v[214:217], v[104:107]
	v_mfma_f32_16x16x32_bf16 v[92:95], v[162:165], v[222:225], v[92:95]
	v_mfma_f32_16x16x32_bf16 v[88:91], v[170:173], v[222:225], v[88:91]
	v_mfma_f32_16x16x32_bf16 v[76:79], v[162:165], v[230:233], v[76:79]
	v_mfma_f32_16x16x32_bf16 v[72:75], v[170:173], v[230:233], v[72:75]
	v_mfma_f32_16x16x32_bf16 v[116:119], v[186:189], v[202:205], v[116:119]
	v_mfma_f32_16x16x32_bf16 v[112:115], v[194:197], v[202:205], v[112:115]
	v_mfma_f32_16x16x32_bf16 v[100:103], v[186:189], v[210:213], v[100:103]
	v_mfma_f32_16x16x32_bf16 v[96:99], v[194:197], v[210:213], v[96:99]
	v_mfma_f32_16x16x32_bf16 v[84:87], v[186:189], v[218:221], v[84:87]
	v_mfma_f32_16x16x32_bf16 v[80:83], v[194:197], v[218:221], v[80:83]
	v_mfma_f32_16x16x32_bf16 v[68:71], v[186:189], v[226:229], v[68:71]
	v_mfma_f32_16x16x32_bf16 v[64:67], v[194:197], v[226:229], v[64:67]
	v_mfma_f32_16x16x32_bf16 v[116:119], v[190:193], v[206:209], v[116:119]
	v_mfma_f32_16x16x32_bf16 v[112:115], v[198:201], v[206:209], v[112:115]
	v_mfma_f32_16x16x32_bf16 v[100:103], v[190:193], v[214:217], v[100:103]
	v_mfma_f32_16x16x32_bf16 v[96:99], v[198:201], v[214:217], v[96:99]
	v_mfma_f32_16x16x32_bf16 v[84:87], v[190:193], v[222:225], v[84:87]
	v_mfma_f32_16x16x32_bf16 v[80:83], v[198:201], v[222:225], v[80:83]
	v_mfma_f32_16x16x32_bf16 v[68:71], v[190:193], v[230:233], v[68:71]
	v_mfma_f32_16x16x32_bf16 v[64:67], v[198:201], v[230:233], v[64:67]
	s_barrier
	s_add_u32 s77, s77, 0x100
	s_addc_u32 s79, s79, 0
	s_add_u32 s8, s8, 0x100
	s_addc_u32 s9, s9, 0
	s_cmp_ge_u32 s81, s86
	s_mov_b32 s14, s81
	s_cbranch_scc0 .LBB0_623
	s_and_b64 vcc, exec, s[34:35]
	s_cbranch_vccz .LBB0_626
	s_barrier

.LBB0_778:
	ds_read_b128 v[152:155], v139
	ds_read_b128 v[166:169], v139 offset:1024
	ds_read_b128 v[170:173], v139 offset:2048
	ds_read_b128 v[174:177], v139 offset:3072
	ds_read_b128 v[178:181], v161
	ds_read_b128 v[186:189], v161 offset:1024
	ds_read_b128 v[190:193], v161 offset:2048
	ds_read_b128 v[194:197], v161 offset:3072
	s_add_i32 s94, s14, 2
	s_add_u32 s15, s92, 0xfff80080
	s_addc_u32 s24, s93, -1
	s_cmp_eq_u32 vcc_lo, s14
	s_cselect_b32 s14, s85, vcc_hi
	s_cselect_b32 s25, s1, s24
	s_cselect_b32 s24, s11, s15
	s_cselect_b32 s15, s83, s53
	v_lshl_add_u64 v[156:157], s[92:93], 0, v[150:151]
	s_add_i32 m0, s30, 0xc000
	ds_read_b128 v[198:201], v162
	ds_read_b128 v[202:205], v162 offset:1024
	ds_read_b128 v[206:209], v162 offset:2048
	ds_read_b128 v[210:213], v162 offset:3072
	ds_read_b128 v[214:217], v162 offset:4096
	ds_read_b128 v[218:221], v162 offset:5120
	ds_read_b128 v[222:225], v162 offset:6144
	ds_read_b128 v[226:229], v162 offset:7168
	global_load_lds_dwordx4 v[156:157], off
	v_lshl_add_u64 v[156:157], s[92:93], 0, v[148:149]
	s_add_i32 m0, s30, 0xe000
	s_nop 0
	global_load_lds_dwordx4 v[156:157], off
	s_waitcnt vmcnt(8)
	s_waitcnt lgkmcnt(0)
	s_barrier
	s_waitcnt lgkmcnt(0)
	v_mfma_f32_16x16x32_bf16 v[60:63], v[152:155], v[198:201], v[60:63]
	v_mfma_f32_16x16x32_bf16 v[56:59], v[170:173], v[198:201], v[56:59]
	v_mfma_f32_16x16x32_bf16 v[52:55], v[152:155], v[206:209], v[52:55]
	v_mfma_f32_16x16x32_bf16 v[48:51], v[170:173], v[206:209], v[48:51]
	v_mfma_f32_16x16x32_bf16 v[44:47], v[152:155], v[214:217], v[44:47]
	v_mfma_f32_16x16x32_bf16 v[40:43], v[170:173], v[214:217], v[40:43]
	v_mfma_f32_16x16x32_bf16 v[28:31], v[152:155], v[222:225], v[28:31]
	v_mfma_f32_16x16x32_bf16 v[24:27], v[170:173], v[222:225], v[24:27]
	v_mfma_f32_16x16x32_bf16 v[60:63], v[166:169], v[202:205], v[60:63]
	v_mfma_f32_16x16x32_bf16 v[56:59], v[174:177], v[202:205], v[56:59]
	v_mfma_f32_16x16x32_bf16 v[52:55], v[166:169], v[210:213], v[52:55]
	v_mfma_f32_16x16x32_bf16 v[48:51], v[174:177], v[210:213], v[48:51]
	v_mfma_f32_16x16x32_bf16 v[44:47], v[166:169], v[218:221], v[44:47]
	v_mfma_f32_16x16x32_bf16 v[40:43], v[174:177], v[218:221], v[40:43]
	v_mfma_f32_16x16x32_bf16 v[28:31], v[166:169], v[226:229], v[28:31]
	v_mfma_f32_16x16x32_bf16 v[24:27], v[174:177], v[226:229], v[24:27]
	v_mfma_f32_16x16x32_bf16 v[36:39], v[178:181], v[198:201], v[36:39]
	v_mfma_f32_16x16x32_bf16 v[32:35], v[190:193], v[198:201], v[32:35]
	v_mfma_f32_16x16x32_bf16 v[20:23], v[178:181], v[206:209], v[20:23]
	v_mfma_f32_16x16x32_bf16 v[16:19], v[190:193], v[206:209], v[16:19]
	v_mfma_f32_16x16x32_bf16 v[12:15], v[178:181], v[214:217], v[12:15]
	v_mfma_f32_16x16x32_bf16 v[8:11], v[190:193], v[214:217], v[8:11]
	v_mfma_f32_16x16x32_bf16 v[4:7], v[178:181], v[222:225], v[4:7]
	v_mfma_f32_16x16x32_bf16 v[0:3], v[190:193], v[222:225], v[0:3]
	v_mfma_f32_16x16x32_bf16 v[36:39], v[186:189], v[202:205], v[36:39]
	v_mfma_f32_16x16x32_bf16 v[32:35], v[194:197], v[202:205], v[32:35]
	v_mfma_f32_16x16x32_bf16 v[20:23], v[186:189], v[210:213], v[20:23]
	v_mfma_f32_16x16x32_bf16 v[16:19], v[194:197], v[210:213], v[16:19]
	v_mfma_f32_16x16x32_bf16 v[12:15], v[186:189], v[218:221], v[12:15]
	v_mfma_f32_16x16x32_bf16 v[8:11], v[194:197], v[218:221], v[8:11]
	v_mfma_f32_16x16x32_bf16 v[4:7], v[186:189], v[226:229], v[4:7]
	v_mfma_f32_16x16x32_bf16 v[0:3], v[194:197], v[226:229], v[0:3]
	s_barrier
	s_add_i32 s54, s60, s29
	v_lshl_add_u64 v[156:157], s[14:15], 0, v[130:131]
	s_mov_b32 m0, s54
	ds_read_b128 v[198:201], v162 offset:16384
	ds_read_b128 v[202:205], v162 offset:17408
	ds_read_b128 v[206:209], v162 offset:18432
	ds_read_b128 v[210:213], v162 offset:19456
	ds_read_b128 v[214:217], v162 offset:20480
	ds_read_b128 v[218:221], v162 offset:21504
	ds_read_b128 v[222:225], v162 offset:22528
	ds_read_b128 v[226:229], v162 offset:23552
	global_load_lds_dwordx4 v[156:157], off
	s_add_i32 m0, s54, 0x2000
	s_add_u32 s54, s14, 0x80000
	v_lshl_add_u64 v[230:231], s[14:15], 0, v[134:135]
	s_addc_u32 s55, s15, 0
	s_add_i32 s95, s61, s29
	global_load_lds_dwordx4 v[230:231], off
	v_lshl_add_u64 v[232:233], s[54:55], 0, v[130:131]
	s_mov_b32 m0, s95
	v_lshl_add_u64 v[234:235], s[24:25], 0, v[132:133]
	global_load_lds_dwordx4 v[232:233], off
	v_lshl_add_u64 v[232:233], s[54:55], 0, v[134:135]
	s_add_i32 m0, s95, 0x2000
	s_nop 0
	global_load_lds_dwordx4 v[232:233], off
	v_lshl_add_u64 v[232:233], s[24:25], 0, v[128:129]
	s_mov_b32 m0, s30
	s_nop 0
	global_load_lds_dwordx4 v[232:233], off
	s_mov_b32 m0, s31
	s_nop 0
	global_load_lds_dwordx4 v[234:235], off
	s_waitcnt vmcnt(8)
	s_waitcnt lgkmcnt(0)
	s_barrier
	s_waitcnt lgkmcnt(0)
	v_mfma_f32_16x16x32_bf16 v[120:123], v[152:155], v[198:201], v[120:123]
	v_mfma_f32_16x16x32_bf16 v[124:127], v[170:173], v[198:201], v[124:127]
	v_mfma_f32_16x16x32_bf16 v[104:107], v[152:155], v[206:209], v[104:107]
	v_mfma_f32_16x16x32_bf16 v[108:111], v[170:173], v[206:209], v[108:111]
	v_mfma_f32_16x16x32_bf16 v[88:91], v[152:155], v[214:217], v[88:91]
	v_mfma_f32_16x16x32_bf16 v[92:95], v[170:173], v[214:217], v[92:95]
	v_mfma_f32_16x16x32_bf16 v[72:75], v[152:155], v[222:225], v[72:75]
	v_mfma_f32_16x16x32_bf16 v[76:79], v[170:173], v[222:225], v[76:79]
	v_mfma_f32_16x16x32_bf16 v[120:123], v[166:169], v[202:205], v[120:123]
	v_mfma_f32_16x16x32_bf16 v[124:127], v[174:177], v[202:205], v[124:127]
	v_mfma_f32_16x16x32_bf16 v[104:107], v[166:169], v[210:213], v[104:107]
	v_mfma_f32_16x16x32_bf16 v[108:111], v[174:177], v[210:213], v[108:111]
	v_mfma_f32_16x16x32_bf16 v[88:91], v[166:169], v[218:221], v[88:91]
	v_mfma_f32_16x16x32_bf16 v[92:95], v[174:177], v[218:221], v[92:95]
	v_mfma_f32_16x16x32_bf16 v[72:75], v[166:169], v[226:229], v[72:75]
	v_mfma_f32_16x16x32_bf16 v[76:79], v[174:177], v[226:229], v[76:79]
	v_mfma_f32_16x16x32_bf16 v[116:119], v[178:181], v[198:201], v[116:119]
	v_mfma_f32_16x16x32_bf16 v[112:115], v[190:193], v[198:201], v[112:115]
	v_mfma_f32_16x16x32_bf16 v[100:103], v[178:181], v[206:209], v[100:103]
	v_mfma_f32_16x16x32_bf16 v[96:99], v[190:193], v[206:209], v[96:99]
	v_mfma_f32_16x16x32_bf16 v[84:87], v[178:181], v[214:217], v[84:87]
	v_mfma_f32_16x16x32_bf16 v[80:83], v[190:193], v[214:217], v[80:83]
	v_mfma_f32_16x16x32_bf16 v[68:71], v[178:181], v[222:225], v[68:71]
	v_mfma_f32_16x16x32_bf16 v[64:67], v[190:193], v[222:225], v[64:67]
	v_mfma_f32_16x16x32_bf16 v[116:119], v[186:189], v[202:205], v[116:119]
	v_mfma_f32_16x16x32_bf16 v[112:115], v[194:197], v[202:205], v[112:115]
	v_mfma_f32_16x16x32_bf16 v[100:103], v[186:189], v[210:213], v[100:103]
	v_mfma_f32_16x16x32_bf16 v[96:99], v[194:197], v[210:213], v[96:99]
	v_mfma_f32_16x16x32_bf16 v[84:87], v[186:189], v[218:221], v[84:87]
	v_mfma_f32_16x16x32_bf16 v[80:83], v[194:197], v[218:221], v[80:83]
	v_mfma_f32_16x16x32_bf16 v[68:71], v[186:189], v[226:229], v[68:71]
	v_mfma_f32_16x16x32_bf16 v[64:67], v[194:197], v[226:229], v[64:67]
	s_barrier
	s_add_i32 s54, 16, 0x18000
	v_add_u32_e32 v136, s54, v159
	s_add_i32 s55, 16, 0x1c000
	ds_read_b128 v[152:155], v136
	ds_read_b128 v[166:169], v136 offset:1024
	ds_read_b128 v[170:173], v136 offset:2048
	ds_read_b128 v[174:177], v136 offset:3072
	v_add_u32_e32 v136, s55, v159
	ds_read_b128 v[178:181], v136
	ds_read_b128 v[186:189], v136 offset:1024
	ds_read_b128 v[190:193], v136 offset:2048
	ds_read_b128 v[194:197], v136 offset:3072
	s_add_u32 s24, s24, 0x80000
	s_addc_u32 s25, s25, 0
	s_mov_b32 m0, s33
	v_lshl_add_u64 v[236:237], s[24:25], 0, v[128:129]
	ds_read_b128 v[198:201], v162 offset:32768
	ds_read_b128 v[202:205], v162 offset:33792
	ds_read_b128 v[206:209], v162 offset:34816
	ds_read_b128 v[210:213], v162 offset:35840
	ds_read_b128 v[214:217], v162 offset:36864
	ds_read_b128 v[218:221], v162 offset:37888
	ds_read_b128 v[222:225], v162 offset:38912
	ds_read_b128 v[226:229], v162 offset:39936
	global_load_lds_dwordx4 v[236:237], off
	v_lshl_add_u64 v[236:237], s[24:25], 0, v[132:133]
	s_mov_b32 m0, s52
	s_nop 0
	global_load_lds_dwordx4 v[236:237], off
	s_waitcnt vmcnt(8)
	s_waitcnt lgkmcnt(0)
	s_barrier
	s_waitcnt lgkmcnt(0)
	v_mfma_f32_16x16x32_bf16 v[60:63], v[152:155], v[198:201], v[60:63]
	v_mfma_f32_16x16x32_bf16 v[56:59], v[170:173], v[198:201], v[56:59]
	v_mfma_f32_16x16x32_bf16 v[52:55], v[152:155], v[206:209], v[52:55]
	v_mfma_f32_16x16x32_bf16 v[48:51], v[170:173], v[206:209], v[48:51]
	v_mfma_f32_16x16x32_bf16 v[44:47], v[152:155], v[214:217], v[44:47]
	v_mfma_f32_16x16x32_bf16 v[40:43], v[170:173], v[214:217], v[40:43]
	v_mfma_f32_16x16x32_bf16 v[28:31], v[152:155], v[222:225], v[28:31]
	v_mfma_f32_16x16x32_bf16 v[24:27], v[170:173], v[222:225], v[24:27]
	v_mfma_f32_16x16x32_bf16 v[60:63], v[166:169], v[202:205], v[60:63]
	v_mfma_f32_16x16x32_bf16 v[56:59], v[174:177], v[202:205], v[56:59]
	v_mfma_f32_16x16x32_bf16 v[52:55], v[166:169], v[210:213], v[52:55]
	v_mfma_f32_16x16x32_bf16 v[48:51], v[174:177], v[210:213], v[48:51]
	v_mfma_f32_16x16x32_bf16 v[44:47], v[166:169], v[218:221], v[44:47]
	v_mfma_f32_16x16x32_bf16 v[40:43], v[174:177], v[218:221], v[40:43]
	v_mfma_f32_16x16x32_bf16 v[28:31], v[166:169], v[226:229], v[28:31]
	v_mfma_f32_16x16x32_bf16 v[24:27], v[174:177], v[226:229], v[24:27]
	v_mfma_f32_16x16x32_bf16 v[36:39], v[178:181], v[198:201], v[36:39]
	v_mfma_f32_16x16x32_bf16 v[32:35], v[190:193], v[198:201], v[32:35]
	v_mfma_f32_16x16x32_bf16 v[20:23], v[178:181], v[206:209], v[20:23]
	v_mfma_f32_16x16x32_bf16 v[16:19], v[190:193], v[206:209], v[16:19]
	v_mfma_f32_16x16x32_bf16 v[12:15], v[178:181], v[214:217], v[12:15]
	v_mfma_f32_16x16x32_bf16 v[8:11], v[190:193], v[214:217], v[8:11]
	v_mfma_f32_16x16x32_bf16 v[4:7], v[178:181], v[222:225], v[4:7]
	v_mfma_f32_16x16x32_bf16 v[0:3], v[190:193], v[222:225], v[0:3]
	v_mfma_f32_16x16x32_bf16 v[36:39], v[186:189], v[202:205], v[36:39]
	v_mfma_f32_16x16x32_bf16 v[32:35], v[194:197], v[202:205], v[32:35]
	v_mfma_f32_16x16x32_bf16 v[20:23], v[186:189], v[210:213], v[20:23]
	v_mfma_f32_16x16x32_bf16 v[16:19], v[194:197], v[210:213], v[16:19]
	v_mfma_f32_16x16x32_bf16 v[12:15], v[186:189], v[218:221], v[12:15]
	v_mfma_f32_16x16x32_bf16 v[8:11], v[194:197], v[218:221], v[8:11]
	v_mfma_f32_16x16x32_bf16 v[4:7], v[186:189], v[226:229], v[4:7]
	v_mfma_f32_16x16x32_bf16 v[0:3], v[194:197], v[226:229], v[0:3]
	s_barrier
	s_add_i32 s24, s54, s29
	v_lshl_add_u64 v[156:157], v[156:157], 0, s[72:73]
	s_mov_b32 m0, s24
	ds_read_b128 v[198:201], v162 offset:49152
	ds_read_b128 v[202:205], v162 offset:50176
	ds_read_b128 v[206:209], v162 offset:51200
	ds_read_b128 v[210:213], v162 offset:52224
	ds_read_b128 v[214:217], v162 offset:53248
	ds_read_b128 v[218:221], v162 offset:54272
	ds_read_b128 v[222:225], v162 offset:55296
	ds_read_b128 v[226:229], v162 offset:56320
	global_load_lds_dwordx4 v[156:157], off
	s_add_i32 m0, s24, 0x2000
	s_add_u32 s14, s14, 0x80080
	v_lshl_add_u64 v[156:157], v[230:231], 0, s[72:73]
	s_addc_u32 s15, s15, 0
	s_add_i32 s24, s55, s29
	global_load_lds_dwordx4 v[156:157], off
	v_lshl_add_u64 v[156:157], s[14:15], 0, v[130:131]
	s_mov_b32 m0, s24
	s_nop 0
	global_load_lds_dwordx4 v[156:157], off
	v_lshl_add_u64 v[156:157], s[14:15], 0, v[134:135]
	s_add_i32 m0, s24, 0x2000
	s_nop 0
	global_load_lds_dwordx4 v[156:157], off
	v_lshl_add_u64 v[156:157], v[232:233], 0, s[72:73]
	s_mov_b32 m0, s58
	s_nop 0
	global_load_lds_dwordx4 v[156:157], off
	v_lshl_add_u64 v[156:157], v[234:235], 0, s[72:73]
	s_mov_b32 m0, s59
	s_nop 0
	global_load_lds_dwordx4 v[156:157], off
	s_waitcnt vmcnt(8)
	s_waitcnt lgkmcnt(0)
	s_barrier
	s_waitcnt lgkmcnt(0)
	v_mfma_f32_16x16x32_bf16 v[120:123], v[152:155], v[198:201], v[120:123]
	v_mfma_f32_16x16x32_bf16 v[124:127], v[170:173], v[198:201], v[124:127]
	v_mfma_f32_16x16x32_bf16 v[104:107], v[152:155], v[206:209], v[104:107]
	v_mfma_f32_16x16x32_bf16 v[108:111], v[170:173], v[206:209], v[108:111]
	v_mfma_f32_16x16x32_bf16 v[88:91], v[152:155], v[214:217], v[88:91]
	v_mfma_f32_16x16x32_bf16 v[92:95], v[170:173], v[214:217], v[92:95]
	v_mfma_f32_16x16x32_bf16 v[72:75], v[152:155], v[222:225], v[72:75]
	v_mfma_f32_16x16x32_bf16 v[76:79], v[170:173], v[222:225], v[76:79]
	v_mfma_f32_16x16x32_bf16 v[120:123], v[166:169], v[202:205], v[120:123]
	v_mfma_f32_16x16x32_bf16 v[124:127], v[174:177], v[202:205], v[124:127]
	v_mfma_f32_16x16x32_bf16 v[104:107], v[166:169], v[210:213], v[104:107]
	v_mfma_f32_16x16x32_bf16 v[108:111], v[174:177], v[210:213], v[108:111]
	v_mfma_f32_16x16x32_bf16 v[88:91], v[166:169], v[218:221], v[88:91]
	v_mfma_f32_16x16x32_bf16 v[92:95], v[174:177], v[218:221], v[92:95]
	v_mfma_f32_16x16x32_bf16 v[72:75], v[166:169], v[226:229], v[72:75]
	v_mfma_f32_16x16x32_bf16 v[76:79], v[174:177], v[226:229], v[76:79]
	v_mfma_f32_16x16x32_bf16 v[116:119], v[178:181], v[198:201], v[116:119]
	v_mfma_f32_16x16x32_bf16 v[112:115], v[190:193], v[198:201], v[112:115]
	v_mfma_f32_16x16x32_bf16 v[100:103], v[178:181], v[206:209], v[100:103]
	v_mfma_f32_16x16x32_bf16 v[96:99], v[190:193], v[206:209], v[96:99]
	v_mfma_f32_16x16x32_bf16 v[84:87], v[178:181], v[214:217], v[84:87]
	v_mfma_f32_16x16x32_bf16 v[80:83], v[190:193], v[214:217], v[80:83]
	v_mfma_f32_16x16x32_bf16 v[68:71], v[178:181], v[222:225], v[68:71]
	v_mfma_f32_16x16x32_bf16 v[64:67], v[190:193], v[222:225], v[64:67]
	v_mfma_f32_16x16x32_bf16 v[116:119], v[186:189], v[202:205], v[116:119]
	v_mfma_f32_16x16x32_bf16 v[112:115], v[194:197], v[202:205], v[112:115]
	v_mfma_f32_16x16x32_bf16 v[100:103], v[186:189], v[210:213], v[100:103]
	v_mfma_f32_16x16x32_bf16 v[96:99], v[194:197], v[210:213], v[96:99]
	v_mfma_f32_16x16x32_bf16 v[84:87], v[186:189], v[218:221], v[84:87]
	v_mfma_f32_16x16x32_bf16 v[80:83], v[194:197], v[218:221], v[80:83]
	v_mfma_f32_16x16x32_bf16 v[68:71], v[186:189], v[226:229], v[68:71]
	v_mfma_f32_16x16x32_bf16 v[64:67], v[194:197], v[226:229], v[64:67]
	s_barrier
	s_add_u32 vcc_hi, vcc_hi, 0x100
	s_addc_u32 s53, s53, 0
	s_add_u32 s92, s92, 0x100
	s_addc_u32 s93, s93, 0
	s_cmp_ge_u32 s94, s97
	s_mov_b32 s14, s94
	s_cbranch_scc0 .LBB0_778
	s_and_b64 vcc, exec, s[76:77]
	s_cbranch_vccz .LBB0_781
	s_barrier

.LBB0_910:
	v_add_u32_e32 v155, s62, v149
	ds_read_b128 v[164:167], v155
	ds_read_b128 v[168:171], v155 offset:1024
	ds_read_b128 v[172:175], v155 offset:2048
	ds_read_b128 v[176:179], v155 offset:3072
	v_add_u32_e32 v155, s63, v149
	ds_read_b128 v[186:189], v155
	ds_read_b128 v[190:193], v155 offset:1024
	ds_read_b128 v[194:197], v155 offset:2048
	ds_read_b128 v[198:201], v155 offset:3072
	s_add_u32 s24, s78, 0xfff80080
	s_addc_u32 s25, s79, -1
	s_and_b64 s[14:15], s[14:15], exec
	s_cselect_b32 s25, s26, s25
	s_cselect_b32 s24, s27, s24
	s_cselect_b32 s15, s17, s67
	s_cselect_b32 s14, s35, s66
	v_lshl_add_u64 v[180:181], s[78:79], 0, v[138:139]
	s_add_i32 m0, s53, 0xc000
	ds_read_b128 v[202:205], v153
	ds_read_b128 v[206:209], v153 offset:1024
	ds_read_b128 v[210:213], v153 offset:2048
	ds_read_b128 v[214:217], v153 offset:3072
	ds_read_b128 v[218:221], v153 offset:4096
	ds_read_b128 v[222:225], v153 offset:5120
	ds_read_b128 v[226:229], v153 offset:6144
	ds_read_b128 v[230:233], v153 offset:7168
	global_load_lds_dwordx4 v[180:181], off
	v_lshl_add_u64 v[180:181], s[78:79], 0, v[136:137]
	s_add_i32 m0, s53, 0xe000
	s_nop 0
	global_load_lds_dwordx4 v[180:181], off
	s_waitcnt vmcnt(8)
	s_waitcnt lgkmcnt(0)
	s_barrier
	s_waitcnt lgkmcnt(0)
	v_mfma_f32_16x16x32_bf16 v[124:127], v[164:167], v[202:205], v[124:127]
	v_mfma_f32_16x16x32_bf16 v[120:123], v[172:175], v[202:205], v[120:123]
	v_mfma_f32_16x16x32_bf16 v[116:119], v[164:167], v[210:213], v[116:119]
	v_mfma_f32_16x16x32_bf16 v[112:115], v[172:175], v[210:213], v[112:115]
	v_mfma_f32_16x16x32_bf16 v[100:103], v[164:167], v[218:221], v[100:103]
	v_mfma_f32_16x16x32_bf16 v[96:99], v[172:175], v[218:221], v[96:99]
	v_mfma_f32_16x16x32_bf16 v[84:87], v[164:167], v[226:229], v[84:87]
	v_mfma_f32_16x16x32_bf16 v[80:83], v[172:175], v[226:229], v[80:83]
	v_mfma_f32_16x16x32_bf16 v[124:127], v[168:171], v[206:209], v[124:127]
	v_mfma_f32_16x16x32_bf16 v[120:123], v[176:179], v[206:209], v[120:123]
	v_mfma_f32_16x16x32_bf16 v[116:119], v[168:171], v[214:217], v[116:119]
	v_mfma_f32_16x16x32_bf16 v[112:115], v[176:179], v[214:217], v[112:115]
	v_mfma_f32_16x16x32_bf16 v[100:103], v[168:171], v[222:225], v[100:103]
	v_mfma_f32_16x16x32_bf16 v[96:99], v[176:179], v[222:225], v[96:99]
	v_mfma_f32_16x16x32_bf16 v[84:87], v[168:171], v[230:233], v[84:87]
	v_mfma_f32_16x16x32_bf16 v[80:83], v[176:179], v[230:233], v[80:83]
	v_mfma_f32_16x16x32_bf16 v[108:111], v[186:189], v[202:205], v[108:111]
	v_mfma_f32_16x16x32_bf16 v[104:107], v[194:197], v[202:205], v[104:107]
	v_mfma_f32_16x16x32_bf16 v[92:95], v[186:189], v[210:213], v[92:95]
	v_mfma_f32_16x16x32_bf16 v[88:91], v[194:197], v[210:213], v[88:91]
	v_mfma_f32_16x16x32_bf16 v[76:79], v[186:189], v[218:221], v[76:79]
	v_mfma_f32_16x16x32_bf16 v[72:75], v[194:197], v[218:221], v[72:75]
	v_mfma_f32_16x16x32_bf16 v[68:71], v[186:189], v[226:229], v[68:71]
	v_mfma_f32_16x16x32_bf16 v[64:67], v[194:197], v[226:229], v[64:67]
	v_mfma_f32_16x16x32_bf16 v[108:111], v[190:193], v[206:209], v[108:111]
	v_mfma_f32_16x16x32_bf16 v[104:107], v[198:201], v[206:209], v[104:107]
	v_mfma_f32_16x16x32_bf16 v[92:95], v[190:193], v[214:217], v[92:95]
	v_mfma_f32_16x16x32_bf16 v[88:91], v[198:201], v[214:217], v[88:91]
	v_mfma_f32_16x16x32_bf16 v[76:79], v[190:193], v[222:225], v[76:79]
	v_mfma_f32_16x16x32_bf16 v[72:75], v[198:201], v[222:225], v[72:75]
	v_mfma_f32_16x16x32_bf16 v[68:71], v[190:193], v[230:233], v[68:71]
	v_mfma_f32_16x16x32_bf16 v[64:67], v[198:201], v[230:233], v[64:67]
	s_barrier
	s_add_i32 s75, s62, s52
	v_lshl_add_u64 v[180:181], s[14:15], 0, v[130:131]
	s_mov_b32 m0, s75
	ds_read_b128 v[202:205], v153 offset:16384
	ds_read_b128 v[206:209], v153 offset:17408
	ds_read_b128 v[210:213], v153 offset:18432
	ds_read_b128 v[214:217], v153 offset:19456
	ds_read_b128 v[218:221], v153 offset:20480
	ds_read_b128 v[222:225], v153 offset:21504
	ds_read_b128 v[226:229], v153 offset:22528
	ds_read_b128 v[230:233], v153 offset:23552
	global_load_lds_dwordx4 v[180:181], off
	s_add_i32 m0, s75, 0x2000
	s_add_u32 s80, s14, 0x80000
	v_lshl_add_u64 v[234:235], s[14:15], 0, v[134:135]
	s_addc_u32 s81, s15, 0
	s_add_i32 s75, s63, s52
	global_load_lds_dwordx4 v[234:235], off
	v_lshl_add_u64 v[236:237], s[80:81], 0, v[130:131]
	s_mov_b32 m0, s75
	v_lshl_add_u64 v[238:239], s[24:25], 0, v[132:133]
	global_load_lds_dwordx4 v[236:237], off
	v_lshl_add_u64 v[236:237], s[80:81], 0, v[134:135]
	s_add_i32 m0, s75, 0x2000
	s_nop 0
	global_load_lds_dwordx4 v[236:237], off
	v_lshl_add_u64 v[236:237], s[24:25], 0, v[128:129]
	s_mov_b32 m0, s53
	s_nop 0
	global_load_lds_dwordx4 v[236:237], off
	s_mov_b32 m0, s54
	s_nop 0
	global_load_lds_dwordx4 v[238:239], off
	s_waitcnt vmcnt(8)
	s_waitcnt lgkmcnt(0)
	s_barrier
	s_waitcnt lgkmcnt(0)
	v_mfma_f32_16x16x32_bf16 v[60:63], v[164:167], v[202:205], v[60:63]
	v_mfma_f32_16x16x32_bf16 v[56:59], v[172:175], v[202:205], v[56:59]
	v_mfma_f32_16x16x32_bf16 v[52:55], v[164:167], v[210:213], v[52:55]
	v_mfma_f32_16x16x32_bf16 v[48:51], v[172:175], v[210:213], v[48:51]
	v_mfma_f32_16x16x32_bf16 v[36:39], v[164:167], v[218:221], v[36:39]
	v_mfma_f32_16x16x32_bf16 v[32:35], v[172:175], v[218:221], v[32:35]
	v_mfma_f32_16x16x32_bf16 v[20:23], v[164:167], v[226:229], v[20:23]
	v_mfma_f32_16x16x32_bf16 v[16:19], v[172:175], v[226:229], v[16:19]
	v_mfma_f32_16x16x32_bf16 v[60:63], v[168:171], v[206:209], v[60:63]
	v_mfma_f32_16x16x32_bf16 v[56:59], v[176:179], v[206:209], v[56:59]
	v_mfma_f32_16x16x32_bf16 v[52:55], v[168:171], v[214:217], v[52:55]
	v_mfma_f32_16x16x32_bf16 v[48:51], v[176:179], v[214:217], v[48:51]
	v_mfma_f32_16x16x32_bf16 v[36:39], v[168:171], v[222:225], v[36:39]
	v_mfma_f32_16x16x32_bf16 v[32:35], v[176:179], v[222:225], v[32:35]
	v_mfma_f32_16x16x32_bf16 v[20:23], v[168:171], v[230:233], v[20:23]
	v_mfma_f32_16x16x32_bf16 v[16:19], v[176:179], v[230:233], v[16:19]
	v_mfma_f32_16x16x32_bf16 v[44:47], v[186:189], v[202:205], v[44:47]
	v_mfma_f32_16x16x32_bf16 v[40:43], v[194:197], v[202:205], v[40:43]
	v_mfma_f32_16x16x32_bf16 v[28:31], v[186:189], v[210:213], v[28:31]
	v_mfma_f32_16x16x32_bf16 v[24:27], v[194:197], v[210:213], v[24:27]
	v_mfma_f32_16x16x32_bf16 v[12:15], v[186:189], v[218:221], v[12:15]
	v_mfma_f32_16x16x32_bf16 v[8:11], v[194:197], v[218:221], v[8:11]
	v_mfma_f32_16x16x32_bf16 v[4:7], v[186:189], v[226:229], v[4:7]
	v_mfma_f32_16x16x32_bf16 v[0:3], v[194:197], v[226:229], v[0:3]
	v_mfma_f32_16x16x32_bf16 v[44:47], v[190:193], v[206:209], v[44:47]
	v_mfma_f32_16x16x32_bf16 v[40:43], v[198:201], v[206:209], v[40:43]
	v_mfma_f32_16x16x32_bf16 v[28:31], v[190:193], v[214:217], v[28:31]
	v_mfma_f32_16x16x32_bf16 v[24:27], v[198:201], v[214:217], v[24:27]
	v_mfma_f32_16x16x32_bf16 v[12:15], v[190:193], v[222:225], v[12:15]
	v_mfma_f32_16x16x32_bf16 v[8:11], v[198:201], v[222:225], v[8:11]
	v_mfma_f32_16x16x32_bf16 v[4:7], v[190:193], v[230:233], v[4:7]
	v_mfma_f32_16x16x32_bf16 v[0:3], v[198:201], v[230:233], v[0:3]
	s_barrier
	s_add_i32 s75, 16, 0x18000
	v_add_u32_e32 v155, s75, v149
	s_add_i32 s80, 16, 0x1c000
	ds_read_b128 v[164:167], v155
	ds_read_b128 v[168:171], v155 offset:1024
	ds_read_b128 v[172:175], v155 offset:2048
	ds_read_b128 v[176:179], v155 offset:3072
	v_add_u32_e32 v155, s80, v149
	ds_read_b128 v[186:189], v155
	ds_read_b128 v[190:193], v155 offset:1024
	ds_read_b128 v[194:197], v155 offset:2048
	ds_read_b128 v[198:201], v155 offset:3072
	s_add_u32 s24, s24, 0x80000
	s_addc_u32 s25, s25, 0
	s_mov_b32 m0, s55
	v_lshl_add_u64 v[240:241], s[24:25], 0, v[128:129]
	ds_read_b128 v[202:205], v153 offset:32768
	ds_read_b128 v[206:209], v153 offset:33792
	ds_read_b128 v[210:213], v153 offset:34816
	ds_read_b128 v[214:217], v153 offset:35840
	ds_read_b128 v[218:221], v153 offset:36864
	ds_read_b128 v[222:225], v153 offset:37888
	ds_read_b128 v[226:229], v153 offset:38912
	ds_read_b128 v[230:233], v153 offset:39936
	global_load_lds_dwordx4 v[240:241], off
	v_lshl_add_u64 v[240:241], s[24:25], 0, v[132:133]
	s_mov_b32 m0, s56
	s_nop 0
	global_load_lds_dwordx4 v[240:241], off
	s_waitcnt vmcnt(8)
	s_waitcnt lgkmcnt(0)
	s_barrier
	s_waitcnt lgkmcnt(0)
	v_mfma_f32_16x16x32_bf16 v[124:127], v[164:167], v[202:205], v[124:127]
	v_mfma_f32_16x16x32_bf16 v[120:123], v[172:175], v[202:205], v[120:123]
	v_mfma_f32_16x16x32_bf16 v[116:119], v[164:167], v[210:213], v[116:119]
	v_mfma_f32_16x16x32_bf16 v[112:115], v[172:175], v[210:213], v[112:115]
	v_mfma_f32_16x16x32_bf16 v[100:103], v[164:167], v[218:221], v[100:103]
	v_mfma_f32_16x16x32_bf16 v[96:99], v[172:175], v[218:221], v[96:99]
	v_mfma_f32_16x16x32_bf16 v[84:87], v[164:167], v[226:229], v[84:87]
	v_mfma_f32_16x16x32_bf16 v[80:83], v[172:175], v[226:229], v[80:83]
	v_mfma_f32_16x16x32_bf16 v[124:127], v[168:171], v[206:209], v[124:127]
	v_mfma_f32_16x16x32_bf16 v[120:123], v[176:179], v[206:209], v[120:123]
	v_mfma_f32_16x16x32_bf16 v[116:119], v[168:171], v[214:217], v[116:119]
	v_mfma_f32_16x16x32_bf16 v[112:115], v[176:179], v[214:217], v[112:115]
	v_mfma_f32_16x16x32_bf16 v[100:103], v[168:171], v[222:225], v[100:103]
	v_mfma_f32_16x16x32_bf16 v[96:99], v[176:179], v[222:225], v[96:99]
	v_mfma_f32_16x16x32_bf16 v[84:87], v[168:171], v[230:233], v[84:87]
	v_mfma_f32_16x16x32_bf16 v[80:83], v[176:179], v[230:233], v[80:83]
	v_mfma_f32_16x16x32_bf16 v[108:111], v[186:189], v[202:205], v[108:111]
	v_mfma_f32_16x16x32_bf16 v[104:107], v[194:197], v[202:205], v[104:107]
	v_mfma_f32_16x16x32_bf16 v[92:95], v[186:189], v[210:213], v[92:95]
	v_mfma_f32_16x16x32_bf16 v[88:91], v[194:197], v[210:213], v[88:91]
	v_mfma_f32_16x16x32_bf16 v[76:79], v[186:189], v[218:221], v[76:79]
	v_mfma_f32_16x16x32_bf16 v[72:75], v[194:197], v[218:221], v[72:75]
	v_mfma_f32_16x16x32_bf16 v[68:71], v[186:189], v[226:229], v[68:71]
	v_mfma_f32_16x16x32_bf16 v[64:67], v[194:197], v[226:229], v[64:67]
	v_mfma_f32_16x16x32_bf16 v[108:111], v[190:193], v[206:209], v[108:111]
	v_mfma_f32_16x16x32_bf16 v[104:107], v[198:201], v[206:209], v[104:107]
	v_mfma_f32_16x16x32_bf16 v[92:95], v[190:193], v[214:217], v[92:95]
	v_mfma_f32_16x16x32_bf16 v[88:91], v[198:201], v[214:217], v[88:91]
	v_mfma_f32_16x16x32_bf16 v[76:79], v[190:193], v[222:225], v[76:79]
	v_mfma_f32_16x16x32_bf16 v[72:75], v[198:201], v[222:225], v[72:75]
	v_mfma_f32_16x16x32_bf16 v[68:71], v[190:193], v[230:233], v[68:71]
	v_mfma_f32_16x16x32_bf16 v[64:67], v[198:201], v[230:233], v[64:67]
	s_barrier
	s_add_i32 s24, s75, s52
	v_lshl_add_u64 v[180:181], v[180:181], 0, s[10:11]
	s_mov_b32 m0, s24
	ds_read_b128 v[202:205], v153 offset:49152
	ds_read_b128 v[206:209], v153 offset:50176
	ds_read_b128 v[210:213], v153 offset:51200
	ds_read_b128 v[214:217], v153 offset:52224
	ds_read_b128 v[218:221], v153 offset:53248
	ds_read_b128 v[222:225], v153 offset:54272
	ds_read_b128 v[226:229], v153 offset:55296
	ds_read_b128 v[230:233], v153 offset:56320
	global_load_lds_dwordx4 v[180:181], off
	s_add_i32 m0, s24, 0x2000
	s_add_u32 s14, s14, 0x80080
	v_lshl_add_u64 v[180:181], v[234:235], 0, s[10:11]
	s_addc_u32 s15, s15, 0
	s_add_i32 s24, s80, s52
	global_load_lds_dwordx4 v[180:181], off
	v_lshl_add_u64 v[180:181], s[14:15], 0, v[130:131]
	s_mov_b32 m0, s24
	s_nop 0
	global_load_lds_dwordx4 v[180:181], off
	v_lshl_add_u64 v[180:181], s[14:15], 0, v[134:135]
	s_add_i32 m0, s24, 0x2000
	s_nop 0
	global_load_lds_dwordx4 v[180:181], off
	v_lshl_add_u64 v[180:181], v[236:237], 0, s[10:11]
	s_mov_b32 m0, s58
	s_nop 0
	global_load_lds_dwordx4 v[180:181], off
	v_lshl_add_u64 v[180:181], v[238:239], 0, s[10:11]
	s_mov_b32 m0, s59
	s_nop 0
	global_load_lds_dwordx4 v[180:181], off
	s_waitcnt vmcnt(8)
	s_waitcnt lgkmcnt(0)
	s_barrier
	s_waitcnt lgkmcnt(0)
	v_mfma_f32_16x16x32_bf16 v[60:63], v[164:167], v[202:205], v[60:63]
	v_mfma_f32_16x16x32_bf16 v[56:59], v[172:175], v[202:205], v[56:59]
	v_mfma_f32_16x16x32_bf16 v[52:55], v[164:167], v[210:213], v[52:55]
	v_mfma_f32_16x16x32_bf16 v[48:51], v[172:175], v[210:213], v[48:51]
	v_mfma_f32_16x16x32_bf16 v[36:39], v[164:167], v[218:221], v[36:39]
	v_mfma_f32_16x16x32_bf16 v[32:35], v[172:175], v[218:221], v[32:35]
	v_mfma_f32_16x16x32_bf16 v[20:23], v[164:167], v[226:229], v[20:23]
	v_mfma_f32_16x16x32_bf16 v[16:19], v[172:175], v[226:229], v[16:19]
	v_mfma_f32_16x16x32_bf16 v[60:63], v[168:171], v[206:209], v[60:63]
	v_mfma_f32_16x16x32_bf16 v[56:59], v[176:179], v[206:209], v[56:59]
	v_mfma_f32_16x16x32_bf16 v[52:55], v[168:171], v[214:217], v[52:55]
	v_mfma_f32_16x16x32_bf16 v[48:51], v[176:179], v[214:217], v[48:51]
	v_mfma_f32_16x16x32_bf16 v[36:39], v[168:171], v[222:225], v[36:39]
	v_mfma_f32_16x16x32_bf16 v[32:35], v[176:179], v[222:225], v[32:35]
	v_mfma_f32_16x16x32_bf16 v[20:23], v[168:171], v[230:233], v[20:23]
	v_mfma_f32_16x16x32_bf16 v[16:19], v[176:179], v[230:233], v[16:19]
	v_mfma_f32_16x16x32_bf16 v[44:47], v[186:189], v[202:205], v[44:47]
	v_mfma_f32_16x16x32_bf16 v[40:43], v[194:197], v[202:205], v[40:43]
	v_mfma_f32_16x16x32_bf16 v[28:31], v[186:189], v[210:213], v[28:31]
	v_mfma_f32_16x16x32_bf16 v[24:27], v[194:197], v[210:213], v[24:27]
	v_mfma_f32_16x16x32_bf16 v[12:15], v[186:189], v[218:221], v[12:15]
	v_mfma_f32_16x16x32_bf16 v[8:11], v[194:197], v[218:221], v[8:11]
	v_mfma_f32_16x16x32_bf16 v[4:7], v[186:189], v[226:229], v[4:7]
	v_mfma_f32_16x16x32_bf16 v[0:3], v[194:197], v[226:229], v[0:3]
	v_mfma_f32_16x16x32_bf16 v[44:47], v[190:193], v[206:209], v[44:47]
	v_mfma_f32_16x16x32_bf16 v[40:43], v[198:201], v[206:209], v[40:43]
	v_mfma_f32_16x16x32_bf16 v[28:31], v[190:193], v[214:217], v[28:31]
	v_mfma_f32_16x16x32_bf16 v[24:27], v[198:201], v[214:217], v[24:27]
	v_mfma_f32_16x16x32_bf16 v[12:15], v[190:193], v[222:225], v[12:15]
	v_mfma_f32_16x16x32_bf16 v[8:11], v[198:201], v[222:225], v[8:11]
	v_mfma_f32_16x16x32_bf16 v[4:7], v[190:193], v[230:233], v[4:7]
	v_mfma_f32_16x16x32_bf16 v[0:3], v[198:201], v[230:233], v[0:3]
	s_barrier
	s_add_i32 s74, s74, 2
	s_add_u32 s66, s66, 0x100
	s_addc_u32 s67, s67, 0
	s_add_u32 s78, s78, 0x100
	s_addc_u32 s79, s79, 0
	s_cmp_gt_u32 s74, 29
	s_cbranch_scc1 .LBB0_913

.LBB0_1042:
	ds_read_b128 v[152:155], v139
	ds_read_b128 v[166:169], v139 offset:1024
	ds_read_b128 v[170:173], v139 offset:2048
	ds_read_b128 v[174:177], v139 offset:3072
	ds_read_b128 v[178:181], v161
	ds_read_b128 v[186:189], v161 offset:1024
	ds_read_b128 v[190:193], v161 offset:2048
	ds_read_b128 v[194:197], v161 offset:3072
	s_add_i32 s67, s14, 2
	s_add_u32 s8, s0, 0x100
	s_addc_u32 s9, s1, 0
	s_cmp_eq_u32 s60, s14
	s_cselect_b32 s14, s72, s61
	s_cselect_b32 s77, s65, s9
	s_cselect_b32 s76, s64, s8
	s_cselect_b32 s15, s73, s66
	v_lshl_add_u64 v[156:157], s[0:1], 0, v[150:151]
	s_add_i32 m0, s54, 0xc000
	ds_read_b128 v[198:201], v162
	ds_read_b128 v[202:205], v162 offset:1024
	ds_read_b128 v[206:209], v162 offset:2048
	ds_read_b128 v[210:213], v162 offset:3072
	ds_read_b128 v[214:217], v162 offset:4096
	ds_read_b128 v[218:221], v162 offset:5120
	ds_read_b128 v[222:225], v162 offset:6144
	ds_read_b128 v[226:229], v162 offset:7168
	global_load_lds_dwordx4 v[156:157], off
	v_lshl_add_u64 v[156:157], s[0:1], 0, v[148:149]
	s_add_i32 m0, s54, 0xe000
	s_nop 0
	global_load_lds_dwordx4 v[156:157], off
	s_waitcnt vmcnt(8)
	s_waitcnt lgkmcnt(0)
	s_barrier
	s_waitcnt lgkmcnt(0)
	v_mfma_f32_16x16x32_bf16 v[60:63], v[152:155], v[198:201], v[60:63]
	v_mfma_f32_16x16x32_bf16 v[56:59], v[170:173], v[198:201], v[56:59]
	v_mfma_f32_16x16x32_bf16 v[52:55], v[152:155], v[206:209], v[52:55]
	v_mfma_f32_16x16x32_bf16 v[48:51], v[170:173], v[206:209], v[48:51]
	v_mfma_f32_16x16x32_bf16 v[44:47], v[152:155], v[214:217], v[44:47]
	v_mfma_f32_16x16x32_bf16 v[40:43], v[170:173], v[214:217], v[40:43]
	v_mfma_f32_16x16x32_bf16 v[28:31], v[152:155], v[222:225], v[28:31]
	v_mfma_f32_16x16x32_bf16 v[24:27], v[170:173], v[222:225], v[24:27]
	v_mfma_f32_16x16x32_bf16 v[60:63], v[166:169], v[202:205], v[60:63]
	v_mfma_f32_16x16x32_bf16 v[56:59], v[174:177], v[202:205], v[56:59]
	v_mfma_f32_16x16x32_bf16 v[52:55], v[166:169], v[210:213], v[52:55]
	v_mfma_f32_16x16x32_bf16 v[48:51], v[174:177], v[210:213], v[48:51]
	v_mfma_f32_16x16x32_bf16 v[44:47], v[166:169], v[218:221], v[44:47]
	v_mfma_f32_16x16x32_bf16 v[40:43], v[174:177], v[218:221], v[40:43]
	v_mfma_f32_16x16x32_bf16 v[28:31], v[166:169], v[226:229], v[28:31]
	v_mfma_f32_16x16x32_bf16 v[24:27], v[174:177], v[226:229], v[24:27]
	v_mfma_f32_16x16x32_bf16 v[36:39], v[178:181], v[198:201], v[36:39]
	v_mfma_f32_16x16x32_bf16 v[32:35], v[190:193], v[198:201], v[32:35]
	v_mfma_f32_16x16x32_bf16 v[20:23], v[178:181], v[206:209], v[20:23]
	v_mfma_f32_16x16x32_bf16 v[16:19], v[190:193], v[206:209], v[16:19]
	v_mfma_f32_16x16x32_bf16 v[12:15], v[178:181], v[214:217], v[12:15]
	v_mfma_f32_16x16x32_bf16 v[8:11], v[190:193], v[214:217], v[8:11]
	v_mfma_f32_16x16x32_bf16 v[4:7], v[178:181], v[222:225], v[4:7]
	v_mfma_f32_16x16x32_bf16 v[0:3], v[190:193], v[222:225], v[0:3]
	v_mfma_f32_16x16x32_bf16 v[36:39], v[186:189], v[202:205], v[36:39]
	v_mfma_f32_16x16x32_bf16 v[32:35], v[194:197], v[202:205], v[32:35]
	v_mfma_f32_16x16x32_bf16 v[20:23], v[186:189], v[210:213], v[20:23]
	v_mfma_f32_16x16x32_bf16 v[16:19], v[194:197], v[210:213], v[16:19]
	v_mfma_f32_16x16x32_bf16 v[12:15], v[186:189], v[218:221], v[12:15]
	v_mfma_f32_16x16x32_bf16 v[8:11], v[194:197], v[218:221], v[8:11]
	v_mfma_f32_16x16x32_bf16 v[4:7], v[186:189], v[226:229], v[4:7]
	v_mfma_f32_16x16x32_bf16 v[0:3], v[194:197], v[226:229], v[0:3]
	s_barrier
	s_add_i32 s0, s85, s53
	v_lshl_add_u64 v[156:157], s[14:15], 0, v[130:131]
	s_mov_b32 m0, s0
	ds_read_b128 v[198:201], v162 offset:16384
	ds_read_b128 v[202:205], v162 offset:17408
	ds_read_b128 v[206:209], v162 offset:18432
	ds_read_b128 v[210:213], v162 offset:19456
	ds_read_b128 v[214:217], v162 offset:20480
	ds_read_b128 v[218:221], v162 offset:21504
	ds_read_b128 v[222:225], v162 offset:22528
	ds_read_b128 v[226:229], v162 offset:23552
	global_load_lds_dwordx4 v[156:157], off
	s_add_i32 m0, s0, 0x2000
	s_add_u32 s0, s14, 0x160000
	v_lshl_add_u64 v[230:231], s[14:15], 0, v[134:135]
	s_addc_u32 s1, s15, 0
	s_add_i32 vcc_lo, s86, s53
	global_load_lds_dwordx4 v[230:231], off
	v_lshl_add_u64 v[232:233], s[0:1], 0, v[130:131]
	s_mov_b32 m0, vcc_lo
	v_lshl_add_u64 v[234:235], s[76:77], 0, v[132:133]
	global_load_lds_dwordx4 v[232:233], off
	v_lshl_add_u64 v[232:233], s[0:1], 0, v[134:135]
	s_add_i32 m0, vcc_lo, 0x2000
	s_nop 0
	global_load_lds_dwordx4 v[232:233], off
	v_lshl_add_u64 v[232:233], s[76:77], 0, v[128:129]
	s_mov_b32 m0, s54
	s_nop 0
	global_load_lds_dwordx4 v[232:233], off
	s_mov_b32 m0, s55
	s_nop 0
	global_load_lds_dwordx4 v[234:235], off
	s_waitcnt vmcnt(8)
	s_waitcnt lgkmcnt(0)
	s_barrier
	s_waitcnt lgkmcnt(0)
	v_mfma_f32_16x16x32_bf16 v[120:123], v[152:155], v[198:201], v[120:123]
	v_mfma_f32_16x16x32_bf16 v[124:127], v[170:173], v[198:201], v[124:127]
	v_mfma_f32_16x16x32_bf16 v[104:107], v[152:155], v[206:209], v[104:107]
	v_mfma_f32_16x16x32_bf16 v[108:111], v[170:173], v[206:209], v[108:111]
	v_mfma_f32_16x16x32_bf16 v[88:91], v[152:155], v[214:217], v[88:91]
	v_mfma_f32_16x16x32_bf16 v[92:95], v[170:173], v[214:217], v[92:95]
	v_mfma_f32_16x16x32_bf16 v[72:75], v[152:155], v[222:225], v[72:75]
	v_mfma_f32_16x16x32_bf16 v[76:79], v[170:173], v[222:225], v[76:79]
	v_mfma_f32_16x16x32_bf16 v[120:123], v[166:169], v[202:205], v[120:123]
	v_mfma_f32_16x16x32_bf16 v[124:127], v[174:177], v[202:205], v[124:127]
	v_mfma_f32_16x16x32_bf16 v[104:107], v[166:169], v[210:213], v[104:107]
	v_mfma_f32_16x16x32_bf16 v[108:111], v[174:177], v[210:213], v[108:111]
	v_mfma_f32_16x16x32_bf16 v[88:91], v[166:169], v[218:221], v[88:91]
	v_mfma_f32_16x16x32_bf16 v[92:95], v[174:177], v[218:221], v[92:95]
	v_mfma_f32_16x16x32_bf16 v[72:75], v[166:169], v[226:229], v[72:75]
	v_mfma_f32_16x16x32_bf16 v[76:79], v[174:177], v[226:229], v[76:79]
	v_mfma_f32_16x16x32_bf16 v[116:119], v[178:181], v[198:201], v[116:119]
	v_mfma_f32_16x16x32_bf16 v[112:115], v[190:193], v[198:201], v[112:115]
	v_mfma_f32_16x16x32_bf16 v[100:103], v[178:181], v[206:209], v[100:103]
	v_mfma_f32_16x16x32_bf16 v[96:99], v[190:193], v[206:209], v[96:99]
	v_mfma_f32_16x16x32_bf16 v[84:87], v[178:181], v[214:217], v[84:87]
	v_mfma_f32_16x16x32_bf16 v[80:83], v[190:193], v[214:217], v[80:83]
	v_mfma_f32_16x16x32_bf16 v[68:71], v[178:181], v[222:225], v[68:71]
	v_mfma_f32_16x16x32_bf16 v[64:67], v[190:193], v[222:225], v[64:67]
	v_mfma_f32_16x16x32_bf16 v[116:119], v[186:189], v[202:205], v[116:119]
	v_mfma_f32_16x16x32_bf16 v[112:115], v[194:197], v[202:205], v[112:115]
	v_mfma_f32_16x16x32_bf16 v[100:103], v[186:189], v[210:213], v[100:103]
	v_mfma_f32_16x16x32_bf16 v[96:99], v[194:197], v[210:213], v[96:99]
	v_mfma_f32_16x16x32_bf16 v[84:87], v[186:189], v[218:221], v[84:87]
	v_mfma_f32_16x16x32_bf16 v[80:83], v[194:197], v[218:221], v[80:83]
	v_mfma_f32_16x16x32_bf16 v[68:71], v[186:189], v[226:229], v[68:71]
	v_mfma_f32_16x16x32_bf16 v[64:67], v[194:197], v[226:229], v[64:67]
	s_barrier
	s_add_i32 vcc_lo, 16, 0x18000
	v_add_u32_e32 v136, vcc_lo, v159
	s_add_i32 vcc_hi, 16, 0x1c000
	ds_read_b128 v[152:155], v136
	ds_read_b128 v[166:169], v136 offset:1024
	ds_read_b128 v[170:173], v136 offset:2048
	ds_read_b128 v[174:177], v136 offset:3072
	v_add_u32_e32 v136, vcc_hi, v159
	ds_read_b128 v[178:181], v136
	ds_read_b128 v[186:189], v136 offset:1024
	ds_read_b128 v[190:193], v136 offset:2048
	ds_read_b128 v[194:197], v136 offset:3072
	s_add_u32 s0, s76, 0x160000
	s_addc_u32 s1, s77, 0
	s_mov_b32 m0, s74
	v_lshl_add_u64 v[236:237], s[0:1], 0, v[128:129]
	ds_read_b128 v[198:201], v162 offset:32768
	ds_read_b128 v[202:205], v162 offset:33792
	ds_read_b128 v[206:209], v162 offset:34816
	ds_read_b128 v[210:213], v162 offset:35840
	ds_read_b128 v[214:217], v162 offset:36864
	ds_read_b128 v[218:221], v162 offset:37888
	ds_read_b128 v[222:225], v162 offset:38912
	ds_read_b128 v[226:229], v162 offset:39936
	global_load_lds_dwordx4 v[236:237], off
	v_lshl_add_u64 v[236:237], s[0:1], 0, v[132:133]
	s_mov_b32 m0, s75
	s_nop 0
	global_load_lds_dwordx4 v[236:237], off
	s_waitcnt vmcnt(8)
	s_waitcnt lgkmcnt(0)
	s_barrier
	s_waitcnt lgkmcnt(0)
	v_mfma_f32_16x16x32_bf16 v[60:63], v[152:155], v[198:201], v[60:63]
	v_mfma_f32_16x16x32_bf16 v[56:59], v[170:173], v[198:201], v[56:59]
	v_mfma_f32_16x16x32_bf16 v[52:55], v[152:155], v[206:209], v[52:55]
	v_mfma_f32_16x16x32_bf16 v[48:51], v[170:173], v[206:209], v[48:51]
	v_mfma_f32_16x16x32_bf16 v[44:47], v[152:155], v[214:217], v[44:47]
	v_mfma_f32_16x16x32_bf16 v[40:43], v[170:173], v[214:217], v[40:43]
	v_mfma_f32_16x16x32_bf16 v[28:31], v[152:155], v[222:225], v[28:31]
	v_mfma_f32_16x16x32_bf16 v[24:27], v[170:173], v[222:225], v[24:27]
	v_mfma_f32_16x16x32_bf16 v[60:63], v[166:169], v[202:205], v[60:63]
	v_mfma_f32_16x16x32_bf16 v[56:59], v[174:177], v[202:205], v[56:59]
	v_mfma_f32_16x16x32_bf16 v[52:55], v[166:169], v[210:213], v[52:55]
	v_mfma_f32_16x16x32_bf16 v[48:51], v[174:177], v[210:213], v[48:51]
	v_mfma_f32_16x16x32_bf16 v[44:47], v[166:169], v[218:221], v[44:47]
	v_mfma_f32_16x16x32_bf16 v[40:43], v[174:177], v[218:221], v[40:43]
	v_mfma_f32_16x16x32_bf16 v[28:31], v[166:169], v[226:229], v[28:31]
	v_mfma_f32_16x16x32_bf16 v[24:27], v[174:177], v[226:229], v[24:27]
	v_mfma_f32_16x16x32_bf16 v[36:39], v[178:181], v[198:201], v[36:39]
	v_mfma_f32_16x16x32_bf16 v[32:35], v[190:193], v[198:201], v[32:35]
	v_mfma_f32_16x16x32_bf16 v[20:23], v[178:181], v[206:209], v[20:23]
	v_mfma_f32_16x16x32_bf16 v[16:19], v[190:193], v[206:209], v[16:19]
	v_mfma_f32_16x16x32_bf16 v[12:15], v[178:181], v[214:217], v[12:15]
	v_mfma_f32_16x16x32_bf16 v[8:11], v[190:193], v[214:217], v[8:11]
	v_mfma_f32_16x16x32_bf16 v[4:7], v[178:181], v[222:225], v[4:7]
	v_mfma_f32_16x16x32_bf16 v[0:3], v[190:193], v[222:225], v[0:3]
	v_mfma_f32_16x16x32_bf16 v[36:39], v[186:189], v[202:205], v[36:39]
	v_mfma_f32_16x16x32_bf16 v[32:35], v[194:197], v[202:205], v[32:35]
	v_mfma_f32_16x16x32_bf16 v[20:23], v[186:189], v[210:213], v[20:23]
	v_mfma_f32_16x16x32_bf16 v[16:19], v[194:197], v[210:213], v[16:19]
	v_mfma_f32_16x16x32_bf16 v[12:15], v[186:189], v[218:221], v[12:15]
	v_mfma_f32_16x16x32_bf16 v[8:11], v[194:197], v[218:221], v[8:11]
	v_mfma_f32_16x16x32_bf16 v[4:7], v[186:189], v[226:229], v[4:7]
	v_mfma_f32_16x16x32_bf16 v[0:3], v[194:197], v[226:229], v[0:3]
	s_barrier
	s_add_i32 s0, vcc_lo, s53
	v_lshl_add_u64 v[156:157], v[156:157], 0, s[30:31]
	s_mov_b32 m0, s0
	ds_read_b128 v[198:201], v162 offset:49152
	ds_read_b128 v[202:205], v162 offset:50176
	ds_read_b128 v[206:209], v162 offset:51200
	ds_read_b128 v[210:213], v162 offset:52224
	ds_read_b128 v[214:217], v162 offset:53248
	ds_read_b128 v[218:221], v162 offset:54272
	ds_read_b128 v[222:225], v162 offset:55296
	ds_read_b128 v[226:229], v162 offset:56320
	global_load_lds_dwordx4 v[156:157], off
	s_add_i32 m0, s0, 0x2000
	s_add_u32 s0, s14, 0x160080
	v_lshl_add_u64 v[156:157], v[230:231], 0, s[30:31]
	s_addc_u32 s1, s15, 0
	s_add_i32 s14, vcc_hi, s53
	global_load_lds_dwordx4 v[156:157], off
	v_lshl_add_u64 v[156:157], s[0:1], 0, v[130:131]
	s_mov_b32 m0, s14
	s_nop 0
	global_load_lds_dwordx4 v[156:157], off
	v_lshl_add_u64 v[156:157], s[0:1], 0, v[134:135]
	s_add_i32 m0, s14, 0x2000
	s_nop 0
	global_load_lds_dwordx4 v[156:157], off
	v_lshl_add_u64 v[156:157], v[232:233], 0, s[30:31]
	s_mov_b32 m0, s83
	s_nop 0
	global_load_lds_dwordx4 v[156:157], off
	v_lshl_add_u64 v[156:157], v[234:235], 0, s[30:31]
	s_mov_b32 m0, s84
	s_nop 0
	global_load_lds_dwordx4 v[156:157], off
	s_waitcnt vmcnt(8)
	s_waitcnt lgkmcnt(0)
	s_barrier
	s_waitcnt lgkmcnt(0)
	v_mfma_f32_16x16x32_bf16 v[120:123], v[152:155], v[198:201], v[120:123]
	v_mfma_f32_16x16x32_bf16 v[124:127], v[170:173], v[198:201], v[124:127]
	v_mfma_f32_16x16x32_bf16 v[104:107], v[152:155], v[206:209], v[104:107]
	v_mfma_f32_16x16x32_bf16 v[108:111], v[170:173], v[206:209], v[108:111]
	v_mfma_f32_16x16x32_bf16 v[88:91], v[152:155], v[214:217], v[88:91]
	v_mfma_f32_16x16x32_bf16 v[92:95], v[170:173], v[214:217], v[92:95]
	v_mfma_f32_16x16x32_bf16 v[72:75], v[152:155], v[222:225], v[72:75]
	v_mfma_f32_16x16x32_bf16 v[76:79], v[170:173], v[222:225], v[76:79]
	v_mfma_f32_16x16x32_bf16 v[120:123], v[166:169], v[202:205], v[120:123]
	v_mfma_f32_16x16x32_bf16 v[124:127], v[174:177], v[202:205], v[124:127]
	v_mfma_f32_16x16x32_bf16 v[104:107], v[166:169], v[210:213], v[104:107]
	v_mfma_f32_16x16x32_bf16 v[108:111], v[174:177], v[210:213], v[108:111]
	v_mfma_f32_16x16x32_bf16 v[88:91], v[166:169], v[218:221], v[88:91]
	v_mfma_f32_16x16x32_bf16 v[92:95], v[174:177], v[218:221], v[92:95]
	v_mfma_f32_16x16x32_bf16 v[72:75], v[166:169], v[226:229], v[72:75]
	v_mfma_f32_16x16x32_bf16 v[76:79], v[174:177], v[226:229], v[76:79]
	v_mfma_f32_16x16x32_bf16 v[116:119], v[178:181], v[198:201], v[116:119]
	v_mfma_f32_16x16x32_bf16 v[112:115], v[190:193], v[198:201], v[112:115]
	v_mfma_f32_16x16x32_bf16 v[100:103], v[178:181], v[206:209], v[100:103]
	v_mfma_f32_16x16x32_bf16 v[96:99], v[190:193], v[206:209], v[96:99]
	v_mfma_f32_16x16x32_bf16 v[84:87], v[178:181], v[214:217], v[84:87]
	v_mfma_f32_16x16x32_bf16 v[80:83], v[190:193], v[214:217], v[80:83]
	v_mfma_f32_16x16x32_bf16 v[68:71], v[178:181], v[222:225], v[68:71]
	v_mfma_f32_16x16x32_bf16 v[64:67], v[190:193], v[222:225], v[64:67]
	v_mfma_f32_16x16x32_bf16 v[116:119], v[186:189], v[202:205], v[116:119]
	v_mfma_f32_16x16x32_bf16 v[112:115], v[194:197], v[202:205], v[112:115]
	v_mfma_f32_16x16x32_bf16 v[100:103], v[186:189], v[210:213], v[100:103]
	v_mfma_f32_16x16x32_bf16 v[96:99], v[194:197], v[210:213], v[96:99]
	v_mfma_f32_16x16x32_bf16 v[84:87], v[186:189], v[218:221], v[84:87]
	v_mfma_f32_16x16x32_bf16 v[80:83], v[194:197], v[218:221], v[80:83]
	v_mfma_f32_16x16x32_bf16 v[68:71], v[186:189], v[226:229], v[68:71]
	v_mfma_f32_16x16x32_bf16 v[64:67], v[194:197], v[226:229], v[64:67]
	s_barrier
	s_add_u32 s61, s61, 0x100
	s_addc_u32 s66, s66, 0
	s_cmp_ge_u32 s67, s59
	s_mov_b64 s[0:1], s[8:9]
	s_mov_b32 s14, s67
	s_cbranch_scc0 .LBB0_1042
	s_and_b64 vcc, exec, s[34:35]
	s_cbranch_vccz .LBB0_1045
	s_barrier

.LBB0_1176:
	v_add_u32_e32 v126, s21, v157
	ds_read_b128 v[122:125], v126
	ds_read_b128 v[136:139], v126 offset:1024
	ds_read_b128 v[140:143], v126 offset:2048
	ds_read_b128 v[192:195], v126 offset:3072
	v_add_u32_e32 v126, s33, v157
	ds_read_b128 v[196:199], v126
	ds_read_b128 v[200:203], v126 offset:1024
	ds_read_b128 v[204:207], v126 offset:2048
	ds_read_b128 v[208:211], v126 offset:3072
	s_add_u32 s12, s0, 0xfff80080
	s_addc_u32 s13, s1, -1
	s_and_b64 s[8:9], s[8:9], exec
	s_cselect_b32 s13, s5, s13
	s_cselect_b32 s12, s15, s12
	s_cselect_b32 s9, s34, s56
	s_cselect_b32 s8, s35, s52
	v_lshl_add_u64 v[126:127], s[0:1], 0, v[168:169]
	s_add_i32 m0, s96, 0xc000
	ds_read_b128 v[212:215], v177
	ds_read_b128 v[216:219], v177 offset:1024
	ds_read_b128 v[220:223], v177 offset:2048
	ds_read_b128 v[224:227], v177 offset:3072
	ds_read_b128 v[228:231], v177 offset:4096
	ds_read_b128 v[232:235], v177 offset:5120
	ds_read_b128 v[236:239], v177 offset:6144
	ds_read_b128 v[240:243], v177 offset:7168
	global_load_lds_dwordx4 v[126:127], off
	v_lshl_add_u64 v[126:127], s[0:1], 0, v[166:167]
	s_add_i32 m0, s96, 0xe000
	s_nop 0
	global_load_lds_dwordx4 v[126:127], off
	s_waitcnt vmcnt(8)
	s_waitcnt lgkmcnt(0)
	s_barrier
	s_waitcnt lgkmcnt(0)
	v_mfma_f32_16x16x32_bf16 v[112:115], v[122:125], v[212:215], v[112:115]
	v_mfma_f32_16x16x32_bf16 v[116:119], v[140:143], v[212:215], v[116:119]
	v_mfma_f32_16x16x32_bf16 v[108:111], v[122:125], v[220:223], v[108:111]
	v_mfma_f32_16x16x32_bf16 v[100:103], v[140:143], v[220:223], v[100:103]
	v_mfma_f32_16x16x32_bf16 v[92:95], v[122:125], v[228:231], v[92:95]
	v_mfma_f32_16x16x32_bf16 v[84:87], v[140:143], v[228:231], v[84:87]
	v_mfma_f32_16x16x32_bf16 v[76:79], v[122:125], v[236:239], v[76:79]
	v_mfma_f32_16x16x32_bf16 v[68:71], v[140:143], v[236:239], v[68:71]
	v_mfma_f32_16x16x32_bf16 v[112:115], v[136:139], v[216:219], v[112:115]
	v_mfma_f32_16x16x32_bf16 v[116:119], v[192:195], v[216:219], v[116:119]
	v_mfma_f32_16x16x32_bf16 v[108:111], v[136:139], v[224:227], v[108:111]
	v_mfma_f32_16x16x32_bf16 v[100:103], v[192:195], v[224:227], v[100:103]
	v_mfma_f32_16x16x32_bf16 v[92:95], v[136:139], v[232:235], v[92:95]
	v_mfma_f32_16x16x32_bf16 v[84:87], v[192:195], v[232:235], v[84:87]
	v_mfma_f32_16x16x32_bf16 v[76:79], v[136:139], v[240:243], v[76:79]
	v_mfma_f32_16x16x32_bf16 v[68:71], v[192:195], v[240:243], v[68:71]
	v_mfma_f32_16x16x32_bf16 v[104:107], v[196:199], v[212:215], v[104:107]
	v_mfma_f32_16x16x32_bf16 v[96:99], v[204:207], v[212:215], v[96:99]
	v_mfma_f32_16x16x32_bf16 v[88:91], v[196:199], v[220:223], v[88:91]
	v_mfma_f32_16x16x32_bf16 v[80:83], v[204:207], v[220:223], v[80:83]
	v_mfma_f32_16x16x32_bf16 v[72:75], v[196:199], v[228:231], v[72:75]
	v_mfma_f32_16x16x32_bf16 v[64:67], v[204:207], v[228:231], v[64:67]
	v_mfma_f32_16x16x32_bf16 v[60:63], v[196:199], v[236:239], v[60:63]
	v_mfma_f32_16x16x32_bf16 v[56:59], v[204:207], v[236:239], v[56:59]
	v_mfma_f32_16x16x32_bf16 v[104:107], v[200:203], v[216:219], v[104:107]
	v_mfma_f32_16x16x32_bf16 v[96:99], v[208:211], v[216:219], v[96:99]
	v_mfma_f32_16x16x32_bf16 v[88:91], v[200:203], v[224:227], v[88:91]
	v_mfma_f32_16x16x32_bf16 v[80:83], v[208:211], v[224:227], v[80:83]
	v_mfma_f32_16x16x32_bf16 v[72:75], v[200:203], v[232:235], v[72:75]
	v_mfma_f32_16x16x32_bf16 v[64:67], v[208:211], v[232:235], v[64:67]
	v_mfma_f32_16x16x32_bf16 v[60:63], v[200:203], v[240:243], v[60:63]
	v_mfma_f32_16x16x32_bf16 v[56:59], v[208:211], v[240:243], v[56:59]
	s_barrier
	s_add_i32 s58, s21, s74
	v_lshl_add_u64 v[244:245], s[8:9], 0, v[146:147]
	s_mov_b32 m0, s58
	ds_read_b128 v[212:215], v177 offset:16384
	ds_read_b128 v[216:219], v177 offset:17408
	ds_read_b128 v[220:223], v177 offset:18432
	ds_read_b128 v[224:227], v177 offset:19456
	ds_read_b128 v[228:231], v177 offset:20480
	ds_read_b128 v[232:235], v177 offset:21504
	ds_read_b128 v[236:239], v177 offset:22528
	ds_read_b128 v[240:243], v177 offset:23552
	global_load_lds_dwordx4 v[244:245], off
	s_add_i32 m0, s58, 0x2000
	s_add_u32 s58, s8, 0x80000
	v_lshl_add_u64 v[246:247], s[8:9], 0, v[150:151]
	s_addc_u32 s59, s9, 0
	s_add_i32 s60, s33, s74
	global_load_lds_dwordx4 v[246:247], off
	v_lshl_add_u64 v[126:127], s[58:59], 0, v[146:147]
	s_mov_b32 m0, s60
	v_lshl_add_u64 v[248:249], s[12:13], 0, v[144:145]
	global_load_lds_dwordx4 v[126:127], off
	v_lshl_add_u64 v[126:127], s[58:59], 0, v[150:151]
	s_add_i32 m0, s60, 0x2000
	v_lshl_add_u64 v[250:251], s[12:13], 0, v[148:149]
	global_load_lds_dwordx4 v[126:127], off
	s_mov_b32 m0, s96
	s_nop 0
	global_load_lds_dwordx4 v[248:249], off
	s_mov_b32 m0, s97
	s_nop 0
	global_load_lds_dwordx4 v[250:251], off
	s_waitcnt vmcnt(8)
	s_waitcnt lgkmcnt(0)
	s_barrier
	s_waitcnt lgkmcnt(0)
	v_mfma_f32_16x16x32_bf16 v[52:55], v[122:125], v[212:215], v[52:55]
	v_mfma_f32_16x16x32_bf16 v[48:51], v[140:143], v[212:215], v[48:51]
	v_mfma_f32_16x16x32_bf16 v[44:47], v[122:125], v[220:223], v[44:47]
	v_mfma_f32_16x16x32_bf16 v[36:39], v[140:143], v[220:223], v[36:39]
	v_mfma_f32_16x16x32_bf16 v[28:31], v[122:125], v[228:231], v[28:31]
	v_mfma_f32_16x16x32_bf16 v[20:23], v[140:143], v[228:231], v[20:23]
	v_mfma_f32_16x16x32_bf16 v[126:129], v[140:143], v[236:239], v[128:131]
	v_mfma_f32_16x16x32_bf16 v[52:55], v[136:139], v[216:219], v[52:55]
	v_mfma_f32_16x16x32_bf16 v[48:51], v[192:195], v[216:219], v[48:51]
	v_mfma_f32_16x16x32_bf16 v[44:47], v[136:139], v[224:227], v[44:47]
	v_mfma_f32_16x16x32_bf16 v[36:39], v[192:195], v[224:227], v[36:39]
	v_mfma_f32_16x16x32_bf16 v[28:31], v[136:139], v[232:235], v[28:31]
	v_mfma_f32_16x16x32_bf16 v[20:23], v[192:195], v[232:235], v[20:23]
	v_mfma_f32_16x16x32_bf16 v[122:125], v[122:125], v[236:239], v[132:135]
	v_mfma_f32_16x16x32_bf16 v[126:129], v[192:195], v[240:243], v[126:129]
	v_mfma_f32_16x16x32_bf16 v[122:125], v[136:139], v[240:243], v[122:125]
	v_mfma_f32_16x16x32_bf16 v[40:43], v[196:199], v[212:215], v[40:43]
	v_mfma_f32_16x16x32_bf16 v[32:35], v[204:207], v[212:215], v[32:35]
	v_mfma_f32_16x16x32_bf16 v[24:27], v[196:199], v[220:223], v[24:27]
	v_mfma_f32_16x16x32_bf16 v[16:19], v[204:207], v[220:223], v[16:19]
	v_mfma_f32_16x16x32_bf16 v[12:15], v[196:199], v[228:231], v[12:15]
	v_mfma_f32_16x16x32_bf16 v[8:11], v[204:207], v[228:231], v[8:11]
	v_mfma_f32_16x16x32_bf16 v[4:7], v[196:199], v[236:239], v[4:7]
	v_mfma_f32_16x16x32_bf16 v[0:3], v[204:207], v[236:239], v[0:3]
	v_mfma_f32_16x16x32_bf16 v[40:43], v[200:203], v[216:219], v[40:43]
	v_mfma_f32_16x16x32_bf16 v[32:35], v[208:211], v[216:219], v[32:35]
	v_mfma_f32_16x16x32_bf16 v[24:27], v[200:203], v[224:227], v[24:27]
	v_mfma_f32_16x16x32_bf16 v[16:19], v[208:211], v[224:227], v[16:19]
	v_mfma_f32_16x16x32_bf16 v[12:15], v[200:203], v[232:235], v[12:15]
	v_mfma_f32_16x16x32_bf16 v[8:11], v[208:211], v[232:235], v[8:11]
	v_mfma_f32_16x16x32_bf16 v[4:7], v[200:203], v[240:243], v[4:7]
	v_mfma_f32_16x16x32_bf16 v[0:3], v[208:211], v[240:243], v[0:3]
	s_barrier
	s_add_i32 s58, 16, 0x18000
	v_add_u32_e32 v142, s58, v157
	s_add_i32 s59, 16, 0x1c000
	ds_read_b128 v[130:133], v142
	ds_read_b128 v[134:137], v142 offset:1024
	ds_read_b128 v[138:141], v142 offset:2048
	ds_read_b128 v[192:195], v142 offset:3072
	v_add_u32_e32 v142, s59, v157
	ds_read_b128 v[196:199], v142
	ds_read_b128 v[200:203], v142 offset:1024
	ds_read_b128 v[204:207], v142 offset:2048
	ds_read_b128 v[208:211], v142 offset:3072
	s_add_u32 s12, s12, 0x80000
	s_addc_u32 s13, s13, 0
	s_mov_b32 m0, s84
	v_lshl_add_u64 v[142:143], s[12:13], 0, v[144:145]
	ds_read_b128 v[212:215], v177 offset:32768
	ds_read_b128 v[216:219], v177 offset:33792
	ds_read_b128 v[220:223], v177 offset:34816
	ds_read_b128 v[224:227], v177 offset:35840
	ds_read_b128 v[228:231], v177 offset:36864
	ds_read_b128 v[232:235], v177 offset:37888
	ds_read_b128 v[236:239], v177 offset:38912
	ds_read_b128 v[240:243], v177 offset:39936
	global_load_lds_dwordx4 v[142:143], off
	v_lshl_add_u64 v[142:143], s[12:13], 0, v[148:149]
	s_mov_b32 m0, s85
	s_nop 0
	global_load_lds_dwordx4 v[142:143], off
	s_waitcnt vmcnt(8)
	s_waitcnt lgkmcnt(0)
	s_barrier
	s_waitcnt lgkmcnt(0)
	v_mfma_f32_16x16x32_bf16 v[112:115], v[130:133], v[212:215], v[112:115]
	v_mfma_f32_16x16x32_bf16 v[116:119], v[138:141], v[212:215], v[116:119]
	v_mfma_f32_16x16x32_bf16 v[108:111], v[130:133], v[220:223], v[108:111]
	v_mfma_f32_16x16x32_bf16 v[100:103], v[138:141], v[220:223], v[100:103]
	v_mfma_f32_16x16x32_bf16 v[92:95], v[130:133], v[228:231], v[92:95]
	v_mfma_f32_16x16x32_bf16 v[84:87], v[138:141], v[228:231], v[84:87]
	v_mfma_f32_16x16x32_bf16 v[76:79], v[130:133], v[236:239], v[76:79]
	v_mfma_f32_16x16x32_bf16 v[68:71], v[138:141], v[236:239], v[68:71]
	v_mfma_f32_16x16x32_bf16 v[112:115], v[134:137], v[216:219], v[112:115]
	v_mfma_f32_16x16x32_bf16 v[116:119], v[192:195], v[216:219], v[116:119]
	v_mfma_f32_16x16x32_bf16 v[108:111], v[134:137], v[224:227], v[108:111]
	v_mfma_f32_16x16x32_bf16 v[100:103], v[192:195], v[224:227], v[100:103]
	v_mfma_f32_16x16x32_bf16 v[92:95], v[134:137], v[232:235], v[92:95]
	v_mfma_f32_16x16x32_bf16 v[84:87], v[192:195], v[232:235], v[84:87]
	v_mfma_f32_16x16x32_bf16 v[76:79], v[134:137], v[240:243], v[76:79]
	v_mfma_f32_16x16x32_bf16 v[68:71], v[192:195], v[240:243], v[68:71]
	v_mfma_f32_16x16x32_bf16 v[104:107], v[196:199], v[212:215], v[104:107]
	v_mfma_f32_16x16x32_bf16 v[96:99], v[204:207], v[212:215], v[96:99]
	v_mfma_f32_16x16x32_bf16 v[88:91], v[196:199], v[220:223], v[88:91]
	v_mfma_f32_16x16x32_bf16 v[80:83], v[204:207], v[220:223], v[80:83]
	v_mfma_f32_16x16x32_bf16 v[72:75], v[196:199], v[228:231], v[72:75]
	v_mfma_f32_16x16x32_bf16 v[64:67], v[204:207], v[228:231], v[64:67]
	v_mfma_f32_16x16x32_bf16 v[60:63], v[196:199], v[236:239], v[60:63]
	v_mfma_f32_16x16x32_bf16 v[56:59], v[204:207], v[236:239], v[56:59]
	v_mfma_f32_16x16x32_bf16 v[104:107], v[200:203], v[216:219], v[104:107]
	v_mfma_f32_16x16x32_bf16 v[96:99], v[208:211], v[216:219], v[96:99]
	v_mfma_f32_16x16x32_bf16 v[88:91], v[200:203], v[224:227], v[88:91]
	v_mfma_f32_16x16x32_bf16 v[80:83], v[208:211], v[224:227], v[80:83]
	v_mfma_f32_16x16x32_bf16 v[72:75], v[200:203], v[232:235], v[72:75]
	v_mfma_f32_16x16x32_bf16 v[64:67], v[208:211], v[232:235], v[64:67]
	v_mfma_f32_16x16x32_bf16 v[60:63], v[200:203], v[240:243], v[60:63]
	v_mfma_f32_16x16x32_bf16 v[56:59], v[208:211], v[240:243], v[56:59]
	s_barrier
	s_add_i32 s12, s58, s74
	v_lshl_add_u64 v[142:143], v[244:245], 0, s[88:89]
	s_mov_b32 m0, s12
	ds_read_b128 v[212:215], v177 offset:49152
	ds_read_b128 v[216:219], v177 offset:50176
	ds_read_b128 v[220:223], v177 offset:51200
	ds_read_b128 v[224:227], v177 offset:52224
	ds_read_b128 v[228:231], v177 offset:53248
	ds_read_b128 v[232:235], v177 offset:54272
	ds_read_b128 v[236:239], v177 offset:55296
	ds_read_b128 v[240:243], v177 offset:56320
	global_load_lds_dwordx4 v[142:143], off
	s_add_i32 m0, s12, 0x2000
	s_add_u32 s8, s8, 0x80080
	v_lshl_add_u64 v[142:143], v[246:247], 0, s[88:89]
	s_addc_u32 s9, s9, 0
	s_add_i32 s12, s59, s74
	global_load_lds_dwordx4 v[142:143], off
	v_lshl_add_u64 v[142:143], s[8:9], 0, v[146:147]
	s_mov_b32 m0, s12
	s_nop 0
	global_load_lds_dwordx4 v[142:143], off
	v_lshl_add_u64 v[142:143], s[8:9], 0, v[150:151]
	s_add_i32 m0, s12, 0x2000
	s_nop 0
	global_load_lds_dwordx4 v[142:143], off
	v_lshl_add_u64 v[142:143], v[248:249], 0, s[88:89]
	s_mov_b32 m0, s53
	s_nop 0
	global_load_lds_dwordx4 v[142:143], off
	v_lshl_add_u64 v[142:143], v[250:251], 0, s[88:89]
	s_mov_b32 m0, s54
	s_nop 0
	global_load_lds_dwordx4 v[142:143], off
	s_waitcnt vmcnt(8)
	s_waitcnt lgkmcnt(0)
	s_barrier
	s_waitcnt lgkmcnt(0)
	v_mfma_f32_16x16x32_bf16 v[52:55], v[130:133], v[212:215], v[52:55]
	v_mfma_f32_16x16x32_bf16 v[44:47], v[130:133], v[220:223], v[44:47]
	v_mfma_f32_16x16x32_bf16 v[28:31], v[130:133], v[228:231], v[28:31]
	v_mfma_f32_16x16x32_bf16 v[122:125], v[130:133], v[236:239], v[122:125]
	v_mfma_f32_16x16x32_bf16 v[52:55], v[134:137], v[216:219], v[52:55]
	v_mfma_f32_16x16x32_bf16 v[48:51], v[138:141], v[212:215], v[48:51]
	v_mfma_f32_16x16x32_bf16 v[44:47], v[134:137], v[224:227], v[44:47]
	v_mfma_f32_16x16x32_bf16 v[36:39], v[138:141], v[220:223], v[36:39]
	v_mfma_f32_16x16x32_bf16 v[28:31], v[134:137], v[232:235], v[28:31]
	v_mfma_f32_16x16x32_bf16 v[20:23], v[138:141], v[228:231], v[20:23]
	v_mfma_f32_16x16x32_bf16 v[132:135], v[134:137], v[240:243], v[122:125]
	v_mfma_f32_16x16x32_bf16 v[122:125], v[138:141], v[236:239], v[126:129]
	v_mfma_f32_16x16x32_bf16 v[48:51], v[192:195], v[216:219], v[48:51]
	v_mfma_f32_16x16x32_bf16 v[36:39], v[192:195], v[224:227], v[36:39]
	v_mfma_f32_16x16x32_bf16 v[20:23], v[192:195], v[232:235], v[20:23]
	v_mfma_f32_16x16x32_bf16 v[128:131], v[192:195], v[240:243], v[122:125]
	v_mfma_f32_16x16x32_bf16 v[40:43], v[196:199], v[212:215], v[40:43]
	v_mfma_f32_16x16x32_bf16 v[32:35], v[204:207], v[212:215], v[32:35]
	v_mfma_f32_16x16x32_bf16 v[24:27], v[196:199], v[220:223], v[24:27]
	v_mfma_f32_16x16x32_bf16 v[16:19], v[204:207], v[220:223], v[16:19]
	v_mfma_f32_16x16x32_bf16 v[12:15], v[196:199], v[228:231], v[12:15]
	v_mfma_f32_16x16x32_bf16 v[8:11], v[204:207], v[228:231], v[8:11]
	v_mfma_f32_16x16x32_bf16 v[4:7], v[196:199], v[236:239], v[4:7]
	v_mfma_f32_16x16x32_bf16 v[0:3], v[204:207], v[236:239], v[0:3]
	v_mfma_f32_16x16x32_bf16 v[40:43], v[200:203], v[216:219], v[40:43]
	v_mfma_f32_16x16x32_bf16 v[32:35], v[208:211], v[216:219], v[32:35]
	v_mfma_f32_16x16x32_bf16 v[24:27], v[200:203], v[224:227], v[24:27]
	v_mfma_f32_16x16x32_bf16 v[16:19], v[208:211], v[224:227], v[16:19]
	v_mfma_f32_16x16x32_bf16 v[12:15], v[200:203], v[232:235], v[12:15]
	v_mfma_f32_16x16x32_bf16 v[8:11], v[208:211], v[232:235], v[8:11]
	v_mfma_f32_16x16x32_bf16 v[4:7], v[200:203], v[240:243], v[4:7]
	v_mfma_f32_16x16x32_bf16 v[0:3], v[208:211], v[240:243], v[0:3]
	s_barrier
	s_add_i32 s57, s57, 2
	s_add_u32 s52, s52, 0x100
	s_addc_u32 s56, s56, 0
	s_add_u32 s0, s0, 0x100
	s_addc_u32 s1, s1, 0
	s_cmp_gt_u32 s57, 29
	s_cbranch_scc1 .LBB0_1179

.LBB0_1467:
	s_add_i32 s92, s66, 2
	s_add_u32 s8, s64, 0xfffc0080
	s_addc_u32 s9, s65, -1
	s_add_i32 s93, 16, 0x10000
	s_cmp_eq_u32 s89, s66
	s_cselect_b32 s67, s51, s9
	s_cselect_b32 s66, s57, s8
	s_cselect_b32 s9, s87, s91
	s_cselect_b32 s8, s88, s90
	s_add_i32 s96, 16, 0x14000
	v_add_u32_e32 v140, s93, v184
	v_add_u32_e32 v187, s96, v184
	ds_read_b128 v[128:131], v140
	ds_read_b128 v[132:135], v140 offset:1024
	ds_read_b128 v[136:139], v140 offset:2048
	ds_read_b128 v[140:143], v140 offset:3072
	ds_read_b128 v[174:177], v187
	ds_read_b128 v[178:181], v187 offset:1024
	ds_read_b128 v[188:191], v187 offset:2048
	ds_read_b128 v[192:195], v187 offset:3072
	v_lshl_add_u64 v[228:229], s[64:65], 0, v[172:173]
	s_add_i32 m0, s74, 0xc000
	ds_read_b128 v[196:199], v153
	ds_read_b128 v[200:203], v153 offset:1024
	ds_read_b128 v[204:207], v153 offset:2048
	ds_read_b128 v[208:211], v153 offset:3072
	ds_read_b128 v[212:215], v153 offset:4096
	ds_read_b128 v[216:219], v153 offset:5120
	ds_read_b128 v[220:223], v153 offset:6144
	ds_read_b128 v[224:227], v153 offset:7168
	global_load_lds_dwordx4 v[228:229], off
	v_lshl_add_u64 v[228:229], s[64:65], 0, v[170:171]
	s_add_i32 m0, s74, 0xe000
	s_nop 0
	global_load_lds_dwordx4 v[228:229], off
	s_waitcnt vmcnt(8)
	s_waitcnt lgkmcnt(0)
	s_barrier
	s_waitcnt lgkmcnt(0)
	v_mfma_f32_16x16x32_bf16 v[60:63], v[128:131], v[196:199], v[60:63]
	v_mfma_f32_16x16x32_bf16 v[56:59], v[136:139], v[196:199], v[56:59]
	v_mfma_f32_16x16x32_bf16 v[44:47], v[128:131], v[204:207], v[44:47]
	v_mfma_f32_16x16x32_bf16 v[40:43], v[136:139], v[204:207], v[40:43]
	v_mfma_f32_16x16x32_bf16 v[28:31], v[128:131], v[212:215], v[28:31]
	v_mfma_f32_16x16x32_bf16 v[24:27], v[136:139], v[212:215], v[24:27]
	v_mfma_f32_16x16x32_bf16 v[12:15], v[128:131], v[220:223], v[12:15]
	v_mfma_f32_16x16x32_bf16 v[8:11], v[136:139], v[220:223], v[8:11]
	v_mfma_f32_16x16x32_bf16 v[60:63], v[132:135], v[200:203], v[60:63]
	v_mfma_f32_16x16x32_bf16 v[56:59], v[140:143], v[200:203], v[56:59]
	v_mfma_f32_16x16x32_bf16 v[44:47], v[132:135], v[208:211], v[44:47]
	v_mfma_f32_16x16x32_bf16 v[40:43], v[140:143], v[208:211], v[40:43]
	v_mfma_f32_16x16x32_bf16 v[28:31], v[132:135], v[216:219], v[28:31]
	v_mfma_f32_16x16x32_bf16 v[24:27], v[140:143], v[216:219], v[24:27]
	v_mfma_f32_16x16x32_bf16 v[12:15], v[132:135], v[224:227], v[12:15]
	v_mfma_f32_16x16x32_bf16 v[8:11], v[140:143], v[224:227], v[8:11]
	v_mfma_f32_16x16x32_bf16 v[52:55], v[174:177], v[196:199], v[52:55]
	v_mfma_f32_16x16x32_bf16 v[48:51], v[188:191], v[196:199], v[48:51]
	v_mfma_f32_16x16x32_bf16 v[36:39], v[174:177], v[204:207], v[36:39]
	v_mfma_f32_16x16x32_bf16 v[32:35], v[188:191], v[204:207], v[32:35]
	v_mfma_f32_16x16x32_bf16 v[20:23], v[174:177], v[212:215], v[20:23]
	v_mfma_f32_16x16x32_bf16 v[16:19], v[188:191], v[212:215], v[16:19]
	v_mfma_f32_16x16x32_bf16 v[4:7], v[174:177], v[220:223], v[4:7]
	v_mfma_f32_16x16x32_bf16 v[0:3], v[188:191], v[220:223], v[0:3]
	v_mfma_f32_16x16x32_bf16 v[52:55], v[178:181], v[200:203], v[52:55]
	v_mfma_f32_16x16x32_bf16 v[48:51], v[192:195], v[200:203], v[48:51]
	v_mfma_f32_16x16x32_bf16 v[36:39], v[178:181], v[208:211], v[36:39]
	v_mfma_f32_16x16x32_bf16 v[32:35], v[192:195], v[208:211], v[32:35]
	v_mfma_f32_16x16x32_bf16 v[20:23], v[178:181], v[216:219], v[20:23]
	v_mfma_f32_16x16x32_bf16 v[16:19], v[192:195], v[216:219], v[16:19]
	v_mfma_f32_16x16x32_bf16 v[4:7], v[178:181], v[224:227], v[4:7]
	v_mfma_f32_16x16x32_bf16 v[0:3], v[192:195], v[224:227], v[0:3]
	s_barrier
	s_add_i32 s93, s93, s73
	v_lshl_add_u64 v[228:229], s[8:9], 0, v[144:145]
	s_mov_b32 m0, s93
	ds_read_b128 v[196:199], v153 offset:16384
	ds_read_b128 v[200:203], v153 offset:17408
	ds_read_b128 v[204:207], v153 offset:18432
	ds_read_b128 v[208:211], v153 offset:19456
	ds_read_b128 v[212:215], v153 offset:20480
	ds_read_b128 v[216:219], v153 offset:21504
	ds_read_b128 v[220:223], v153 offset:22528
	ds_read_b128 v[224:227], v153 offset:23552
	global_load_lds_dwordx4 v[228:229], off
	s_add_i32 m0, s93, 0x2000
	s_add_u32 s94, s8, 0x40000
	v_lshl_add_u64 v[230:231], s[8:9], 0, v[146:147]
	s_addc_u32 s95, s9, 0
	s_add_i32 s93, s96, s73
	global_load_lds_dwordx4 v[230:231], off
	v_lshl_add_u64 v[232:233], s[94:95], 0, v[144:145]
	s_mov_b32 m0, s93
	v_lshl_add_u64 v[234:235], s[66:67], 0, v[148:149]
	global_load_lds_dwordx4 v[232:233], off
	v_lshl_add_u64 v[232:233], s[94:95], 0, v[146:147]
	s_add_i32 m0, s93, 0x2000
	s_nop 0
	global_load_lds_dwordx4 v[232:233], off
	v_lshl_add_u64 v[232:233], s[66:67], 0, v[150:151]
	s_mov_b32 m0, s74
	s_nop 0
	global_load_lds_dwordx4 v[232:233], off
	s_mov_b32 m0, s75
	s_nop 0
	global_load_lds_dwordx4 v[234:235], off
	s_waitcnt vmcnt(8)
	s_waitcnt lgkmcnt(0)
	s_barrier
	s_waitcnt lgkmcnt(0)
	v_mfma_f32_16x16x32_bf16 v[124:127], v[128:131], v[196:199], v[124:127]
	v_mfma_f32_16x16x32_bf16 v[120:123], v[136:139], v[196:199], v[120:123]
	v_mfma_f32_16x16x32_bf16 v[108:111], v[128:131], v[204:207], v[108:111]
	v_mfma_f32_16x16x32_bf16 v[104:107], v[136:139], v[204:207], v[104:107]
	v_mfma_f32_16x16x32_bf16 v[92:95], v[128:131], v[212:215], v[92:95]
	v_mfma_f32_16x16x32_bf16 v[88:91], v[136:139], v[212:215], v[88:91]
	v_mfma_f32_16x16x32_bf16 v[76:79], v[128:131], v[220:223], v[76:79]
	v_mfma_f32_16x16x32_bf16 v[72:75], v[136:139], v[220:223], v[72:75]
	v_mfma_f32_16x16x32_bf16 v[124:127], v[132:135], v[200:203], v[124:127]
	v_mfma_f32_16x16x32_bf16 v[120:123], v[140:143], v[200:203], v[120:123]
	v_mfma_f32_16x16x32_bf16 v[108:111], v[132:135], v[208:211], v[108:111]
	v_mfma_f32_16x16x32_bf16 v[104:107], v[140:143], v[208:211], v[104:107]
	v_mfma_f32_16x16x32_bf16 v[92:95], v[132:135], v[216:219], v[92:95]
	v_mfma_f32_16x16x32_bf16 v[88:91], v[140:143], v[216:219], v[88:91]
	v_mfma_f32_16x16x32_bf16 v[76:79], v[132:135], v[224:227], v[76:79]
	v_mfma_f32_16x16x32_bf16 v[72:75], v[140:143], v[224:227], v[72:75]
	v_mfma_f32_16x16x32_bf16 v[116:119], v[174:177], v[196:199], v[116:119]
	v_mfma_f32_16x16x32_bf16 v[112:115], v[188:191], v[196:199], v[112:115]
	v_mfma_f32_16x16x32_bf16 v[100:103], v[174:177], v[204:207], v[100:103]
	v_mfma_f32_16x16x32_bf16 v[96:99], v[188:191], v[204:207], v[96:99]
	v_mfma_f32_16x16x32_bf16 v[84:87], v[174:177], v[212:215], v[84:87]
	v_mfma_f32_16x16x32_bf16 v[80:83], v[188:191], v[212:215], v[80:83]
	v_mfma_f32_16x16x32_bf16 v[68:71], v[174:177], v[220:223], v[68:71]
	v_mfma_f32_16x16x32_bf16 v[64:67], v[188:191], v[220:223], v[64:67]
	v_mfma_f32_16x16x32_bf16 v[116:119], v[178:181], v[200:203], v[116:119]
	v_mfma_f32_16x16x32_bf16 v[112:115], v[192:195], v[200:203], v[112:115]
	v_mfma_f32_16x16x32_bf16 v[100:103], v[178:181], v[208:211], v[100:103]
	v_mfma_f32_16x16x32_bf16 v[96:99], v[192:195], v[208:211], v[96:99]
	v_mfma_f32_16x16x32_bf16 v[84:87], v[178:181], v[216:219], v[84:87]
	v_mfma_f32_16x16x32_bf16 v[80:83], v[192:195], v[216:219], v[80:83]
	v_mfma_f32_16x16x32_bf16 v[68:71], v[178:181], v[224:227], v[68:71]
	v_mfma_f32_16x16x32_bf16 v[64:67], v[192:195], v[224:227], v[64:67]
	s_barrier
	s_add_i32 s93, 16, 0x18000
	s_add_i32 s94, 16, 0x1c000
	v_add_u32_e32 v140, s93, v184
	v_add_u32_e32 v187, s94, v184
	ds_read_b128 v[128:131], v140
	ds_read_b128 v[132:135], v140 offset:1024
	ds_read_b128 v[136:139], v140 offset:2048
	ds_read_b128 v[140:143], v140 offset:3072
	ds_read_b128 v[174:177], v187
	ds_read_b128 v[178:181], v187 offset:1024
	ds_read_b128 v[188:191], v187 offset:2048
	ds_read_b128 v[192:195], v187 offset:3072
	s_add_u32 s66, s66, 0x40000
	s_addc_u32 s67, s67, 0
	s_mov_b32 m0, s76
	v_lshl_add_u64 v[236:237], s[66:67], 0, v[150:151]
	ds_read_b128 v[196:199], v153 offset:32768
	ds_read_b128 v[200:203], v153 offset:33792
	ds_read_b128 v[204:207], v153 offset:34816
	ds_read_b128 v[208:211], v153 offset:35840
	ds_read_b128 v[212:215], v153 offset:36864
	ds_read_b128 v[216:219], v153 offset:37888
	ds_read_b128 v[220:223], v153 offset:38912
	ds_read_b128 v[224:227], v153 offset:39936
	global_load_lds_dwordx4 v[236:237], off
	v_lshl_add_u64 v[236:237], s[66:67], 0, v[148:149]
	s_mov_b32 m0, s77
	s_nop 0
	global_load_lds_dwordx4 v[236:237], off
	s_waitcnt vmcnt(8)
	s_waitcnt lgkmcnt(0)
	s_barrier
	s_waitcnt lgkmcnt(0)
	v_mfma_f32_16x16x32_bf16 v[60:63], v[128:131], v[196:199], v[60:63]
	v_mfma_f32_16x16x32_bf16 v[56:59], v[136:139], v[196:199], v[56:59]
	v_mfma_f32_16x16x32_bf16 v[44:47], v[128:131], v[204:207], v[44:47]
	v_mfma_f32_16x16x32_bf16 v[40:43], v[136:139], v[204:207], v[40:43]
	v_mfma_f32_16x16x32_bf16 v[28:31], v[128:131], v[212:215], v[28:31]
	v_mfma_f32_16x16x32_bf16 v[24:27], v[136:139], v[212:215], v[24:27]
	v_mfma_f32_16x16x32_bf16 v[12:15], v[128:131], v[220:223], v[12:15]
	v_mfma_f32_16x16x32_bf16 v[8:11], v[136:139], v[220:223], v[8:11]
	v_mfma_f32_16x16x32_bf16 v[60:63], v[132:135], v[200:203], v[60:63]
	v_mfma_f32_16x16x32_bf16 v[56:59], v[140:143], v[200:203], v[56:59]
	v_mfma_f32_16x16x32_bf16 v[44:47], v[132:135], v[208:211], v[44:47]
	v_mfma_f32_16x16x32_bf16 v[40:43], v[140:143], v[208:211], v[40:43]
	v_mfma_f32_16x16x32_bf16 v[28:31], v[132:135], v[216:219], v[28:31]
	v_mfma_f32_16x16x32_bf16 v[24:27], v[140:143], v[216:219], v[24:27]
	v_mfma_f32_16x16x32_bf16 v[12:15], v[132:135], v[224:227], v[12:15]
	v_mfma_f32_16x16x32_bf16 v[8:11], v[140:143], v[224:227], v[8:11]
	v_mfma_f32_16x16x32_bf16 v[52:55], v[174:177], v[196:199], v[52:55]
	v_mfma_f32_16x16x32_bf16 v[48:51], v[188:191], v[196:199], v[48:51]
	v_mfma_f32_16x16x32_bf16 v[36:39], v[174:177], v[204:207], v[36:39]
	v_mfma_f32_16x16x32_bf16 v[32:35], v[188:191], v[204:207], v[32:35]
	v_mfma_f32_16x16x32_bf16 v[20:23], v[174:177], v[212:215], v[20:23]
	v_mfma_f32_16x16x32_bf16 v[16:19], v[188:191], v[212:215], v[16:19]
	v_mfma_f32_16x16x32_bf16 v[4:7], v[174:177], v[220:223], v[4:7]
	v_mfma_f32_16x16x32_bf16 v[0:3], v[188:191], v[220:223], v[0:3]
	v_mfma_f32_16x16x32_bf16 v[52:55], v[178:181], v[200:203], v[52:55]
	v_mfma_f32_16x16x32_bf16 v[48:51], v[192:195], v[200:203], v[48:51]
	v_mfma_f32_16x16x32_bf16 v[36:39], v[178:181], v[208:211], v[36:39]
	v_mfma_f32_16x16x32_bf16 v[32:35], v[192:195], v[208:211], v[32:35]
	v_mfma_f32_16x16x32_bf16 v[20:23], v[178:181], v[216:219], v[20:23]
	v_mfma_f32_16x16x32_bf16 v[16:19], v[192:195], v[216:219], v[16:19]
	v_mfma_f32_16x16x32_bf16 v[4:7], v[178:181], v[224:227], v[4:7]
	v_mfma_f32_16x16x32_bf16 v[0:3], v[192:195], v[224:227], v[0:3]
	s_barrier
	s_add_i32 s66, s93, s73
	v_lshl_add_u64 v[228:229], v[228:229], 0, s[30:31]
	s_mov_b32 m0, s66
	ds_read_b128 v[196:199], v153 offset:49152
	ds_read_b128 v[200:203], v153 offset:50176
	ds_read_b128 v[204:207], v153 offset:51200
	ds_read_b128 v[208:211], v153 offset:52224
	ds_read_b128 v[212:215], v153 offset:53248
	ds_read_b128 v[216:219], v153 offset:54272
	ds_read_b128 v[220:223], v153 offset:55296
	ds_read_b128 v[224:227], v153 offset:56320
	global_load_lds_dwordx4 v[228:229], off
	s_add_i32 m0, s66, 0x2000
	s_add_u32 s8, s8, 0x40080
	v_lshl_add_u64 v[228:229], v[230:231], 0, s[30:31]
	s_addc_u32 s9, s9, 0
	s_add_i32 s66, s94, s73
	global_load_lds_dwordx4 v[228:229], off
	v_lshl_add_u64 v[228:229], s[8:9], 0, v[144:145]
	s_mov_b32 m0, s66
	s_nop 0
	global_load_lds_dwordx4 v[228:229], off
	v_lshl_add_u64 v[228:229], s[8:9], 0, v[146:147]
	s_add_i32 m0, s66, 0x2000
	s_nop 0
	global_load_lds_dwordx4 v[228:229], off
	v_lshl_add_u64 v[228:229], v[232:233], 0, s[30:31]
	s_mov_b32 m0, s78
	s_nop 0
	global_load_lds_dwordx4 v[228:229], off
	v_lshl_add_u64 v[228:229], v[234:235], 0, s[30:31]
	s_mov_b32 m0, s79
	s_nop 0
	global_load_lds_dwordx4 v[228:229], off
	s_waitcnt vmcnt(8)
	s_waitcnt lgkmcnt(0)
	s_barrier
	s_waitcnt lgkmcnt(0)
	v_mfma_f32_16x16x32_bf16 v[124:127], v[128:131], v[196:199], v[124:127]
	v_mfma_f32_16x16x32_bf16 v[120:123], v[136:139], v[196:199], v[120:123]
	v_mfma_f32_16x16x32_bf16 v[108:111], v[128:131], v[204:207], v[108:111]
	v_mfma_f32_16x16x32_bf16 v[104:107], v[136:139], v[204:207], v[104:107]
	v_mfma_f32_16x16x32_bf16 v[92:95], v[128:131], v[212:215], v[92:95]
	v_mfma_f32_16x16x32_bf16 v[88:91], v[136:139], v[212:215], v[88:91]
	v_mfma_f32_16x16x32_bf16 v[76:79], v[128:131], v[220:223], v[76:79]
	v_mfma_f32_16x16x32_bf16 v[72:75], v[136:139], v[220:223], v[72:75]
	v_mfma_f32_16x16x32_bf16 v[124:127], v[132:135], v[200:203], v[124:127]
	v_mfma_f32_16x16x32_bf16 v[120:123], v[140:143], v[200:203], v[120:123]
	v_mfma_f32_16x16x32_bf16 v[108:111], v[132:135], v[208:211], v[108:111]
	v_mfma_f32_16x16x32_bf16 v[104:107], v[140:143], v[208:211], v[104:107]
	v_mfma_f32_16x16x32_bf16 v[92:95], v[132:135], v[216:219], v[92:95]
	v_mfma_f32_16x16x32_bf16 v[88:91], v[140:143], v[216:219], v[88:91]
	v_mfma_f32_16x16x32_bf16 v[76:79], v[132:135], v[224:227], v[76:79]
	v_mfma_f32_16x16x32_bf16 v[72:75], v[140:143], v[224:227], v[72:75]
	v_mfma_f32_16x16x32_bf16 v[116:119], v[174:177], v[196:199], v[116:119]
	v_mfma_f32_16x16x32_bf16 v[112:115], v[188:191], v[196:199], v[112:115]
	v_mfma_f32_16x16x32_bf16 v[100:103], v[174:177], v[204:207], v[100:103]
	v_mfma_f32_16x16x32_bf16 v[96:99], v[188:191], v[204:207], v[96:99]
	v_mfma_f32_16x16x32_bf16 v[84:87], v[174:177], v[212:215], v[84:87]
	v_mfma_f32_16x16x32_bf16 v[80:83], v[188:191], v[212:215], v[80:83]
	v_mfma_f32_16x16x32_bf16 v[68:71], v[174:177], v[220:223], v[68:71]
	v_mfma_f32_16x16x32_bf16 v[64:67], v[188:191], v[220:223], v[64:67]
	v_mfma_f32_16x16x32_bf16 v[116:119], v[178:181], v[200:203], v[116:119]
	v_mfma_f32_16x16x32_bf16 v[112:115], v[192:195], v[200:203], v[112:115]
	v_mfma_f32_16x16x32_bf16 v[100:103], v[178:181], v[208:211], v[100:103]
	v_mfma_f32_16x16x32_bf16 v[96:99], v[192:195], v[208:211], v[96:99]
	v_mfma_f32_16x16x32_bf16 v[84:87], v[178:181], v[216:219], v[84:87]
	v_mfma_f32_16x16x32_bf16 v[80:83], v[192:195], v[216:219], v[80:83]
	v_mfma_f32_16x16x32_bf16 v[68:71], v[178:181], v[224:227], v[68:71]
	v_mfma_f32_16x16x32_bf16 v[64:67], v[192:195], v[224:227], v[64:67]
	s_barrier
	s_add_u32 s90, s90, 0x100
	s_addc_u32 s91, s91, 0
	s_add_u32 s64, s64, 0x100
	s_addc_u32 s65, s65, 0
	s_cmp_ge_u32 s92, s86
	s_mov_b32 s66, s92
	s_cbranch_scc0 .LBB0_1467
	s_and_b64 vcc, exec, s[42:43]
	s_cbranch_vccz .LBB0_1470
	s_barrier

.LBB0_1558:
	ds_read_b128 v[158:161], v137
	ds_read_b128 v[162:165], v137 offset:1024
	ds_read_b128 v[166:169], v137 offset:2048
	ds_read_b128 v[170:173], v137 offset:3072
	ds_read_b128 v[186:189], v177
	ds_read_b128 v[190:193], v177 offset:1024
	ds_read_b128 v[194:197], v177 offset:2048
	ds_read_b128 v[198:201], v177 offset:3072
	s_add_i32 s78, s8, 2
	s_add_u32 s9, s4, 0xfffc0080
	s_addc_u32 s48, s5, -1
	s_cmp_eq_u32 s43, s8
	s_cselect_b32 s8, s41, s76
	s_cselect_b32 s49, s45, s48
	s_cselect_b32 s48, s44, s9
	s_cselect_b32 s9, s39, s77
	v_lshl_add_u64 v[180:181], s[4:5], 0, v[156:157]
	s_add_i32 m0, s13, 0xc000
	ds_read_b128 v[202:205], v178
	ds_read_b128 v[206:209], v178 offset:1024
	ds_read_b128 v[210:213], v178 offset:2048
	ds_read_b128 v[214:217], v178 offset:3072
	ds_read_b128 v[218:221], v178 offset:4096
	ds_read_b128 v[222:225], v178 offset:5120
	ds_read_b128 v[226:229], v178 offset:6144
	ds_read_b128 v[230:233], v178 offset:7168
	global_load_lds_dwordx4 v[180:181], off
	v_lshl_add_u64 v[180:181], s[4:5], 0, v[154:155]
	s_add_i32 m0, s13, 0xe000
	s_nop 0
	global_load_lds_dwordx4 v[180:181], off
	s_waitcnt vmcnt(8)
	s_waitcnt lgkmcnt(0)
	s_barrier
	s_waitcnt lgkmcnt(0)
	v_mfma_f32_16x16x32_bf16 v[60:63], v[158:161], v[202:205], v[60:63]
	v_mfma_f32_16x16x32_bf16 v[56:59], v[166:169], v[202:205], v[56:59]
	v_mfma_f32_16x16x32_bf16 v[44:47], v[158:161], v[210:213], v[44:47]
	v_mfma_f32_16x16x32_bf16 v[40:43], v[166:169], v[210:213], v[40:43]
	v_mfma_f32_16x16x32_bf16 v[28:31], v[158:161], v[218:221], v[28:31]
	v_mfma_f32_16x16x32_bf16 v[24:27], v[166:169], v[218:221], v[24:27]
	v_mfma_f32_16x16x32_bf16 v[12:15], v[158:161], v[226:229], v[12:15]
	v_mfma_f32_16x16x32_bf16 v[8:11], v[166:169], v[226:229], v[8:11]
	v_mfma_f32_16x16x32_bf16 v[60:63], v[162:165], v[206:209], v[60:63]
	v_mfma_f32_16x16x32_bf16 v[56:59], v[170:173], v[206:209], v[56:59]
	v_mfma_f32_16x16x32_bf16 v[44:47], v[162:165], v[214:217], v[44:47]
	v_mfma_f32_16x16x32_bf16 v[40:43], v[170:173], v[214:217], v[40:43]
	v_mfma_f32_16x16x32_bf16 v[28:31], v[162:165], v[222:225], v[28:31]
	v_mfma_f32_16x16x32_bf16 v[24:27], v[170:173], v[222:225], v[24:27]
	v_mfma_f32_16x16x32_bf16 v[12:15], v[162:165], v[230:233], v[12:15]
	v_mfma_f32_16x16x32_bf16 v[8:11], v[170:173], v[230:233], v[8:11]
	v_mfma_f32_16x16x32_bf16 v[52:55], v[186:189], v[202:205], v[52:55]
	v_mfma_f32_16x16x32_bf16 v[48:51], v[194:197], v[202:205], v[48:51]
	v_mfma_f32_16x16x32_bf16 v[36:39], v[186:189], v[210:213], v[36:39]
	v_mfma_f32_16x16x32_bf16 v[32:35], v[194:197], v[210:213], v[32:35]
	v_mfma_f32_16x16x32_bf16 v[20:23], v[186:189], v[218:221], v[20:23]
	v_mfma_f32_16x16x32_bf16 v[16:19], v[194:197], v[218:221], v[16:19]
	v_mfma_f32_16x16x32_bf16 v[4:7], v[186:189], v[226:229], v[4:7]
	v_mfma_f32_16x16x32_bf16 v[0:3], v[194:197], v[226:229], v[0:3]
	v_mfma_f32_16x16x32_bf16 v[52:55], v[190:193], v[206:209], v[52:55]
	v_mfma_f32_16x16x32_bf16 v[48:51], v[198:201], v[206:209], v[48:51]
	v_mfma_f32_16x16x32_bf16 v[36:39], v[190:193], v[214:217], v[36:39]
	v_mfma_f32_16x16x32_bf16 v[32:35], v[198:201], v[214:217], v[32:35]
	v_mfma_f32_16x16x32_bf16 v[20:23], v[190:193], v[222:225], v[20:23]
	v_mfma_f32_16x16x32_bf16 v[16:19], v[198:201], v[222:225], v[16:19]
	v_mfma_f32_16x16x32_bf16 v[4:7], v[190:193], v[230:233], v[4:7]
	v_mfma_f32_16x16x32_bf16 v[0:3], v[198:201], v[230:233], v[0:3]
	s_barrier
	s_add_i32 s79, s62, s50
	v_lshl_add_u64 v[180:181], s[8:9], 0, v[130:131]
	s_mov_b32 m0, s79
	ds_read_b128 v[202:205], v178 offset:16384
	ds_read_b128 v[206:209], v178 offset:17408
	ds_read_b128 v[210:213], v178 offset:18432
	ds_read_b128 v[214:217], v178 offset:19456
	ds_read_b128 v[218:221], v178 offset:20480
	ds_read_b128 v[222:225], v178 offset:21504
	ds_read_b128 v[226:229], v178 offset:22528
	ds_read_b128 v[230:233], v178 offset:23552
	global_load_lds_dwordx4 v[180:181], off
	s_add_i32 m0, s79, 0x2000
	s_add_u32 s80, s8, 0x40000
	v_lshl_add_u64 v[234:235], s[8:9], 0, v[134:135]
	s_addc_u32 s81, s9, 0
	s_add_i32 s79, s63, s50
	global_load_lds_dwordx4 v[234:235], off
	v_lshl_add_u64 v[236:237], s[80:81], 0, v[130:131]
	s_mov_b32 m0, s79
	v_lshl_add_u64 v[238:239], s[48:49], 0, v[132:133]
	global_load_lds_dwordx4 v[236:237], off
	v_lshl_add_u64 v[236:237], s[80:81], 0, v[134:135]
	s_add_i32 m0, s79, 0x2000
	s_nop 0
	global_load_lds_dwordx4 v[236:237], off
	v_lshl_add_u64 v[236:237], s[48:49], 0, v[128:129]
	s_mov_b32 m0, s13
	s_nop 0
	global_load_lds_dwordx4 v[236:237], off
	s_mov_b32 m0, s51
	s_nop 0
	global_load_lds_dwordx4 v[238:239], off
	s_waitcnt vmcnt(8)
	s_waitcnt lgkmcnt(0)
	s_barrier
	s_waitcnt lgkmcnt(0)
	v_mfma_f32_16x16x32_bf16 v[124:127], v[158:161], v[202:205], v[124:127]
	v_mfma_f32_16x16x32_bf16 v[120:123], v[166:169], v[202:205], v[120:123]
	v_mfma_f32_16x16x32_bf16 v[108:111], v[158:161], v[210:213], v[108:111]
	v_mfma_f32_16x16x32_bf16 v[104:107], v[166:169], v[210:213], v[104:107]
	v_mfma_f32_16x16x32_bf16 v[92:95], v[158:161], v[218:221], v[92:95]
	v_mfma_f32_16x16x32_bf16 v[88:91], v[166:169], v[218:221], v[88:91]
	v_mfma_f32_16x16x32_bf16 v[76:79], v[158:161], v[226:229], v[76:79]
	v_mfma_f32_16x16x32_bf16 v[72:75], v[166:169], v[226:229], v[72:75]
	v_mfma_f32_16x16x32_bf16 v[124:127], v[162:165], v[206:209], v[124:127]
	v_mfma_f32_16x16x32_bf16 v[120:123], v[170:173], v[206:209], v[120:123]
	v_mfma_f32_16x16x32_bf16 v[108:111], v[162:165], v[214:217], v[108:111]
	v_mfma_f32_16x16x32_bf16 v[104:107], v[170:173], v[214:217], v[104:107]
	v_mfma_f32_16x16x32_bf16 v[92:95], v[162:165], v[222:225], v[92:95]
	v_mfma_f32_16x16x32_bf16 v[88:91], v[170:173], v[222:225], v[88:91]
	v_mfma_f32_16x16x32_bf16 v[76:79], v[162:165], v[230:233], v[76:79]
	v_mfma_f32_16x16x32_bf16 v[72:75], v[170:173], v[230:233], v[72:75]
	v_mfma_f32_16x16x32_bf16 v[116:119], v[186:189], v[202:205], v[116:119]
	v_mfma_f32_16x16x32_bf16 v[112:115], v[194:197], v[202:205], v[112:115]
	v_mfma_f32_16x16x32_bf16 v[100:103], v[186:189], v[210:213], v[100:103]
	v_mfma_f32_16x16x32_bf16 v[96:99], v[194:197], v[210:213], v[96:99]
	v_mfma_f32_16x16x32_bf16 v[84:87], v[186:189], v[218:221], v[84:87]
	v_mfma_f32_16x16x32_bf16 v[80:83], v[194:197], v[218:221], v[80:83]
	v_mfma_f32_16x16x32_bf16 v[68:71], v[186:189], v[226:229], v[68:71]
	v_mfma_f32_16x16x32_bf16 v[64:67], v[194:197], v[226:229], v[64:67]
	v_mfma_f32_16x16x32_bf16 v[116:119], v[190:193], v[206:209], v[116:119]
	v_mfma_f32_16x16x32_bf16 v[112:115], v[198:201], v[206:209], v[112:115]
	v_mfma_f32_16x16x32_bf16 v[100:103], v[190:193], v[214:217], v[100:103]
	v_mfma_f32_16x16x32_bf16 v[96:99], v[198:201], v[214:217], v[96:99]
	v_mfma_f32_16x16x32_bf16 v[84:87], v[190:193], v[222:225], v[84:87]
	v_mfma_f32_16x16x32_bf16 v[80:83], v[198:201], v[222:225], v[80:83]
	v_mfma_f32_16x16x32_bf16 v[68:71], v[190:193], v[230:233], v[68:71]
	v_mfma_f32_16x16x32_bf16 v[64:67], v[198:201], v[230:233], v[64:67]
	s_barrier
	s_add_i32 s79, 16, 0x18000
	s_add_i32 s80, 16, 0x1c000
	v_add_u32_e32 v170, s79, v175
	v_add_u32_e32 v179, s80, v175
	ds_read_b128 v[158:161], v170
	ds_read_b128 v[162:165], v170 offset:1024
	ds_read_b128 v[166:169], v170 offset:2048
	ds_read_b128 v[170:173], v170 offset:3072
	ds_read_b128 v[186:189], v179
	ds_read_b128 v[190:193], v179 offset:1024
	ds_read_b128 v[194:197], v179 offset:2048
	ds_read_b128 v[198:201], v179 offset:3072
	s_add_u32 s48, s48, 0x40000
	s_addc_u32 s49, s49, 0
	s_mov_b32 m0, s52
	v_lshl_add_u64 v[240:241], s[48:49], 0, v[128:129]
	ds_read_b128 v[202:205], v178 offset:32768
	ds_read_b128 v[206:209], v178 offset:33792
	ds_read_b128 v[210:213], v178 offset:34816
	ds_read_b128 v[214:217], v178 offset:35840
	ds_read_b128 v[218:221], v178 offset:36864
	ds_read_b128 v[222:225], v178 offset:37888
	ds_read_b128 v[226:229], v178 offset:38912
	ds_read_b128 v[230:233], v178 offset:39936
	global_load_lds_dwordx4 v[240:241], off
	v_lshl_add_u64 v[240:241], s[48:49], 0, v[132:133]
	s_mov_b32 m0, s54
	s_nop 0
	global_load_lds_dwordx4 v[240:241], off
	s_waitcnt vmcnt(8)
	s_waitcnt lgkmcnt(0)
	s_barrier
	s_waitcnt lgkmcnt(0)
	v_mfma_f32_16x16x32_bf16 v[60:63], v[158:161], v[202:205], v[60:63]
	v_mfma_f32_16x16x32_bf16 v[56:59], v[166:169], v[202:205], v[56:59]
	v_mfma_f32_16x16x32_bf16 v[44:47], v[158:161], v[210:213], v[44:47]
	v_mfma_f32_16x16x32_bf16 v[40:43], v[166:169], v[210:213], v[40:43]
	v_mfma_f32_16x16x32_bf16 v[28:31], v[158:161], v[218:221], v[28:31]
	v_mfma_f32_16x16x32_bf16 v[24:27], v[166:169], v[218:221], v[24:27]
	v_mfma_f32_16x16x32_bf16 v[12:15], v[158:161], v[226:229], v[12:15]
	v_mfma_f32_16x16x32_bf16 v[8:11], v[166:169], v[226:229], v[8:11]
	v_mfma_f32_16x16x32_bf16 v[60:63], v[162:165], v[206:209], v[60:63]
	v_mfma_f32_16x16x32_bf16 v[56:59], v[170:173], v[206:209], v[56:59]
	v_mfma_f32_16x16x32_bf16 v[44:47], v[162:165], v[214:217], v[44:47]
	v_mfma_f32_16x16x32_bf16 v[40:43], v[170:173], v[214:217], v[40:43]
	v_mfma_f32_16x16x32_bf16 v[28:31], v[162:165], v[222:225], v[28:31]
	v_mfma_f32_16x16x32_bf16 v[24:27], v[170:173], v[222:225], v[24:27]
	v_mfma_f32_16x16x32_bf16 v[12:15], v[162:165], v[230:233], v[12:15]
	v_mfma_f32_16x16x32_bf16 v[8:11], v[170:173], v[230:233], v[8:11]
	v_mfma_f32_16x16x32_bf16 v[52:55], v[186:189], v[202:205], v[52:55]
	v_mfma_f32_16x16x32_bf16 v[48:51], v[194:197], v[202:205], v[48:51]
	v_mfma_f32_16x16x32_bf16 v[36:39], v[186:189], v[210:213], v[36:39]
	v_mfma_f32_16x16x32_bf16 v[32:35], v[194:197], v[210:213], v[32:35]
	v_mfma_f32_16x16x32_bf16 v[20:23], v[186:189], v[218:221], v[20:23]
	v_mfma_f32_16x16x32_bf16 v[16:19], v[194:197], v[218:221], v[16:19]
	v_mfma_f32_16x16x32_bf16 v[4:7], v[186:189], v[226:229], v[4:7]
	v_mfma_f32_16x16x32_bf16 v[0:3], v[194:197], v[226:229], v[0:3]
	v_mfma_f32_16x16x32_bf16 v[52:55], v[190:193], v[206:209], v[52:55]
	v_mfma_f32_16x16x32_bf16 v[48:51], v[198:201], v[206:209], v[48:51]
	v_mfma_f32_16x16x32_bf16 v[36:39], v[190:193], v[214:217], v[36:39]
	v_mfma_f32_16x16x32_bf16 v[32:35], v[198:201], v[214:217], v[32:35]
	v_mfma_f32_16x16x32_bf16 v[20:23], v[190:193], v[222:225], v[20:23]
	v_mfma_f32_16x16x32_bf16 v[16:19], v[198:201], v[222:225], v[16:19]
	v_mfma_f32_16x16x32_bf16 v[4:7], v[190:193], v[230:233], v[4:7]
	v_mfma_f32_16x16x32_bf16 v[0:3], v[198:201], v[230:233], v[0:3]
	s_barrier
	s_add_i32 s48, s79, s50
	v_lshl_add_u64 v[180:181], v[180:181], 0, s[16:17]
	s_mov_b32 m0, s48
	ds_read_b128 v[202:205], v178 offset:49152
	ds_read_b128 v[206:209], v178 offset:50176
	ds_read_b128 v[210:213], v178 offset:51200
	ds_read_b128 v[214:217], v178 offset:52224
	ds_read_b128 v[218:221], v178 offset:53248
	ds_read_b128 v[222:225], v178 offset:54272
	ds_read_b128 v[226:229], v178 offset:55296
	ds_read_b128 v[230:233], v178 offset:56320
	global_load_lds_dwordx4 v[180:181], off
	s_add_i32 m0, s48, 0x2000
	s_add_u32 s8, s8, 0x40080
	v_lshl_add_u64 v[180:181], v[234:235], 0, s[16:17]
	s_addc_u32 s9, s9, 0
	s_add_i32 s48, s80, s50
	global_load_lds_dwordx4 v[180:181], off
	v_lshl_add_u64 v[180:181], s[8:9], 0, v[130:131]
	s_mov_b32 m0, s48
	s_nop 0
	global_load_lds_dwordx4 v[180:181], off
	v_lshl_add_u64 v[180:181], s[8:9], 0, v[134:135]
	s_add_i32 m0, s48, 0x2000
	s_nop 0
	global_load_lds_dwordx4 v[180:181], off
	v_lshl_add_u64 v[180:181], v[236:237], 0, s[16:17]
	s_mov_b32 m0, s55
	s_nop 0
	global_load_lds_dwordx4 v[180:181], off
	v_lshl_add_u64 v[180:181], v[238:239], 0, s[16:17]
	s_mov_b32 m0, s56
	s_nop 0
	global_load_lds_dwordx4 v[180:181], off
	s_waitcnt vmcnt(8)
	s_waitcnt lgkmcnt(0)
	s_barrier
	s_waitcnt lgkmcnt(0)
	v_mfma_f32_16x16x32_bf16 v[124:127], v[158:161], v[202:205], v[124:127]
	v_mfma_f32_16x16x32_bf16 v[120:123], v[166:169], v[202:205], v[120:123]
	v_mfma_f32_16x16x32_bf16 v[108:111], v[158:161], v[210:213], v[108:111]
	v_mfma_f32_16x16x32_bf16 v[104:107], v[166:169], v[210:213], v[104:107]
	v_mfma_f32_16x16x32_bf16 v[92:95], v[158:161], v[218:221], v[92:95]
	v_mfma_f32_16x16x32_bf16 v[88:91], v[166:169], v[218:221], v[88:91]
	v_mfma_f32_16x16x32_bf16 v[76:79], v[158:161], v[226:229], v[76:79]
	v_mfma_f32_16x16x32_bf16 v[72:75], v[166:169], v[226:229], v[72:75]
	v_mfma_f32_16x16x32_bf16 v[124:127], v[162:165], v[206:209], v[124:127]
	v_mfma_f32_16x16x32_bf16 v[120:123], v[170:173], v[206:209], v[120:123]
	v_mfma_f32_16x16x32_bf16 v[108:111], v[162:165], v[214:217], v[108:111]
	v_mfma_f32_16x16x32_bf16 v[104:107], v[170:173], v[214:217], v[104:107]
	v_mfma_f32_16x16x32_bf16 v[92:95], v[162:165], v[222:225], v[92:95]
	v_mfma_f32_16x16x32_bf16 v[88:91], v[170:173], v[222:225], v[88:91]
	v_mfma_f32_16x16x32_bf16 v[76:79], v[162:165], v[230:233], v[76:79]
	v_mfma_f32_16x16x32_bf16 v[72:75], v[170:173], v[230:233], v[72:75]
	v_mfma_f32_16x16x32_bf16 v[116:119], v[186:189], v[202:205], v[116:119]
	v_mfma_f32_16x16x32_bf16 v[112:115], v[194:197], v[202:205], v[112:115]
	v_mfma_f32_16x16x32_bf16 v[100:103], v[186:189], v[210:213], v[100:103]
	v_mfma_f32_16x16x32_bf16 v[96:99], v[194:197], v[210:213], v[96:99]
	v_mfma_f32_16x16x32_bf16 v[84:87], v[186:189], v[218:221], v[84:87]
	v_mfma_f32_16x16x32_bf16 v[80:83], v[194:197], v[218:221], v[80:83]
	v_mfma_f32_16x16x32_bf16 v[68:71], v[186:189], v[226:229], v[68:71]
	v_mfma_f32_16x16x32_bf16 v[64:67], v[194:197], v[226:229], v[64:67]
	v_mfma_f32_16x16x32_bf16 v[116:119], v[190:193], v[206:209], v[116:119]
	v_mfma_f32_16x16x32_bf16 v[112:115], v[198:201], v[206:209], v[112:115]
	v_mfma_f32_16x16x32_bf16 v[100:103], v[190:193], v[214:217], v[100:103]
	v_mfma_f32_16x16x32_bf16 v[96:99], v[198:201], v[214:217], v[96:99]
	v_mfma_f32_16x16x32_bf16 v[84:87], v[190:193], v[222:225], v[84:87]
	v_mfma_f32_16x16x32_bf16 v[80:83], v[198:201], v[222:225], v[80:83]
	v_mfma_f32_16x16x32_bf16 v[68:71], v[190:193], v[230:233], v[68:71]
	v_mfma_f32_16x16x32_bf16 v[64:67], v[198:201], v[230:233], v[64:67]
	s_barrier
	s_add_u32 s76, s76, 0x100
	s_addc_u32 s77, s77, 0
	s_add_u32 s4, s4, 0x100
	s_addc_u32 s5, s5, 0
	s_cmp_ge_u32 s78, s74
	s_mov_b32 s8, s78
	s_cbranch_scc0 .LBB0_1558
	s_and_b64 vcc, exec, s[26:27]
	s_cbranch_vccz .LBB0_1561
	s_barrier

.LBB0_1711:
	ds_read_b128 v[152:155], v139
	ds_read_b128 v[166:169], v139 offset:1024
	ds_read_b128 v[170:173], v139 offset:2048
	ds_read_b128 v[174:177], v139 offset:3072
	ds_read_b128 v[178:181], v161
	ds_read_b128 v[184:187], v161 offset:1024
	ds_read_b128 v[188:191], v161 offset:2048
	ds_read_b128 v[192:195], v161 offset:3072
	s_add_i32 s85, s50, 2
	s_add_u32 s8, s48, 0xfff80080
	s_addc_u32 s9, s49, -1
	s_cmp_eq_u32 s82, s50
	s_cselect_b32 s50, s5, s8
	s_cselect_b32 s51, s1, s9
	s_cselect_b32 s9, s39, s84
	s_cselect_b32 s8, s41, s83
	v_lshl_add_u64 v[156:157], s[48:49], 0, v[150:151]
	s_add_i32 m0, s53, 0xc000
	ds_read_b128 v[196:199], v162
	ds_read_b128 v[200:203], v162 offset:1024
	ds_read_b128 v[204:207], v162 offset:2048
	ds_read_b128 v[208:211], v162 offset:3072
	ds_read_b128 v[212:215], v162 offset:4096
	ds_read_b128 v[216:219], v162 offset:5120
	ds_read_b128 v[220:223], v162 offset:6144
	ds_read_b128 v[224:227], v162 offset:7168
	global_load_lds_dwordx4 v[156:157], off
	v_lshl_add_u64 v[156:157], s[48:49], 0, v[148:149]
	s_add_i32 m0, s53, 0xe000
	s_nop 0
	global_load_lds_dwordx4 v[156:157], off
	s_waitcnt vmcnt(8)
	s_waitcnt lgkmcnt(0)
	s_barrier
	s_waitcnt lgkmcnt(0)
	v_mfma_f32_16x16x32_bf16 v[60:63], v[152:155], v[196:199], v[60:63]
	v_mfma_f32_16x16x32_bf16 v[56:59], v[170:173], v[196:199], v[56:59]
	v_mfma_f32_16x16x32_bf16 v[52:55], v[152:155], v[204:207], v[52:55]
	v_mfma_f32_16x16x32_bf16 v[48:51], v[170:173], v[204:207], v[48:51]
	v_mfma_f32_16x16x32_bf16 v[44:47], v[152:155], v[212:215], v[44:47]
	v_mfma_f32_16x16x32_bf16 v[40:43], v[170:173], v[212:215], v[40:43]
	v_mfma_f32_16x16x32_bf16 v[28:31], v[152:155], v[220:223], v[28:31]
	v_mfma_f32_16x16x32_bf16 v[24:27], v[170:173], v[220:223], v[24:27]
	v_mfma_f32_16x16x32_bf16 v[60:63], v[166:169], v[200:203], v[60:63]
	v_mfma_f32_16x16x32_bf16 v[56:59], v[174:177], v[200:203], v[56:59]
	v_mfma_f32_16x16x32_bf16 v[52:55], v[166:169], v[208:211], v[52:55]
	v_mfma_f32_16x16x32_bf16 v[48:51], v[174:177], v[208:211], v[48:51]
	v_mfma_f32_16x16x32_bf16 v[44:47], v[166:169], v[216:219], v[44:47]
	v_mfma_f32_16x16x32_bf16 v[40:43], v[174:177], v[216:219], v[40:43]
	v_mfma_f32_16x16x32_bf16 v[28:31], v[166:169], v[224:227], v[28:31]
	v_mfma_f32_16x16x32_bf16 v[24:27], v[174:177], v[224:227], v[24:27]
	v_mfma_f32_16x16x32_bf16 v[36:39], v[178:181], v[196:199], v[36:39]
	v_mfma_f32_16x16x32_bf16 v[32:35], v[188:191], v[196:199], v[32:35]
	v_mfma_f32_16x16x32_bf16 v[20:23], v[178:181], v[204:207], v[20:23]
	v_mfma_f32_16x16x32_bf16 v[16:19], v[188:191], v[204:207], v[16:19]
	v_mfma_f32_16x16x32_bf16 v[12:15], v[178:181], v[212:215], v[12:15]
	v_mfma_f32_16x16x32_bf16 v[8:11], v[188:191], v[212:215], v[8:11]
	v_mfma_f32_16x16x32_bf16 v[4:7], v[178:181], v[220:223], v[4:7]
	v_mfma_f32_16x16x32_bf16 v[0:3], v[188:191], v[220:223], v[0:3]
	v_mfma_f32_16x16x32_bf16 v[36:39], v[184:187], v[200:203], v[36:39]
	v_mfma_f32_16x16x32_bf16 v[32:35], v[192:195], v[200:203], v[32:35]
	v_mfma_f32_16x16x32_bf16 v[20:23], v[184:187], v[208:211], v[20:23]
	v_mfma_f32_16x16x32_bf16 v[16:19], v[192:195], v[208:211], v[16:19]
	v_mfma_f32_16x16x32_bf16 v[12:15], v[184:187], v[216:219], v[12:15]
	v_mfma_f32_16x16x32_bf16 v[8:11], v[192:195], v[216:219], v[8:11]
	v_mfma_f32_16x16x32_bf16 v[4:7], v[184:187], v[224:227], v[4:7]
	v_mfma_f32_16x16x32_bf16 v[0:3], v[192:195], v[224:227], v[0:3]
	s_barrier
	s_add_i32 s86, s64, s52
	v_lshl_add_u64 v[156:157], s[8:9], 0, v[130:131]
	s_mov_b32 m0, s86
	ds_read_b128 v[196:199], v162 offset:16384
	ds_read_b128 v[200:203], v162 offset:17408
	ds_read_b128 v[204:207], v162 offset:18432
	ds_read_b128 v[208:211], v162 offset:19456
	ds_read_b128 v[212:215], v162 offset:20480
	ds_read_b128 v[216:219], v162 offset:21504
	ds_read_b128 v[220:223], v162 offset:22528
	ds_read_b128 v[224:227], v162 offset:23552
	global_load_lds_dwordx4 v[156:157], off
	s_add_i32 m0, s86, 0x2000
	s_add_u32 s86, s8, 0x80000
	v_lshl_add_u64 v[228:229], s[8:9], 0, v[134:135]
	s_addc_u32 s87, s9, 0
	s_add_i32 s88, s65, s52
	global_load_lds_dwordx4 v[228:229], off
	v_lshl_add_u64 v[230:231], s[86:87], 0, v[130:131]
	s_mov_b32 m0, s88
	v_lshl_add_u64 v[232:233], s[50:51], 0, v[132:133]
	global_load_lds_dwordx4 v[230:231], off
	v_lshl_add_u64 v[230:231], s[86:87], 0, v[134:135]
	s_add_i32 m0, s88, 0x2000
	s_nop 0
	global_load_lds_dwordx4 v[230:231], off
	v_lshl_add_u64 v[230:231], s[50:51], 0, v[128:129]
	s_mov_b32 m0, s53
	s_nop 0
	global_load_lds_dwordx4 v[230:231], off
	s_mov_b32 m0, s54
	s_nop 0
	global_load_lds_dwordx4 v[232:233], off
	s_waitcnt vmcnt(8)
	s_waitcnt lgkmcnt(0)
	s_barrier
	s_waitcnt lgkmcnt(0)
	v_mfma_f32_16x16x32_bf16 v[120:123], v[152:155], v[196:199], v[120:123]
	v_mfma_f32_16x16x32_bf16 v[124:127], v[170:173], v[196:199], v[124:127]
	v_mfma_f32_16x16x32_bf16 v[104:107], v[152:155], v[204:207], v[104:107]
	v_mfma_f32_16x16x32_bf16 v[108:111], v[170:173], v[204:207], v[108:111]
	v_mfma_f32_16x16x32_bf16 v[88:91], v[152:155], v[212:215], v[88:91]
	v_mfma_f32_16x16x32_bf16 v[92:95], v[170:173], v[212:215], v[92:95]
	v_mfma_f32_16x16x32_bf16 v[72:75], v[152:155], v[220:223], v[72:75]
	v_mfma_f32_16x16x32_bf16 v[76:79], v[170:173], v[220:223], v[76:79]
	v_mfma_f32_16x16x32_bf16 v[120:123], v[166:169], v[200:203], v[120:123]
	v_mfma_f32_16x16x32_bf16 v[124:127], v[174:177], v[200:203], v[124:127]
	v_mfma_f32_16x16x32_bf16 v[104:107], v[166:169], v[208:211], v[104:107]
	v_mfma_f32_16x16x32_bf16 v[108:111], v[174:177], v[208:211], v[108:111]
	v_mfma_f32_16x16x32_bf16 v[88:91], v[166:169], v[216:219], v[88:91]
	v_mfma_f32_16x16x32_bf16 v[92:95], v[174:177], v[216:219], v[92:95]
	v_mfma_f32_16x16x32_bf16 v[72:75], v[166:169], v[224:227], v[72:75]
	v_mfma_f32_16x16x32_bf16 v[76:79], v[174:177], v[224:227], v[76:79]
	v_mfma_f32_16x16x32_bf16 v[116:119], v[178:181], v[196:199], v[116:119]
	v_mfma_f32_16x16x32_bf16 v[112:115], v[188:191], v[196:199], v[112:115]
	v_mfma_f32_16x16x32_bf16 v[100:103], v[178:181], v[204:207], v[100:103]
	v_mfma_f32_16x16x32_bf16 v[96:99], v[188:191], v[204:207], v[96:99]
	v_mfma_f32_16x16x32_bf16 v[84:87], v[178:181], v[212:215], v[84:87]
	v_mfma_f32_16x16x32_bf16 v[80:83], v[188:191], v[212:215], v[80:83]
	v_mfma_f32_16x16x32_bf16 v[68:71], v[178:181], v[220:223], v[68:71]
	v_mfma_f32_16x16x32_bf16 v[64:67], v[188:191], v[220:223], v[64:67]
	v_mfma_f32_16x16x32_bf16 v[116:119], v[184:187], v[200:203], v[116:119]
	v_mfma_f32_16x16x32_bf16 v[112:115], v[192:195], v[200:203], v[112:115]
	v_mfma_f32_16x16x32_bf16 v[100:103], v[184:187], v[208:211], v[100:103]
	v_mfma_f32_16x16x32_bf16 v[96:99], v[192:195], v[208:211], v[96:99]
	v_mfma_f32_16x16x32_bf16 v[84:87], v[184:187], v[216:219], v[84:87]
	v_mfma_f32_16x16x32_bf16 v[80:83], v[192:195], v[216:219], v[80:83]
	v_mfma_f32_16x16x32_bf16 v[68:71], v[184:187], v[224:227], v[68:71]
	v_mfma_f32_16x16x32_bf16 v[64:67], v[192:195], v[224:227], v[64:67]
	s_barrier
	s_add_i32 s86, 16, 0x18000
	v_add_u32_e32 v136, s86, v159
	s_add_i32 s87, 16, 0x1c000
	ds_read_b128 v[152:155], v136
	ds_read_b128 v[166:169], v136 offset:1024
	ds_read_b128 v[170:173], v136 offset:2048
	ds_read_b128 v[174:177], v136 offset:3072
	v_add_u32_e32 v136, s87, v159
	ds_read_b128 v[178:181], v136
	ds_read_b128 v[184:187], v136 offset:1024
	ds_read_b128 v[188:191], v136 offset:2048
	ds_read_b128 v[192:195], v136 offset:3072
	s_add_u32 s50, s50, 0x80000
	s_addc_u32 s51, s51, 0
	s_mov_b32 m0, s55
	v_lshl_add_u64 v[234:235], s[50:51], 0, v[128:129]
	ds_read_b128 v[196:199], v162 offset:32768
	ds_read_b128 v[200:203], v162 offset:33792
	ds_read_b128 v[204:207], v162 offset:34816
	ds_read_b128 v[208:211], v162 offset:35840
	ds_read_b128 v[212:215], v162 offset:36864
	ds_read_b128 v[216:219], v162 offset:37888
	ds_read_b128 v[220:223], v162 offset:38912
	ds_read_b128 v[224:227], v162 offset:39936
	global_load_lds_dwordx4 v[234:235], off
	v_lshl_add_u64 v[234:235], s[50:51], 0, v[132:133]
	s_mov_b32 m0, s56
	s_nop 0
	global_load_lds_dwordx4 v[234:235], off
	s_waitcnt vmcnt(8)
	s_waitcnt lgkmcnt(0)
	s_barrier
	s_waitcnt lgkmcnt(0)
	v_mfma_f32_16x16x32_bf16 v[60:63], v[152:155], v[196:199], v[60:63]
	v_mfma_f32_16x16x32_bf16 v[56:59], v[170:173], v[196:199], v[56:59]
	v_mfma_f32_16x16x32_bf16 v[52:55], v[152:155], v[204:207], v[52:55]
	v_mfma_f32_16x16x32_bf16 v[48:51], v[170:173], v[204:207], v[48:51]
	v_mfma_f32_16x16x32_bf16 v[44:47], v[152:155], v[212:215], v[44:47]
	v_mfma_f32_16x16x32_bf16 v[40:43], v[170:173], v[212:215], v[40:43]
	v_mfma_f32_16x16x32_bf16 v[28:31], v[152:155], v[220:223], v[28:31]
	v_mfma_f32_16x16x32_bf16 v[24:27], v[170:173], v[220:223], v[24:27]
	v_mfma_f32_16x16x32_bf16 v[60:63], v[166:169], v[200:203], v[60:63]
	v_mfma_f32_16x16x32_bf16 v[56:59], v[174:177], v[200:203], v[56:59]
	v_mfma_f32_16x16x32_bf16 v[52:55], v[166:169], v[208:211], v[52:55]
	v_mfma_f32_16x16x32_bf16 v[48:51], v[174:177], v[208:211], v[48:51]
	v_mfma_f32_16x16x32_bf16 v[44:47], v[166:169], v[216:219], v[44:47]
	v_mfma_f32_16x16x32_bf16 v[40:43], v[174:177], v[216:219], v[40:43]
	v_mfma_f32_16x16x32_bf16 v[28:31], v[166:169], v[224:227], v[28:31]
	v_mfma_f32_16x16x32_bf16 v[24:27], v[174:177], v[224:227], v[24:27]
	v_mfma_f32_16x16x32_bf16 v[36:39], v[178:181], v[196:199], v[36:39]
	v_mfma_f32_16x16x32_bf16 v[32:35], v[188:191], v[196:199], v[32:35]
	v_mfma_f32_16x16x32_bf16 v[20:23], v[178:181], v[204:207], v[20:23]
	v_mfma_f32_16x16x32_bf16 v[16:19], v[188:191], v[204:207], v[16:19]
	v_mfma_f32_16x16x32_bf16 v[12:15], v[178:181], v[212:215], v[12:15]
	v_mfma_f32_16x16x32_bf16 v[8:11], v[188:191], v[212:215], v[8:11]
	v_mfma_f32_16x16x32_bf16 v[4:7], v[178:181], v[220:223], v[4:7]
	v_mfma_f32_16x16x32_bf16 v[0:3], v[188:191], v[220:223], v[0:3]
	v_mfma_f32_16x16x32_bf16 v[36:39], v[184:187], v[200:203], v[36:39]
	v_mfma_f32_16x16x32_bf16 v[32:35], v[192:195], v[200:203], v[32:35]
	v_mfma_f32_16x16x32_bf16 v[20:23], v[184:187], v[208:211], v[20:23]
	v_mfma_f32_16x16x32_bf16 v[16:19], v[192:195], v[208:211], v[16:19]
	v_mfma_f32_16x16x32_bf16 v[12:15], v[184:187], v[216:219], v[12:15]
	v_mfma_f32_16x16x32_bf16 v[8:11], v[192:195], v[216:219], v[8:11]
	v_mfma_f32_16x16x32_bf16 v[4:7], v[184:187], v[224:227], v[4:7]
	v_mfma_f32_16x16x32_bf16 v[0:3], v[192:195], v[224:227], v[0:3]
	s_barrier
	s_add_i32 s50, s86, s52
	v_lshl_add_u64 v[156:157], v[156:157], 0, s[28:29]
	s_mov_b32 m0, s50
	ds_read_b128 v[196:199], v162 offset:49152
	ds_read_b128 v[200:203], v162 offset:50176
	ds_read_b128 v[204:207], v162 offset:51200
	ds_read_b128 v[208:211], v162 offset:52224
	ds_read_b128 v[212:215], v162 offset:53248
	ds_read_b128 v[216:219], v162 offset:54272
	ds_read_b128 v[220:223], v162 offset:55296
	ds_read_b128 v[224:227], v162 offset:56320
	global_load_lds_dwordx4 v[156:157], off
	s_add_i32 m0, s50, 0x2000
	s_add_u32 s8, s8, 0x80080
	v_lshl_add_u64 v[156:157], v[228:229], 0, s[28:29]
	s_addc_u32 s9, s9, 0
	s_add_i32 s50, s87, s52
	global_load_lds_dwordx4 v[156:157], off
	v_lshl_add_u64 v[156:157], s[8:9], 0, v[130:131]
	s_mov_b32 m0, s50
	s_nop 0
	global_load_lds_dwordx4 v[156:157], off
	v_lshl_add_u64 v[156:157], s[8:9], 0, v[134:135]
	s_add_i32 m0, s50, 0x2000
	s_nop 0
	global_load_lds_dwordx4 v[156:157], off
	v_lshl_add_u64 v[156:157], v[230:231], 0, s[28:29]
	s_mov_b32 m0, s62
	s_nop 0
	global_load_lds_dwordx4 v[156:157], off
	v_lshl_add_u64 v[156:157], v[232:233], 0, s[28:29]
	s_mov_b32 m0, s63
	s_nop 0
	global_load_lds_dwordx4 v[156:157], off
	s_waitcnt vmcnt(8)
	s_waitcnt lgkmcnt(0)
	s_barrier
	s_waitcnt lgkmcnt(0)
	v_mfma_f32_16x16x32_bf16 v[120:123], v[152:155], v[196:199], v[120:123]
	v_mfma_f32_16x16x32_bf16 v[124:127], v[170:173], v[196:199], v[124:127]
	v_mfma_f32_16x16x32_bf16 v[104:107], v[152:155], v[204:207], v[104:107]
	v_mfma_f32_16x16x32_bf16 v[108:111], v[170:173], v[204:207], v[108:111]
	v_mfma_f32_16x16x32_bf16 v[88:91], v[152:155], v[212:215], v[88:91]
	v_mfma_f32_16x16x32_bf16 v[92:95], v[170:173], v[212:215], v[92:95]
	v_mfma_f32_16x16x32_bf16 v[72:75], v[152:155], v[220:223], v[72:75]
	v_mfma_f32_16x16x32_bf16 v[76:79], v[170:173], v[220:223], v[76:79]
	v_mfma_f32_16x16x32_bf16 v[120:123], v[166:169], v[200:203], v[120:123]
	v_mfma_f32_16x16x32_bf16 v[124:127], v[174:177], v[200:203], v[124:127]
	v_mfma_f32_16x16x32_bf16 v[104:107], v[166:169], v[208:211], v[104:107]
	v_mfma_f32_16x16x32_bf16 v[108:111], v[174:177], v[208:211], v[108:111]
	v_mfma_f32_16x16x32_bf16 v[88:91], v[166:169], v[216:219], v[88:91]
	v_mfma_f32_16x16x32_bf16 v[92:95], v[174:177], v[216:219], v[92:95]
	v_mfma_f32_16x16x32_bf16 v[72:75], v[166:169], v[224:227], v[72:75]
	v_mfma_f32_16x16x32_bf16 v[76:79], v[174:177], v[224:227], v[76:79]
	v_mfma_f32_16x16x32_bf16 v[116:119], v[178:181], v[196:199], v[116:119]
	v_mfma_f32_16x16x32_bf16 v[112:115], v[188:191], v[196:199], v[112:115]
	v_mfma_f32_16x16x32_bf16 v[100:103], v[178:181], v[204:207], v[100:103]
	v_mfma_f32_16x16x32_bf16 v[96:99], v[188:191], v[204:207], v[96:99]
	v_mfma_f32_16x16x32_bf16 v[84:87], v[178:181], v[212:215], v[84:87]
	v_mfma_f32_16x16x32_bf16 v[80:83], v[188:191], v[212:215], v[80:83]
	v_mfma_f32_16x16x32_bf16 v[68:71], v[178:181], v[220:223], v[68:71]
	v_mfma_f32_16x16x32_bf16 v[64:67], v[188:191], v[220:223], v[64:67]
	v_mfma_f32_16x16x32_bf16 v[116:119], v[184:187], v[200:203], v[116:119]
	v_mfma_f32_16x16x32_bf16 v[112:115], v[192:195], v[200:203], v[112:115]
	v_mfma_f32_16x16x32_bf16 v[100:103], v[184:187], v[208:211], v[100:103]
	v_mfma_f32_16x16x32_bf16 v[96:99], v[192:195], v[208:211], v[96:99]
	v_mfma_f32_16x16x32_bf16 v[84:87], v[184:187], v[216:219], v[84:87]
	v_mfma_f32_16x16x32_bf16 v[80:83], v[192:195], v[216:219], v[80:83]
	v_mfma_f32_16x16x32_bf16 v[68:71], v[184:187], v[224:227], v[68:71]
	v_mfma_f32_16x16x32_bf16 v[64:67], v[192:195], v[224:227], v[64:67]
	s_barrier
	s_add_u32 s83, s83, 0x100
	s_addc_u32 s84, s84, 0
	s_add_u32 s48, s48, 0x100
	s_addc_u32 s49, s49, 0
	s_cmp_ge_u32 s85, s81
	s_mov_b32 s50, s85
	s_cbranch_scc0 .LBB0_1711
	s_and_b64 vcc, exec, s[30:31]
	s_cbranch_vccz .LBB0_1714
	s_barrier

.LBB0_1843:
	v_add_u32_e32 v153, s47, v147
	ds_read_b128 v[164:167], v153
	ds_read_b128 v[168:171], v153 offset:1024
	ds_read_b128 v[172:175], v153 offset:2048
	ds_read_b128 v[176:179], v153 offset:3072
	v_add_u32_e32 v153, s48, v147
	ds_read_b128 v[184:187], v153
	ds_read_b128 v[188:191], v153 offset:1024
	ds_read_b128 v[192:195], v153 offset:2048
	ds_read_b128 v[196:199], v153 offset:3072
	s_add_u32 s34, s30, 0xfff80080
	s_addc_u32 s35, s31, -1
	s_and_b64 s[8:9], s[8:9], exec
	s_cselect_b32 s35, s17, s35
	s_cselect_b32 s34, s51, s34
	s_cselect_b32 s9, s15, s54
	s_cselect_b32 s8, s52, s53
	v_lshl_add_u64 v[180:181], s[30:31], 0, v[138:139]
	s_add_i32 m0, s38, 0xc000
	ds_read_b128 v[200:203], v151
	ds_read_b128 v[204:207], v151 offset:1024
	ds_read_b128 v[208:211], v151 offset:2048
	ds_read_b128 v[212:215], v151 offset:3072
	ds_read_b128 v[216:219], v151 offset:4096
	ds_read_b128 v[220:223], v151 offset:5120
	ds_read_b128 v[224:227], v151 offset:6144
	ds_read_b128 v[228:231], v151 offset:7168
	global_load_lds_dwordx4 v[180:181], off
	v_lshl_add_u64 v[180:181], s[30:31], 0, v[136:137]
	s_add_i32 m0, s38, 0xe000
	s_nop 0
	global_load_lds_dwordx4 v[180:181], off
	s_waitcnt vmcnt(8)
	s_waitcnt lgkmcnt(0)
	s_barrier
	s_waitcnt lgkmcnt(0)
	v_mfma_f32_16x16x32_bf16 v[124:127], v[164:167], v[200:203], v[124:127]
	v_mfma_f32_16x16x32_bf16 v[120:123], v[172:175], v[200:203], v[120:123]
	v_mfma_f32_16x16x32_bf16 v[116:119], v[164:167], v[208:211], v[116:119]
	v_mfma_f32_16x16x32_bf16 v[112:115], v[172:175], v[208:211], v[112:115]
	v_mfma_f32_16x16x32_bf16 v[100:103], v[164:167], v[216:219], v[100:103]
	v_mfma_f32_16x16x32_bf16 v[96:99], v[172:175], v[216:219], v[96:99]
	v_mfma_f32_16x16x32_bf16 v[84:87], v[164:167], v[224:227], v[84:87]
	v_mfma_f32_16x16x32_bf16 v[80:83], v[172:175], v[224:227], v[80:83]
	v_mfma_f32_16x16x32_bf16 v[124:127], v[168:171], v[204:207], v[124:127]
	v_mfma_f32_16x16x32_bf16 v[120:123], v[176:179], v[204:207], v[120:123]
	v_mfma_f32_16x16x32_bf16 v[116:119], v[168:171], v[212:215], v[116:119]
	v_mfma_f32_16x16x32_bf16 v[112:115], v[176:179], v[212:215], v[112:115]
	v_mfma_f32_16x16x32_bf16 v[100:103], v[168:171], v[220:223], v[100:103]
	v_mfma_f32_16x16x32_bf16 v[96:99], v[176:179], v[220:223], v[96:99]
	v_mfma_f32_16x16x32_bf16 v[84:87], v[168:171], v[228:231], v[84:87]
	v_mfma_f32_16x16x32_bf16 v[80:83], v[176:179], v[228:231], v[80:83]
	v_mfma_f32_16x16x32_bf16 v[108:111], v[184:187], v[200:203], v[108:111]
	v_mfma_f32_16x16x32_bf16 v[104:107], v[192:195], v[200:203], v[104:107]
	v_mfma_f32_16x16x32_bf16 v[92:95], v[184:187], v[208:211], v[92:95]
	v_mfma_f32_16x16x32_bf16 v[88:91], v[192:195], v[208:211], v[88:91]
	v_mfma_f32_16x16x32_bf16 v[76:79], v[184:187], v[216:219], v[76:79]
	v_mfma_f32_16x16x32_bf16 v[72:75], v[192:195], v[216:219], v[72:75]
	v_mfma_f32_16x16x32_bf16 v[68:71], v[184:187], v[224:227], v[68:71]
	v_mfma_f32_16x16x32_bf16 v[64:67], v[192:195], v[224:227], v[64:67]
	v_mfma_f32_16x16x32_bf16 v[108:111], v[188:191], v[204:207], v[108:111]
	v_mfma_f32_16x16x32_bf16 v[104:107], v[196:199], v[204:207], v[104:107]
	v_mfma_f32_16x16x32_bf16 v[92:95], v[188:191], v[212:215], v[92:95]
	v_mfma_f32_16x16x32_bf16 v[88:91], v[196:199], v[212:215], v[88:91]
	v_mfma_f32_16x16x32_bf16 v[76:79], v[188:191], v[220:223], v[76:79]
	v_mfma_f32_16x16x32_bf16 v[72:75], v[196:199], v[220:223], v[72:75]
	v_mfma_f32_16x16x32_bf16 v[68:71], v[188:191], v[228:231], v[68:71]
	v_mfma_f32_16x16x32_bf16 v[64:67], v[196:199], v[228:231], v[64:67]
	s_barrier
	s_add_i32 s56, s47, s37
	v_lshl_add_u64 v[180:181], s[8:9], 0, v[130:131]
	s_mov_b32 m0, s56
	ds_read_b128 v[200:203], v151 offset:16384
	ds_read_b128 v[204:207], v151 offset:17408
	ds_read_b128 v[208:211], v151 offset:18432
	ds_read_b128 v[212:215], v151 offset:19456
	ds_read_b128 v[216:219], v151 offset:20480
	ds_read_b128 v[220:223], v151 offset:21504
	ds_read_b128 v[224:227], v151 offset:22528
	ds_read_b128 v[228:231], v151 offset:23552
	global_load_lds_dwordx4 v[180:181], off
	s_add_i32 m0, s56, 0x2000
	s_add_u32 s56, s8, 0x80000
	v_lshl_add_u64 v[232:233], s[8:9], 0, v[134:135]
	s_addc_u32 s57, s9, 0
	s_add_i32 s58, s48, s37
	global_load_lds_dwordx4 v[232:233], off
	v_lshl_add_u64 v[234:235], s[56:57], 0, v[130:131]
	s_mov_b32 m0, s58
	v_lshl_add_u64 v[236:237], s[34:35], 0, v[132:133]
	global_load_lds_dwordx4 v[234:235], off
	v_lshl_add_u64 v[234:235], s[56:57], 0, v[134:135]
	s_add_i32 m0, s58, 0x2000
	s_nop 0
	global_load_lds_dwordx4 v[234:235], off
	v_lshl_add_u64 v[234:235], s[34:35], 0, v[128:129]
	s_mov_b32 m0, s38
	s_nop 0
	global_load_lds_dwordx4 v[234:235], off
	s_mov_b32 m0, s39
	s_nop 0
	global_load_lds_dwordx4 v[236:237], off
	s_waitcnt vmcnt(8)
	s_waitcnt lgkmcnt(0)
	s_barrier
	s_waitcnt lgkmcnt(0)
	v_mfma_f32_16x16x32_bf16 v[60:63], v[164:167], v[200:203], v[60:63]
	v_mfma_f32_16x16x32_bf16 v[56:59], v[172:175], v[200:203], v[56:59]
	v_mfma_f32_16x16x32_bf16 v[52:55], v[164:167], v[208:211], v[52:55]
	v_mfma_f32_16x16x32_bf16 v[48:51], v[172:175], v[208:211], v[48:51]
	v_mfma_f32_16x16x32_bf16 v[36:39], v[164:167], v[216:219], v[36:39]
	v_mfma_f32_16x16x32_bf16 v[32:35], v[172:175], v[216:219], v[32:35]
	v_mfma_f32_16x16x32_bf16 v[20:23], v[164:167], v[224:227], v[20:23]
	v_mfma_f32_16x16x32_bf16 v[16:19], v[172:175], v[224:227], v[16:19]
	v_mfma_f32_16x16x32_bf16 v[60:63], v[168:171], v[204:207], v[60:63]
	v_mfma_f32_16x16x32_bf16 v[56:59], v[176:179], v[204:207], v[56:59]
	v_mfma_f32_16x16x32_bf16 v[52:55], v[168:171], v[212:215], v[52:55]
	v_mfma_f32_16x16x32_bf16 v[48:51], v[176:179], v[212:215], v[48:51]
	v_mfma_f32_16x16x32_bf16 v[36:39], v[168:171], v[220:223], v[36:39]
	v_mfma_f32_16x16x32_bf16 v[32:35], v[176:179], v[220:223], v[32:35]
	v_mfma_f32_16x16x32_bf16 v[20:23], v[168:171], v[228:231], v[20:23]
	v_mfma_f32_16x16x32_bf16 v[16:19], v[176:179], v[228:231], v[16:19]
	v_mfma_f32_16x16x32_bf16 v[44:47], v[184:187], v[200:203], v[44:47]
	v_mfma_f32_16x16x32_bf16 v[40:43], v[192:195], v[200:203], v[40:43]
	v_mfma_f32_16x16x32_bf16 v[28:31], v[184:187], v[208:211], v[28:31]
	v_mfma_f32_16x16x32_bf16 v[24:27], v[192:195], v[208:211], v[24:27]
	v_mfma_f32_16x16x32_bf16 v[12:15], v[184:187], v[216:219], v[12:15]
	v_mfma_f32_16x16x32_bf16 v[8:11], v[192:195], v[216:219], v[8:11]
	v_mfma_f32_16x16x32_bf16 v[4:7], v[184:187], v[224:227], v[4:7]
	v_mfma_f32_16x16x32_bf16 v[0:3], v[192:195], v[224:227], v[0:3]
	v_mfma_f32_16x16x32_bf16 v[44:47], v[188:191], v[204:207], v[44:47]
	v_mfma_f32_16x16x32_bf16 v[40:43], v[196:199], v[204:207], v[40:43]
	v_mfma_f32_16x16x32_bf16 v[28:31], v[188:191], v[212:215], v[28:31]
	v_mfma_f32_16x16x32_bf16 v[24:27], v[196:199], v[212:215], v[24:27]
	v_mfma_f32_16x16x32_bf16 v[12:15], v[188:191], v[220:223], v[12:15]
	v_mfma_f32_16x16x32_bf16 v[8:11], v[196:199], v[220:223], v[8:11]
	v_mfma_f32_16x16x32_bf16 v[4:7], v[188:191], v[228:231], v[4:7]
	v_mfma_f32_16x16x32_bf16 v[0:3], v[196:199], v[228:231], v[0:3]
	s_barrier
	s_add_i32 s56, 16, 0x18000
	v_add_u32_e32 v153, s56, v147
	s_add_i32 s57, 16, 0x1c000
	ds_read_b128 v[164:167], v153
	ds_read_b128 v[168:171], v153 offset:1024
	ds_read_b128 v[172:175], v153 offset:2048
	ds_read_b128 v[176:179], v153 offset:3072
	v_add_u32_e32 v153, s57, v147
	ds_read_b128 v[184:187], v153
	ds_read_b128 v[188:191], v153 offset:1024
	ds_read_b128 v[192:195], v153 offset:2048
	ds_read_b128 v[196:199], v153 offset:3072
	s_add_u32 s34, s34, 0x80000
	s_addc_u32 s35, s35, 0
	s_mov_b32 m0, s40
	v_lshl_add_u64 v[238:239], s[34:35], 0, v[128:129]
	ds_read_b128 v[200:203], v151 offset:32768
	ds_read_b128 v[204:207], v151 offset:33792
	ds_read_b128 v[208:211], v151 offset:34816
	ds_read_b128 v[212:215], v151 offset:35840
	ds_read_b128 v[216:219], v151 offset:36864
	ds_read_b128 v[220:223], v151 offset:37888
	ds_read_b128 v[224:227], v151 offset:38912
	ds_read_b128 v[228:231], v151 offset:39936
	global_load_lds_dwordx4 v[238:239], off
	v_lshl_add_u64 v[238:239], s[34:35], 0, v[132:133]
	s_mov_b32 m0, s41
	s_nop 0
	global_load_lds_dwordx4 v[238:239], off
	s_waitcnt vmcnt(8)
	s_waitcnt lgkmcnt(0)
	s_barrier
	s_waitcnt lgkmcnt(0)
	v_mfma_f32_16x16x32_bf16 v[124:127], v[164:167], v[200:203], v[124:127]
	v_mfma_f32_16x16x32_bf16 v[120:123], v[172:175], v[200:203], v[120:123]
	v_mfma_f32_16x16x32_bf16 v[116:119], v[164:167], v[208:211], v[116:119]
	v_mfma_f32_16x16x32_bf16 v[112:115], v[172:175], v[208:211], v[112:115]
	v_mfma_f32_16x16x32_bf16 v[100:103], v[164:167], v[216:219], v[100:103]
	v_mfma_f32_16x16x32_bf16 v[96:99], v[172:175], v[216:219], v[96:99]
	v_mfma_f32_16x16x32_bf16 v[84:87], v[164:167], v[224:227], v[84:87]
	v_mfma_f32_16x16x32_bf16 v[80:83], v[172:175], v[224:227], v[80:83]
	v_mfma_f32_16x16x32_bf16 v[124:127], v[168:171], v[204:207], v[124:127]
	v_mfma_f32_16x16x32_bf16 v[120:123], v[176:179], v[204:207], v[120:123]
	v_mfma_f32_16x16x32_bf16 v[116:119], v[168:171], v[212:215], v[116:119]
	v_mfma_f32_16x16x32_bf16 v[112:115], v[176:179], v[212:215], v[112:115]
	v_mfma_f32_16x16x32_bf16 v[100:103], v[168:171], v[220:223], v[100:103]
	v_mfma_f32_16x16x32_bf16 v[96:99], v[176:179], v[220:223], v[96:99]
	v_mfma_f32_16x16x32_bf16 v[84:87], v[168:171], v[228:231], v[84:87]
	v_mfma_f32_16x16x32_bf16 v[80:83], v[176:179], v[228:231], v[80:83]
	v_mfma_f32_16x16x32_bf16 v[108:111], v[184:187], v[200:203], v[108:111]
	v_mfma_f32_16x16x32_bf16 v[104:107], v[192:195], v[200:203], v[104:107]
	v_mfma_f32_16x16x32_bf16 v[92:95], v[184:187], v[208:211], v[92:95]
	v_mfma_f32_16x16x32_bf16 v[88:91], v[192:195], v[208:211], v[88:91]
	v_mfma_f32_16x16x32_bf16 v[76:79], v[184:187], v[216:219], v[76:79]
	v_mfma_f32_16x16x32_bf16 v[72:75], v[192:195], v[216:219], v[72:75]
	v_mfma_f32_16x16x32_bf16 v[68:71], v[184:187], v[224:227], v[68:71]
	v_mfma_f32_16x16x32_bf16 v[64:67], v[192:195], v[224:227], v[64:67]
	v_mfma_f32_16x16x32_bf16 v[108:111], v[188:191], v[204:207], v[108:111]
	v_mfma_f32_16x16x32_bf16 v[104:107], v[196:199], v[204:207], v[104:107]
	v_mfma_f32_16x16x32_bf16 v[92:95], v[188:191], v[212:215], v[92:95]
	v_mfma_f32_16x16x32_bf16 v[88:91], v[196:199], v[212:215], v[88:91]
	v_mfma_f32_16x16x32_bf16 v[76:79], v[188:191], v[220:223], v[76:79]
	v_mfma_f32_16x16x32_bf16 v[72:75], v[196:199], v[220:223], v[72:75]
	v_mfma_f32_16x16x32_bf16 v[68:71], v[188:191], v[228:231], v[68:71]
	v_mfma_f32_16x16x32_bf16 v[64:67], v[196:199], v[228:231], v[64:67]
	s_barrier
	s_add_i32 s34, s56, s37
	v_lshl_add_u64 v[180:181], v[180:181], 0, s[10:11]
	s_mov_b32 m0, s34
	ds_read_b128 v[200:203], v151 offset:49152
	ds_read_b128 v[204:207], v151 offset:50176
	ds_read_b128 v[208:211], v151 offset:51200
	ds_read_b128 v[212:215], v151 offset:52224
	ds_read_b128 v[216:219], v151 offset:53248
	ds_read_b128 v[220:223], v151 offset:54272
	ds_read_b128 v[224:227], v151 offset:55296
	ds_read_b128 v[228:231], v151 offset:56320
	global_load_lds_dwordx4 v[180:181], off
	s_add_i32 m0, s34, 0x2000
	s_add_u32 s8, s8, 0x80080
	v_lshl_add_u64 v[180:181], v[232:233], 0, s[10:11]
	s_addc_u32 s9, s9, 0
	s_add_i32 s34, s57, s37
	global_load_lds_dwordx4 v[180:181], off
	v_lshl_add_u64 v[180:181], s[8:9], 0, v[130:131]
	s_mov_b32 m0, s34
	s_nop 0
	global_load_lds_dwordx4 v[180:181], off
	v_lshl_add_u64 v[180:181], s[8:9], 0, v[134:135]
	s_add_i32 m0, s34, 0x2000
	s_nop 0
	global_load_lds_dwordx4 v[180:181], off
	v_lshl_add_u64 v[180:181], v[234:235], 0, s[10:11]
	s_mov_b32 m0, s43
	s_nop 0
	global_load_lds_dwordx4 v[180:181], off
	v_lshl_add_u64 v[180:181], v[236:237], 0, s[10:11]
	s_mov_b32 m0, s44
	s_nop 0
	global_load_lds_dwordx4 v[180:181], off
	s_waitcnt vmcnt(8)
	s_waitcnt lgkmcnt(0)
	s_barrier
	s_waitcnt lgkmcnt(0)
	v_mfma_f32_16x16x32_bf16 v[60:63], v[164:167], v[200:203], v[60:63]
	v_mfma_f32_16x16x32_bf16 v[56:59], v[172:175], v[200:203], v[56:59]
	v_mfma_f32_16x16x32_bf16 v[52:55], v[164:167], v[208:211], v[52:55]
	v_mfma_f32_16x16x32_bf16 v[48:51], v[172:175], v[208:211], v[48:51]
	v_mfma_f32_16x16x32_bf16 v[36:39], v[164:167], v[216:219], v[36:39]
	v_mfma_f32_16x16x32_bf16 v[32:35], v[172:175], v[216:219], v[32:35]
	v_mfma_f32_16x16x32_bf16 v[20:23], v[164:167], v[224:227], v[20:23]
	v_mfma_f32_16x16x32_bf16 v[16:19], v[172:175], v[224:227], v[16:19]
	v_mfma_f32_16x16x32_bf16 v[60:63], v[168:171], v[204:207], v[60:63]
	v_mfma_f32_16x16x32_bf16 v[56:59], v[176:179], v[204:207], v[56:59]
	v_mfma_f32_16x16x32_bf16 v[52:55], v[168:171], v[212:215], v[52:55]
	v_mfma_f32_16x16x32_bf16 v[48:51], v[176:179], v[212:215], v[48:51]
	v_mfma_f32_16x16x32_bf16 v[36:39], v[168:171], v[220:223], v[36:39]
	v_mfma_f32_16x16x32_bf16 v[32:35], v[176:179], v[220:223], v[32:35]
	v_mfma_f32_16x16x32_bf16 v[20:23], v[168:171], v[228:231], v[20:23]
	v_mfma_f32_16x16x32_bf16 v[16:19], v[176:179], v[228:231], v[16:19]
	v_mfma_f32_16x16x32_bf16 v[44:47], v[184:187], v[200:203], v[44:47]
	v_mfma_f32_16x16x32_bf16 v[40:43], v[192:195], v[200:203], v[40:43]
	v_mfma_f32_16x16x32_bf16 v[28:31], v[184:187], v[208:211], v[28:31]
	v_mfma_f32_16x16x32_bf16 v[24:27], v[192:195], v[208:211], v[24:27]
	v_mfma_f32_16x16x32_bf16 v[12:15], v[184:187], v[216:219], v[12:15]
	v_mfma_f32_16x16x32_bf16 v[8:11], v[192:195], v[216:219], v[8:11]
	v_mfma_f32_16x16x32_bf16 v[4:7], v[184:187], v[224:227], v[4:7]
	v_mfma_f32_16x16x32_bf16 v[0:3], v[192:195], v[224:227], v[0:3]
	v_mfma_f32_16x16x32_bf16 v[44:47], v[188:191], v[204:207], v[44:47]
	v_mfma_f32_16x16x32_bf16 v[40:43], v[196:199], v[204:207], v[40:43]
	v_mfma_f32_16x16x32_bf16 v[28:31], v[188:191], v[212:215], v[28:31]
	v_mfma_f32_16x16x32_bf16 v[24:27], v[196:199], v[212:215], v[24:27]
	v_mfma_f32_16x16x32_bf16 v[12:15], v[188:191], v[220:223], v[12:15]
	v_mfma_f32_16x16x32_bf16 v[8:11], v[196:199], v[220:223], v[8:11]
	v_mfma_f32_16x16x32_bf16 v[4:7], v[188:191], v[228:231], v[4:7]
	v_mfma_f32_16x16x32_bf16 v[0:3], v[196:199], v[228:231], v[0:3]
	s_barrier
	s_add_i32 s55, s55, 2
	s_add_u32 s53, s53, 0x100
	s_addc_u32 s54, s54, 0
	s_add_u32 s30, s30, 0x100
	s_addc_u32 s31, s31, 0
	s_cmp_gt_u32 s55, 29
	s_cbranch_scc1 .LBB0_1846

.LBB0_1927:
	ds_read_b128 v[150:153], v137
	ds_read_b128 v[162:165], v137 offset:1024
	ds_read_b128 v[166:169], v137 offset:2048
	ds_read_b128 v[170:173], v137 offset:3072
	ds_read_b128 v[174:177], v159
	ds_read_b128 v[178:181], v159 offset:1024
	ds_read_b128 v[184:187], v159 offset:2048
	ds_read_b128 v[188:191], v159 offset:3072
	s_add_i32 s95, s40, 2
	s_add_u32 s38, s36, 0x100
	s_addc_u32 s39, s37, 0
	s_cmp_eq_u32 s92, s40
	s_cselect_b32 s40, s34, s93
	s_cselect_b32 s43, s31, s39
	s_cselect_b32 s42, s30, s38
	s_cselect_b32 s41, s35, s94
	v_lshl_add_u64 v[154:155], s[36:37], 0, v[148:149]
	s_add_i32 m0, s46, 0xc000
	ds_read_b128 v[192:195], v160
	ds_read_b128 v[196:199], v160 offset:1024
	ds_read_b128 v[200:203], v160 offset:2048
	ds_read_b128 v[204:207], v160 offset:3072
	ds_read_b128 v[208:211], v160 offset:4096
	ds_read_b128 v[212:215], v160 offset:5120
	ds_read_b128 v[216:219], v160 offset:6144
	ds_read_b128 v[220:223], v160 offset:7168
	global_load_lds_dwordx4 v[154:155], off
	v_lshl_add_u64 v[154:155], s[36:37], 0, v[146:147]
	s_add_i32 m0, s46, 0xe000
	s_nop 0
	global_load_lds_dwordx4 v[154:155], off
	s_waitcnt vmcnt(8)
	s_waitcnt lgkmcnt(0)
	s_barrier
	s_waitcnt lgkmcnt(0)
	v_mfma_f32_16x16x32_bf16 v[76:79], v[150:153], v[192:195], v[76:79]
	v_mfma_f32_16x16x32_bf16 v[72:75], v[166:169], v[192:195], v[72:75]
	v_mfma_f32_16x16x32_bf16 v[68:71], v[150:153], v[200:203], v[68:71]
	v_mfma_f32_16x16x32_bf16 v[64:67], v[166:169], v[200:203], v[64:67]
	v_mfma_f32_16x16x32_bf16 v[56:59], v[150:153], v[208:211], v[56:59]
	v_mfma_f32_16x16x32_bf16 v[48:51], v[166:169], v[208:211], v[48:51]
	v_mfma_f32_16x16x32_bf16 v[36:39], v[150:153], v[216:219], v[36:39]
	v_mfma_f32_16x16x32_bf16 v[32:35], v[166:169], v[216:219], v[32:35]
	v_mfma_f32_16x16x32_bf16 v[76:79], v[162:165], v[196:199], v[76:79]
	v_mfma_f32_16x16x32_bf16 v[72:75], v[170:173], v[196:199], v[72:75]
	v_mfma_f32_16x16x32_bf16 v[68:71], v[162:165], v[204:207], v[68:71]
	v_mfma_f32_16x16x32_bf16 v[64:67], v[170:173], v[204:207], v[64:67]
	v_mfma_f32_16x16x32_bf16 v[56:59], v[162:165], v[212:215], v[56:59]
	v_mfma_f32_16x16x32_bf16 v[48:51], v[170:173], v[212:215], v[48:51]
	v_mfma_f32_16x16x32_bf16 v[36:39], v[162:165], v[220:223], v[36:39]
	v_mfma_f32_16x16x32_bf16 v[32:35], v[170:173], v[220:223], v[32:35]
	v_mfma_f32_16x16x32_bf16 v[44:47], v[174:177], v[192:195], v[44:47]
	v_mfma_f32_16x16x32_bf16 v[40:43], v[184:187], v[192:195], v[40:43]
	v_mfma_f32_16x16x32_bf16 v[28:31], v[174:177], v[200:203], v[28:31]
	v_mfma_f32_16x16x32_bf16 v[24:27], v[184:187], v[200:203], v[24:27]
	v_mfma_f32_16x16x32_bf16 v[20:23], v[174:177], v[208:211], v[20:23]
	v_mfma_f32_16x16x32_bf16 v[16:19], v[184:187], v[208:211], v[16:19]
	v_mfma_f32_16x16x32_bf16 v[8:11], v[174:177], v[216:219], v[8:11]
	v_mfma_f32_16x16x32_bf16 v[4:7], v[184:187], v[216:219], v[4:7]
	v_mfma_f32_16x16x32_bf16 v[44:47], v[178:181], v[196:199], v[44:47]
	v_mfma_f32_16x16x32_bf16 v[40:43], v[188:191], v[196:199], v[40:43]
	v_mfma_f32_16x16x32_bf16 v[28:31], v[178:181], v[204:207], v[28:31]
	v_mfma_f32_16x16x32_bf16 v[24:27], v[188:191], v[204:207], v[24:27]
	v_mfma_f32_16x16x32_bf16 v[20:23], v[178:181], v[212:215], v[20:23]
	v_mfma_f32_16x16x32_bf16 v[16:19], v[188:191], v[212:215], v[16:19]
	v_mfma_f32_16x16x32_bf16 v[8:11], v[178:181], v[220:223], v[8:11]
	v_mfma_f32_16x16x32_bf16 v[4:7], v[188:191], v[220:223], v[4:7]
	s_barrier
	s_add_i32 s36, s55, s45
	v_lshl_add_u64 v[154:155], s[40:41], 0, v[130:131]
	s_mov_b32 m0, s36
	ds_read_b128 v[192:195], v160 offset:16384
	ds_read_b128 v[196:199], v160 offset:17408
	ds_read_b128 v[200:203], v160 offset:18432
	ds_read_b128 v[204:207], v160 offset:19456
	ds_read_b128 v[208:211], v160 offset:20480
	ds_read_b128 v[212:215], v160 offset:21504
	ds_read_b128 v[216:219], v160 offset:22528
	ds_read_b128 v[220:223], v160 offset:23552
	global_load_lds_dwordx4 v[154:155], off
	s_add_i32 m0, s36, 0x2000
	s_add_u32 s36, s40, 0x160000
	v_lshl_add_u64 v[224:225], s[40:41], 0, v[134:135]
	s_addc_u32 s37, s41, 0
	s_add_i32 s96, s56, s45
	global_load_lds_dwordx4 v[224:225], off
	v_lshl_add_u64 v[226:227], s[36:37], 0, v[130:131]
	s_mov_b32 m0, s96
	v_lshl_add_u64 v[228:229], s[42:43], 0, v[132:133]
	global_load_lds_dwordx4 v[226:227], off
	v_lshl_add_u64 v[226:227], s[36:37], 0, v[134:135]
	s_add_i32 m0, s96, 0x2000
	s_nop 0
	global_load_lds_dwordx4 v[226:227], off
	v_lshl_add_u64 v[226:227], s[42:43], 0, v[128:129]
	s_mov_b32 m0, s46
	s_nop 0
	global_load_lds_dwordx4 v[226:227], off
	s_mov_b32 m0, s47
	s_nop 0
	global_load_lds_dwordx4 v[228:229], off
	s_waitcnt vmcnt(8)
	s_waitcnt lgkmcnt(0)
	s_barrier
	s_waitcnt lgkmcnt(0)
	v_mfma_f32_16x16x32_bf16 v[124:127], v[150:153], v[192:195], v[124:127]
	v_mfma_f32_16x16x32_bf16 v[120:123], v[166:169], v[192:195], v[120:123]
	v_mfma_f32_16x16x32_bf16 v[108:111], v[150:153], v[200:203], v[108:111]
	v_mfma_f32_16x16x32_bf16 v[104:107], v[166:169], v[200:203], v[104:107]
	v_mfma_f32_16x16x32_bf16 v[92:95], v[150:153], v[208:211], v[92:95]
	v_mfma_f32_16x16x32_bf16 v[88:91], v[166:169], v[208:211], v[88:91]
	v_mfma_f32_16x16x32_bf16 v[60:63], v[150:153], v[216:219], v[60:63]
	v_mfma_f32_16x16x32_bf16 v[52:55], v[166:169], v[216:219], v[52:55]
	v_mfma_f32_16x16x32_bf16 v[124:127], v[162:165], v[196:199], v[124:127]
	v_mfma_f32_16x16x32_bf16 v[120:123], v[170:173], v[196:199], v[120:123]
	v_mfma_f32_16x16x32_bf16 v[108:111], v[162:165], v[204:207], v[108:111]
	v_mfma_f32_16x16x32_bf16 v[104:107], v[170:173], v[204:207], v[104:107]
	v_mfma_f32_16x16x32_bf16 v[92:95], v[162:165], v[212:215], v[92:95]
	v_mfma_f32_16x16x32_bf16 v[88:91], v[170:173], v[212:215], v[88:91]
	v_mfma_f32_16x16x32_bf16 v[60:63], v[162:165], v[220:223], v[60:63]
	v_mfma_f32_16x16x32_bf16 v[52:55], v[170:173], v[220:223], v[52:55]
	v_mfma_f32_16x16x32_bf16 v[116:119], v[174:177], v[192:195], v[116:119]
	v_mfma_f32_16x16x32_bf16 v[112:115], v[184:187], v[192:195], v[112:115]
	v_mfma_f32_16x16x32_bf16 v[100:103], v[174:177], v[200:203], v[100:103]
	v_mfma_f32_16x16x32_bf16 v[96:99], v[184:187], v[200:203], v[96:99]
	v_mfma_f32_16x16x32_bf16 v[84:87], v[174:177], v[208:211], v[84:87]
	v_mfma_f32_16x16x32_bf16 v[80:83], v[184:187], v[208:211], v[80:83]
	v_mfma_f32_16x16x32_bf16 v[12:15], v[174:177], v[216:219], v[12:15]
	v_mfma_f32_16x16x32_bf16 v[0:3], v[184:187], v[216:219], v[0:3]
	v_mfma_f32_16x16x32_bf16 v[116:119], v[178:181], v[196:199], v[116:119]
	v_mfma_f32_16x16x32_bf16 v[112:115], v[188:191], v[196:199], v[112:115]
	v_mfma_f32_16x16x32_bf16 v[100:103], v[178:181], v[204:207], v[100:103]
	v_mfma_f32_16x16x32_bf16 v[96:99], v[188:191], v[204:207], v[96:99]
	v_mfma_f32_16x16x32_bf16 v[84:87], v[178:181], v[212:215], v[84:87]
	v_mfma_f32_16x16x32_bf16 v[80:83], v[188:191], v[212:215], v[80:83]
	v_mfma_f32_16x16x32_bf16 v[12:15], v[178:181], v[220:223], v[12:15]
	v_mfma_f32_16x16x32_bf16 v[0:3], v[188:191], v[220:223], v[0:3]
	s_barrier
	s_add_i32 s96, 16, 0x18000
	v_add_u32_e32 v161, s96, v157
	s_add_i32 s97, 16, 0x1c000
	ds_read_b128 v[150:153], v161
	ds_read_b128 v[162:165], v161 offset:1024
	ds_read_b128 v[166:169], v161 offset:2048
	ds_read_b128 v[170:173], v161 offset:3072
	v_add_u32_e32 v161, s97, v157
	ds_read_b128 v[174:177], v161
	ds_read_b128 v[178:181], v161 offset:1024
	ds_read_b128 v[184:187], v161 offset:2048
	ds_read_b128 v[188:191], v161 offset:3072
	s_add_u32 s36, s42, 0x160000
	s_addc_u32 s37, s43, 0
	s_mov_b32 m0, s48
	v_lshl_add_u64 v[230:231], s[36:37], 0, v[128:129]
	ds_read_b128 v[192:195], v160 offset:32768
	ds_read_b128 v[196:199], v160 offset:33792
	ds_read_b128 v[200:203], v160 offset:34816
	ds_read_b128 v[204:207], v160 offset:35840
	ds_read_b128 v[208:211], v160 offset:36864
	ds_read_b128 v[212:215], v160 offset:37888
	ds_read_b128 v[216:219], v160 offset:38912
	ds_read_b128 v[220:223], v160 offset:39936
	global_load_lds_dwordx4 v[230:231], off
	v_lshl_add_u64 v[230:231], s[36:37], 0, v[132:133]
	s_mov_b32 m0, s49
	s_nop 0
	global_load_lds_dwordx4 v[230:231], off
	s_waitcnt vmcnt(8)
	s_waitcnt lgkmcnt(0)
	s_barrier
	s_waitcnt lgkmcnt(0)
	v_mfma_f32_16x16x32_bf16 v[76:79], v[150:153], v[192:195], v[76:79]
	v_mfma_f32_16x16x32_bf16 v[72:75], v[166:169], v[192:195], v[72:75]
	v_mfma_f32_16x16x32_bf16 v[68:71], v[150:153], v[200:203], v[68:71]
	v_mfma_f32_16x16x32_bf16 v[64:67], v[166:169], v[200:203], v[64:67]
	v_mfma_f32_16x16x32_bf16 v[56:59], v[150:153], v[208:211], v[56:59]
	v_mfma_f32_16x16x32_bf16 v[48:51], v[166:169], v[208:211], v[48:51]
	v_mfma_f32_16x16x32_bf16 v[36:39], v[150:153], v[216:219], v[36:39]
	v_mfma_f32_16x16x32_bf16 v[32:35], v[166:169], v[216:219], v[32:35]
	v_mfma_f32_16x16x32_bf16 v[76:79], v[162:165], v[196:199], v[76:79]
	v_mfma_f32_16x16x32_bf16 v[72:75], v[170:173], v[196:199], v[72:75]
	v_mfma_f32_16x16x32_bf16 v[68:71], v[162:165], v[204:207], v[68:71]
	v_mfma_f32_16x16x32_bf16 v[64:67], v[170:173], v[204:207], v[64:67]
	v_mfma_f32_16x16x32_bf16 v[56:59], v[162:165], v[212:215], v[56:59]
	v_mfma_f32_16x16x32_bf16 v[48:51], v[170:173], v[212:215], v[48:51]
	v_mfma_f32_16x16x32_bf16 v[36:39], v[162:165], v[220:223], v[36:39]
	v_mfma_f32_16x16x32_bf16 v[32:35], v[170:173], v[220:223], v[32:35]
	v_mfma_f32_16x16x32_bf16 v[44:47], v[174:177], v[192:195], v[44:47]
	v_mfma_f32_16x16x32_bf16 v[40:43], v[184:187], v[192:195], v[40:43]
	v_mfma_f32_16x16x32_bf16 v[28:31], v[174:177], v[200:203], v[28:31]
	v_mfma_f32_16x16x32_bf16 v[24:27], v[184:187], v[200:203], v[24:27]
	v_mfma_f32_16x16x32_bf16 v[20:23], v[174:177], v[208:211], v[20:23]
	v_mfma_f32_16x16x32_bf16 v[16:19], v[184:187], v[208:211], v[16:19]
	v_mfma_f32_16x16x32_bf16 v[8:11], v[174:177], v[216:219], v[8:11]
	v_mfma_f32_16x16x32_bf16 v[4:7], v[184:187], v[216:219], v[4:7]
	v_mfma_f32_16x16x32_bf16 v[44:47], v[178:181], v[196:199], v[44:47]
	v_mfma_f32_16x16x32_bf16 v[40:43], v[188:191], v[196:199], v[40:43]
	v_mfma_f32_16x16x32_bf16 v[28:31], v[178:181], v[204:207], v[28:31]
	v_mfma_f32_16x16x32_bf16 v[24:27], v[188:191], v[204:207], v[24:27]
	v_mfma_f32_16x16x32_bf16 v[20:23], v[178:181], v[212:215], v[20:23]
	v_mfma_f32_16x16x32_bf16 v[16:19], v[188:191], v[212:215], v[16:19]
	v_mfma_f32_16x16x32_bf16 v[8:11], v[178:181], v[220:223], v[8:11]
	v_mfma_f32_16x16x32_bf16 v[4:7], v[188:191], v[220:223], v[4:7]
	s_barrier
	s_add_i32 s36, s96, s45
	v_lshl_add_u64 v[154:155], v[154:155], 0, s[8:9]
	s_mov_b32 m0, s36
	ds_read_b128 v[192:195], v160 offset:49152
	ds_read_b128 v[196:199], v160 offset:50176
	ds_read_b128 v[200:203], v160 offset:51200
	ds_read_b128 v[204:207], v160 offset:52224
	ds_read_b128 v[208:211], v160 offset:53248
	ds_read_b128 v[212:215], v160 offset:54272
	ds_read_b128 v[216:219], v160 offset:55296
	ds_read_b128 v[220:223], v160 offset:56320
	global_load_lds_dwordx4 v[154:155], off
	s_add_i32 m0, s36, 0x2000
	s_add_u32 s36, s40, 0x160080
	v_lshl_add_u64 v[154:155], v[224:225], 0, s[8:9]
	s_addc_u32 s37, s41, 0
	s_add_i32 s40, s97, s45
	global_load_lds_dwordx4 v[154:155], off
	v_lshl_add_u64 v[154:155], s[36:37], 0, v[130:131]
	s_mov_b32 m0, s40
	s_nop 0
	global_load_lds_dwordx4 v[154:155], off
	v_lshl_add_u64 v[154:155], s[36:37], 0, v[134:135]
	s_add_i32 m0, s40, 0x2000
	s_nop 0
	global_load_lds_dwordx4 v[154:155], off
	v_lshl_add_u64 v[154:155], v[226:227], 0, s[8:9]
	s_mov_b32 m0, s53
	s_nop 0
	global_load_lds_dwordx4 v[154:155], off
	v_lshl_add_u64 v[154:155], v[228:229], 0, s[8:9]
	s_mov_b32 m0, s54
	s_nop 0
	global_load_lds_dwordx4 v[154:155], off
	s_waitcnt vmcnt(8)
	s_waitcnt lgkmcnt(0)
	s_barrier
	s_waitcnt lgkmcnt(0)
	v_mfma_f32_16x16x32_bf16 v[124:127], v[150:153], v[192:195], v[124:127]
	v_mfma_f32_16x16x32_bf16 v[120:123], v[166:169], v[192:195], v[120:123]
	v_mfma_f32_16x16x32_bf16 v[108:111], v[150:153], v[200:203], v[108:111]
	v_mfma_f32_16x16x32_bf16 v[104:107], v[166:169], v[200:203], v[104:107]
	v_mfma_f32_16x16x32_bf16 v[92:95], v[150:153], v[208:211], v[92:95]
	v_mfma_f32_16x16x32_bf16 v[88:91], v[166:169], v[208:211], v[88:91]
	v_mfma_f32_16x16x32_bf16 v[60:63], v[150:153], v[216:219], v[60:63]
	v_mfma_f32_16x16x32_bf16 v[52:55], v[166:169], v[216:219], v[52:55]
	v_mfma_f32_16x16x32_bf16 v[124:127], v[162:165], v[196:199], v[124:127]
	v_mfma_f32_16x16x32_bf16 v[120:123], v[170:173], v[196:199], v[120:123]
	v_mfma_f32_16x16x32_bf16 v[108:111], v[162:165], v[204:207], v[108:111]
	v_mfma_f32_16x16x32_bf16 v[104:107], v[170:173], v[204:207], v[104:107]
	v_mfma_f32_16x16x32_bf16 v[92:95], v[162:165], v[212:215], v[92:95]
	v_mfma_f32_16x16x32_bf16 v[88:91], v[170:173], v[212:215], v[88:91]
	v_mfma_f32_16x16x32_bf16 v[60:63], v[162:165], v[220:223], v[60:63]
	v_mfma_f32_16x16x32_bf16 v[52:55], v[170:173], v[220:223], v[52:55]
	v_mfma_f32_16x16x32_bf16 v[116:119], v[174:177], v[192:195], v[116:119]
	v_mfma_f32_16x16x32_bf16 v[112:115], v[184:187], v[192:195], v[112:115]
	v_mfma_f32_16x16x32_bf16 v[100:103], v[174:177], v[200:203], v[100:103]
	v_mfma_f32_16x16x32_bf16 v[96:99], v[184:187], v[200:203], v[96:99]
	v_mfma_f32_16x16x32_bf16 v[84:87], v[174:177], v[208:211], v[84:87]
	v_mfma_f32_16x16x32_bf16 v[80:83], v[184:187], v[208:211], v[80:83]
	v_mfma_f32_16x16x32_bf16 v[12:15], v[174:177], v[216:219], v[12:15]
	v_mfma_f32_16x16x32_bf16 v[0:3], v[184:187], v[216:219], v[0:3]
	v_mfma_f32_16x16x32_bf16 v[116:119], v[178:181], v[196:199], v[116:119]
	v_mfma_f32_16x16x32_bf16 v[112:115], v[188:191], v[196:199], v[112:115]
	v_mfma_f32_16x16x32_bf16 v[100:103], v[178:181], v[204:207], v[100:103]
	v_mfma_f32_16x16x32_bf16 v[96:99], v[188:191], v[204:207], v[96:99]
	v_mfma_f32_16x16x32_bf16 v[84:87], v[178:181], v[212:215], v[84:87]
	v_mfma_f32_16x16x32_bf16 v[80:83], v[188:191], v[212:215], v[80:83]
	v_mfma_f32_16x16x32_bf16 v[12:15], v[178:181], v[220:223], v[12:15]
	v_mfma_f32_16x16x32_bf16 v[0:3], v[188:191], v[220:223], v[0:3]
	s_barrier
	s_add_u32 s93, s93, 0x100
	s_addc_u32 s94, s94, 0
	s_cmp_ge_u32 s95, s91
	s_mov_b64 s[36:37], s[38:39]
	s_mov_b32 s40, s95
	s_cbranch_scc0 .LBB0_1927
	s_and_b64 vcc, exec, s[10:11]
	s_cbranch_vccz .LBB0_1930
	s_barrier
